# GLA mix_c items (phases 11, 12): direction-0 gate inputs fetched for the next item at the start of the output section into dead registers; head keeps 4-byte shadow loads so counted waits keep their me
# baseline (speedup 1.0000x reference)
.LBB0_1593:
	s_waitcnt lgkmcnt(0)
	s_lshr_b32 s2, s2, 16
	s_and_b32 s2, 0xffff, s2
	s_cmp_lg_u32 s2, 0
	s_cselect_b64 s[12:13], -1, 0
	v_cndmask_b32_e64 v0, 0, 1, s[12:13]
	s_cmp_lg_u64 s[12:13], 0
	v_readfirstlane_b32 s2, v0
	s_addc_u32 s61, s22, 0
	s_lshl_b32 s12, s2, 1
	s_add_i32 s74, s89, s12
	s_lshl_b32 s12, s2, 7
	s_add_i32 s75, s88, s12
	s_lshl_b32 s12, s2, 3
	v_mov_b32_e32 v2, v1
	v_mov_b32_e32 v3, v1
	s_add_i32 s76, s83, s12
	s_lshl_b32 s12, s2, 6
	s_lshl_b32 s2, s2, 2
	v_mov_b32_e32 v0, v1
	v_mov_b64_e32 v[14:15], v[2:3]
	v_mov_b64_e32 v[18:19], v[2:3]
	s_waitcnt vmcnt(5)
	v_mov_b64_e32 v[30:31], v[2:3]
	s_waitcnt vmcnt(4)
	v_mov_b64_e32 v[34:35], v[2:3]
	s_add_i32 s77, s90, s12
	s_add_i32 s78, s91, s2
	s_mov_b32 s79, s72
	s_mov_b32 s80, s3
	s_mov_b32 s82, s97
	v_mov_b64_e32 v[12:13], v[0:1]
	v_mov_b64_e32 v[16:17], v[0:1]
	v_mov_b64_e32 v[28:29], v[0:1]
	v_mov_b64_e32 v[32:33], v[0:1]
	s_ashr_i32 s32, s82, 8
	s_lshl_b32 s32, s32, 12
	s_and_b32 s66, s82, 63
	s_lshl_b32 s66, s66, 6
	s_or_b32 s32, s32, s66
	s_bfe_u32 s66, s82, 0x20006
	s_lshl_b32 s66, s66, 7
	s_mov_b32 s100, s21
	s_mov_b32 s101, 0
	v_and_b32_e32 v230, 48, v204
	v_mov_b32_e32 v231, 0
	v_and_b32_e32 v232, 15, v204
	v_mov_b64_e32 v[234:235], s[46:47]
	v_or_b32_e32 v233, s32, v232
	v_mad_u64_u32 v[236:237], s[98:99], v233, s33, v[234:235]
	v_lshl_add_u64 v[236:237], v[236:237], 0, v[230:231]
	v_lshl_add_u64 v[236:237], v[236:237], 0, s[100:101]
	global_load_dwordx4 v[206:209], v[236:237], off offset:2048
	v_or_b32_e32 v233, 16, v232
	v_or_b32_e32 v233, s32, v233
	v_mad_u64_u32 v[236:237], s[98:99], v233, s33, v[234:235]
	v_lshl_add_u64 v[236:237], v[236:237], 0, v[230:231]
	v_lshl_add_u64 v[236:237], v[236:237], 0, s[100:101]
	global_load_dwordx4 v[210:213], v[236:237], off offset:2048
	v_or_b32_e32 v233, 32, v232
	v_or_b32_e32 v233, s32, v233
	v_mad_u64_u32 v[236:237], s[98:99], v233, s33, v[234:235]
	v_lshl_add_u64 v[236:237], v[236:237], 0, v[230:231]
	v_lshl_add_u64 v[236:237], v[236:237], 0, s[100:101]
	global_load_dwordx4 v[214:217], v[236:237], off offset:2048
	v_or_b32_e32 v233, 48, v232
	v_or_b32_e32 v233, s32, v233
	v_mad_u64_u32 v[236:237], s[98:99], v233, s33, v[234:235]
	v_lshl_add_u64 v[236:237], v[236:237], 0, v[230:231]
	v_lshl_add_u64 v[236:237], v[236:237], 0, s[100:101]
	global_load_dwordx4 v[218:221], v[236:237], off offset:2048
	v_lshrrev_b32_e32 v233, 6, v204
	v_lshlrev_b32_e32 v233, 4, v233
	v_or_b32_e32 v236, s66, v232
	v_add_u32_e32 v236, v236, v233
	v_lshlrev_b32_e32 v236, 5, v236
	v_and_b32_e32 v233, 16, v204
	v_add_u32_e32 v236, v236, v233
	v_mov_b32_e32 v237, 0
	v_lshl_add_u64 v[236:237], v[236:237], 0, s[50:51]
	v_mov_b32_e32 v222, 0
	v_mov_b32_e32 v223, 0
	v_mov_b32_e32 v224, 0
	v_mov_b32_e32 v225, 0
	v_and_b32_e32 v233, 63, v204
	v_cmp_gt_u32_e32 vcc, 32, v233
	s_and_saveexec_b64 s[70:71], vcc
	global_load_dwordx4 v[222:225], v[236:237], off
	s_or_b64 exec, exec, s[70:71]
	s_lshl_b32 s66, s66, 2
	s_add_u32 s86, s24, s66
	s_addc_u32 s87, s25, 0
	v_lshrrev_b32_e32 v233, 6, v204
	v_lshlrev_b32_e32 v236, 6, v233
	v_bfe_u32 v233, v204, 4, 2
	v_lshl_add_u32 v236, v233, 4, v236
	v_mov_b32_e32 v237, 0
	v_lshl_add_u64 v[236:237], v[236:237], 0, s[86:87]
	global_load_dwordx4 v[226:229], v[236:237], off
	s_waitcnt vmcnt(0)
	s_branch .LBB0_1596

.LBB0_1598:
	s_ashr_i32 s14, s82, 8
	s_and_b32 s67, s82, 63
	s_ashr_i32 s15, s14, 31
	s_bfe_u32 s84, s82, 0x20006
	v_mov_b32_e32 v185, v204
	s_lshl_b64 s[12:13], s[14:15], 12
	s_lshl_b32 s2, s67, 6
	s_or_b32 s12, s12, s2
	v_lshlrev_b32_e32 v0, 3, v185
	s_lshl_b32 s15, s84, 7
	s_lshl_b32 s2, s84, 8
	v_and_b32_e32 v158, 0x78, v0
	v_ashrrev_i32_e32 v168, 4, v185
	s_add_u32 s16, s46, s2
	s_addc_u32 s17, s47, 0
	v_lshlrev_b32_e32 v0, 1, v158
	v_ashrrev_i32_e32 v169, 31, v168
	v_lshl_add_u64 v[2:3], s[16:17], 0, v[0:1]
	v_lshl_add_u64 v[36:37], s[12:13], 0, v[168:169]
	v_add_u32_e32 v164, 32, v168
	v_mad_u64_u32 v[38:39], s[16:17], v36, s33, v[2:3]
	v_ashrrev_i32_e32 v165, 31, v164
	v_mad_i32_i24 v39, v37, s33, v39
	v_lshl_add_u64 v[36:37], s[12:13], 0, v[164:165]
	v_and_b32_e32 v131, 15, v185
	v_mad_u64_u32 v[2:3], s[16:17], v36, s33, v[2:3]
	v_mad_i32_i24 v3, v37, s33, v3
	v_or_b32_e32 v124, s12, v131
	v_mov_b64_e32 v[36:37], s[46:47]
	v_mad_u64_u32 v[134:135], s[16:17], v124, s33, v[36:37]
	v_or_b32_e32 v129, 16, v131
	v_mad_i32_i24 v135, s13, v174, v135
	v_and_b32_e32 v116, 48, v185
	v_mov_b32_e32 v117, v1
	v_or_b32_e32 v130, s12, v129
	global_load_dwordx4 v[96:99], v[38:39], off
	global_load_dwordx4 v[104:107], v[38:39], off offset:1024
	global_load_dwordx4 v[60:63], v[2:3], off
	global_load_dwordx4 v[100:103], v[2:3], off offset:1024
	v_lshl_add_u64 v[2:3], v[134:135], 0, v[116:117]
	v_mad_u64_u32 v[136:137], s[16:17], v130, s33, v[36:37]
	v_or_b32_e32 v177, 32, v131
	v_add_co_u32_e32 v2, vcc, s21, v2
	v_mad_i32_i24 v137, s13, v174, v137
	v_or_b32_e32 v128, s12, v177
	v_addc_co_u32_e32 v3, vcc, 0, v3, vcc
	v_lshl_add_u64 v[38:39], v[136:137], 0, v[116:117]
	v_mad_u64_u32 v[138:139], s[16:17], v128, s33, v[36:37]
	v_add_co_u32_e32 v38, vcc, s21, v38
	v_mad_i32_i24 v139, s13, v174, v139
	s_nop 0
	v_addc_co_u32_e32 v39, vcc, 0, v39, vcc
	global_load_dword v239, v[2:3], off offset:2048
	v_mov_b32_e32 v56, v206
	v_mov_b32_e32 v57, v207
	v_mov_b32_e32 v58, v208
	v_mov_b32_e32 v59, v209
	global_load_dword v239, v[38:39], off offset:2048
	v_mov_b32_e32 v52, v210
	v_mov_b32_e32 v53, v211
	v_mov_b32_e32 v54, v212
	v_mov_b32_e32 v55, v213
	v_lshl_add_u64 v[2:3], v[138:139], 0, v[116:117]
	v_add_co_u32_e32 v38, vcc, s21, v2
	v_ashrrev_i32_e32 v66, 6, v185
	s_nop 0
	v_addc_co_u32_e32 v39, vcc, 0, v3, vcc
	v_or_b32_e32 v3, 48, v131
	v_or_b32_e32 v2, s12, v3
	v_mad_u64_u32 v[140:141], s[16:17], v2, s33, v[36:37]
	v_mad_i32_i24 v141, s13, v174, v141
	v_lshl_add_u64 v[36:37], v[140:141], 0, v[116:117]
	v_add_co_u32_e32 v36, vcc, s21, v36
	v_lshlrev_b32_e32 v122, 4, v66
	s_nop 0
	v_addc_co_u32_e32 v37, vcc, 0, v37, vcc
	global_load_dword v239, v[38:39], off offset:2048
	v_mov_b32_e32 v44, v214
	v_mov_b32_e32 v45, v215
	v_mov_b32_e32 v46, v216
	v_mov_b32_e32 v47, v217
	s_nop 0
	global_load_dword v239, v[36:37], off offset:2048
	v_mov_b32_e32 v36, v218
	v_mov_b32_e32 v37, v219
	v_mov_b32_e32 v38, v220
	v_mov_b32_e32 v39, v221
	v_or_b32_e32 v40, s15, v131
	v_and_b32_e32 v133, 63, v185
	v_add_u32_e32 v48, v40, v122
	v_and_b32_e32 v40, 16, v185
	v_mov_b32_e32 v41, v1
	v_mov_b32_e32 v125, s13
	v_lshl_add_u64 v[50:51], s[50:51], 0, v[40:41]
	v_cmp_lt_u32_e32 vcc, 31, v133
	v_cmp_gt_u32_e64 s[12:13], 32, v133
	v_mov_b32_e32 v40, 0
	v_ashrrev_i32_e32 v49, 31, v48
	v_mov_b32_e32 v108, 0
	v_mov_b32_e32 v109, 0
	v_mov_b32_e32 v110, 0
	v_mov_b32_e32 v111, 0
	s_and_saveexec_b64 s[16:17], s[12:13]
	s_cbranch_execz .LBB0_1600
	v_lshlrev_b64 v[42:43], 5, v[48:49]
	v_lshl_add_u64 v[42:43], v[50:51], 0, v[42:43]
	global_load_dword v239, v[42:43], off
	v_mov_b32_e32 v108, v222
	v_mov_b32_e32 v109, v223
	v_mov_b32_e32 v110, v224
	v_mov_b32_e32 v111, v225
.LBB0_1600:
	s_or_b64 exec, exec, s[16:17]
	s_lshl_b32 s12, s15, 2
	s_add_u32 s12, s24, s12
	v_bfe_u32 v117, v185, 4, 2
	s_addc_u32 s13, s25, 0
	v_ashrrev_i32_e32 v123, 31, v122
	v_lshl_add_u64 v[42:43], v[122:123], 2, s[12:13]
	v_lshlrev_b32_e32 v64, 4, v117
	v_mov_b32_e32 v65, v1
	v_lshl_add_u64 v[64:65], v[42:43], 0, v[64:65]
	global_load_dword v239, v[64:65], off
	v_mov_b32_e32 v112, v226
	v_mov_b32_e32 v113, v227
	v_mov_b32_e32 v114, v228
	v_mov_b32_e32 v115, v229
	v_mov_b32_e32 v41, 0
	v_mov_b32_e32 v42, 0
	v_mov_b32_e32 v43, 0
	s_and_saveexec_b64 s[12:13], vcc
	s_cbranch_execz .LBB0_1602
	v_lshlrev_b64 v[40:41], 5, v[48:49]
	v_lshl_add_u64 v[40:41], v[50:51], 0, v[40:41]
	v_add_co_u32_e32 v40, vcc, 0x4000, v40
	s_nop 1
	v_addc_co_u32_e32 v41, vcc, 0, v41, vcc
	global_load_dwordx4 v[40:43], v[40:41], off
.LBB0_1602:
	s_or_b64 exec, exec, s[12:13]
	global_load_dwordx4 v[48:51], v[64:65], off offset:2048
	v_ashrrev_i32_e32 v64, 31, v185
	v_lshrrev_b32_e32 v64, 27, v64
	v_add_u32_e32 v64, v185, v64
	v_lshrrev_b32_e32 v65, 5, v64
	v_and_b32_e32 v64, 0xfffffe0, v64
	v_sub_u32_e32 v64, v185, v64
	v_mul_lo_u32 v65, v65, s35
	v_lshlrev_b32_e32 v64, 4, v64
	v_add3_u32 v64, s73, v65, v64
	s_nop 0
	ds_write_b128 v64, v[4:7]
	v_add_u32_e32 v64, 0x200, v185
	v_ashrrev_i32_e32 v65, 31, v64
	v_lshrrev_b32_e32 v65, 27, v65
	v_add_u32_e32 v65, v64, v65
	v_lshrrev_b32_e32 v67, 5, v65
	v_and_b32_e32 v65, 0xfffffe0, v65
	v_sub_u32_e32 v64, v64, v65
	v_mul_lo_u32 v65, v67, s35
	v_lshlrev_b32_e32 v64, 4, v64
	v_add3_u32 v64, s73, v65, v64
	s_nop 0
	ds_write_b128 v64, v[8:11]
	v_add_u32_e32 v64, 0x400, v185
	v_ashrrev_i32_e32 v65, 31, v64
	v_lshrrev_b32_e32 v65, 27, v65
	v_add_u32_e32 v65, v64, v65
	v_lshrrev_b32_e32 v67, 5, v65
	v_and_b32_e32 v65, 0xfffffe0, v65
	v_sub_u32_e32 v64, v64, v65
	v_mul_lo_u32 v65, v67, s35
	v_lshlrev_b32_e32 v64, 4, v64
	v_add3_u32 v64, s73, v65, v64
	s_nop 0
	ds_write_b128 v64, v[20:23]
	v_add_u32_e32 v64, 0x600, v185
	v_ashrrev_i32_e32 v65, 31, v64
	v_lshrrev_b32_e32 v65, 27, v65
	v_add_u32_e32 v65, v64, v65
	v_lshrrev_b32_e32 v67, 5, v65
	v_and_b32_e32 v65, 0xfffffe0, v65
	v_sub_u32_e32 v64, v64, v65
	s_lshl_b32 s12, s14, 3
	s_lshl_b32 s13, s84, 1
	v_mul_lo_u32 v65, v67, s35
	v_lshlrev_b32_e32 v64, 4, v64
	s_or_b32 s62, s13, s12
	v_add3_u32 v64, s73, v65, v64
	s_cmp_gt_i32 s62, 44
	s_mov_b64 s[12:13], -1
	s_nop 0
	ds_write_b128 v64, v[24:27]
	s_cbranch_scc0 .LBB0_1608
	s_cmp_gt_u32 s62, 60
	s_cbranch_scc0 .LBB0_1605
	s_sub_i32 s38, s62, 61
	s_mov_b64 s[12:13], 0
	s_mov_b64 s[14:15], s[30:31]
	s_mov_b64 s[16:17], s[38:39]

.LBB0_1610:
	v_lshlrev_b32_e32 v64, 1, v131
	v_lshlrev_b32_e32 v132, 5, v66
	v_and_b32_e32 v64, 24, v64
	v_and_b32_e32 v65, 3, v185
	s_lshl_b64 s[16:17], s[16:17], 22
	v_or3_b32 v72, v65, v64, v132
	s_add_u32 s14, s14, s16
	s_addc_u32 s15, s15, s17
	s_lshl_b32 s16, s67, 16
	v_ashrrev_i32_e32 v73, 31, v72
	v_lshlrev_b32_e32 v175, 3, v117
	v_lshlrev_b32_e32 v64, 9, v131
	v_and_b32_e32 v178, 0xffffffc0, v185
	s_add_u32 s14, s14, s16
	v_lshlrev_b64 v[118:119], 8, v[72:73]
	v_or_b32_e32 v72, 4, v72
	v_add3_u32 v148, 0, v64, v178
	v_lshlrev_b32_e32 v64, 2, v185
	s_addc_u32 s15, s15, 0
	v_lshlrev_b32_e32 v126, 1, v175
	v_mov_b32_e32 v127, v1
	v_ashrrev_i32_e32 v73, 31, v72
	v_and_b32_e32 v65, 0x1fc, v64
	v_lshl_add_u64 v[74:75], s[14:15], 0, v[126:127]
	v_lshlrev_b64 v[120:121], 8, v[72:73]
	v_add_u32_e32 v176, 0, v65
	v_add_u32_e32 v181, s92, v64
	v_add_u32_e32 v180, s92, v65
	v_lshl_add_u64 v[64:65], v[74:75], 0, v[118:119]
	v_lshl_add_u64 v[72:73], v[74:75], 0, v[120:121]
	global_load_dwordx4 v[84:87], v[64:65], off
	global_load_dwordx4 v[80:83], v[64:65], off offset:64
	global_load_dwordx4 v[68:71], v[64:65], off offset:128
	s_nop 0
	global_load_dwordx4 v[64:67], v[64:65], off offset:192
	s_nop 0
	global_load_dwordx4 v[92:95], v[72:73], off
	global_load_dwordx4 v[88:91], v[72:73], off offset:64
	global_load_dwordx4 v[76:79], v[72:73], off offset:128
	s_nop 0
	global_load_dwordx4 v[72:75], v[72:73], off offset:192
	s_nop 0
	v_mfma_f32_16x16x32_bf16 v[142:145], v[108:111], v[56:59], 0
	v_add_u32_e32 v182, v148, v116
	v_ashrrev_i32_e32 v123, 7, v185
	v_lshlrev_b32_e32 v179, 13, v123
	v_cmp_lt_i32_e64 s[12:13], 0, v123
	v_mov_b32_e32 v169, 0
	s_nop 0
	s_nop 1
	v_add_f32_e32 v127, v112, v142
	v_add_f32_e32 v143, v113, v143
	v_add_f32_e32 v147, v114, v144
	v_min_f32_e32 v142, 0, v127
	v_mul_f32_e64 v127, |v127|, s49
	v_mul_f32_e64 v146, |v143|, s49
	v_min_f32_e32 v144, 0, v147
	v_mul_f32_e64 v147, |v147|, s49
	v_add_f32_e32 v145, v115, v145
	v_exp_f32_e32 v127, v127
	v_exp_f32_e32 v146, v146
	v_exp_f32_e32 v147, v147
	v_mul_f32_e64 v149, |v145|, s49
	v_exp_f32_e32 v149, v149
	v_add_f32_e32 v127, 1.0, v127
	v_add_f32_e32 v146, 1.0, v146
	v_add_f32_e32 v147, 1.0, v147
	v_log_f32_e32 v127, v127
	v_log_f32_e32 v146, v146
	v_log_f32_e32 v150, v147
	v_add_f32_e32 v147, 1.0, v149
	v_log_f32_e32 v149, v147
	v_min_f32_e32 v143, 0, v143
	v_xor_b32_e32 v147, 0x80000000, v146
	v_xor_b32_e32 v146, 0x80000000, v127
	v_min_f32_e32 v145, 0, v145
	v_pk_fma_f32 v[142:143], v[146:147], s[48:49], v[142:143] op_sel_hi:[1,0,1]
	v_xor_b32_e32 v147, 0x80000000, v149
	v_xor_b32_e32 v146, 0x80000000, v150
	v_pk_fma_f32 v[144:145], v[146:147], s[48:49], v[144:145] op_sel_hi:[1,0,1]
	v_pk_mul_f32 v[142:143], v[142:143], s[54:55] op_sel_hi:[1,0]
	v_pk_mul_f32 v[144:145], v[144:145], s[54:55] op_sel_hi:[1,0]
	ds_write_b128 v182, v[142:145]
	v_mfma_f32_16x16x32_bf16 v[142:145], v[108:111], v[52:55], 0
	s_nop 7
	v_add_f32_e32 v127, v112, v142
	v_add_f32_e32 v143, v113, v143
	v_add_f32_e32 v147, v114, v144
	v_min_f32_e32 v142, 0, v127
	v_mul_f32_e64 v127, |v127|, s49
	v_mul_f32_e64 v146, |v143|, s49
	v_min_f32_e32 v144, 0, v147
	v_mul_f32_e64 v147, |v147|, s49
	v_add_f32_e32 v145, v115, v145
	v_exp_f32_e32 v127, v127
	v_exp_f32_e32 v146, v146
	v_exp_f32_e32 v147, v147
	v_mul_f32_e64 v148, |v145|, s49
	v_exp_f32_e32 v148, v148
	v_add_f32_e32 v127, 1.0, v127
	v_add_f32_e32 v146, 1.0, v146
	v_add_f32_e32 v147, 1.0, v147
	v_log_f32_e32 v127, v127
	v_log_f32_e32 v146, v146
	v_log_f32_e32 v149, v147
	v_add_f32_e32 v147, 1.0, v148
	v_log_f32_e32 v148, v147
	v_min_f32_e32 v143, 0, v143
	v_xor_b32_e32 v147, 0x80000000, v146
	v_xor_b32_e32 v146, 0x80000000, v127
	v_min_f32_e32 v145, 0, v145
	v_pk_fma_f32 v[142:143], v[146:147], s[48:49], v[142:143] op_sel_hi:[1,0,1]
	v_xor_b32_e32 v147, 0x80000000, v148
	v_xor_b32_e32 v146, 0x80000000, v149
	v_pk_fma_f32 v[144:145], v[146:147], s[48:49], v[144:145] op_sel_hi:[1,0,1]
	v_pk_mul_f32 v[142:143], v[142:143], s[54:55] op_sel_hi:[1,0]
	v_pk_mul_f32 v[144:145], v[144:145], s[54:55] op_sel_hi:[1,0]
	ds_write_b128 v182, v[142:145] offset:8192
	v_mfma_f32_16x16x32_bf16 v[142:145], v[108:111], v[44:47], 0
	v_mfma_f32_16x16x32_bf16 v[108:111], v[108:111], v[36:39], 0
	s_nop 6
	v_add_f32_e32 v127, v112, v142
	v_add_f32_e32 v112, v112, v108
	v_add_f32_e32 v109, v113, v109
	v_add_f32_e32 v143, v113, v143
	v_add_f32_e32 v147, v114, v144
	v_min_f32_e32 v108, 0, v112
	v_mul_f32_e64 v112, |v112|, s49
	v_mul_f32_e64 v113, |v109|, s49
	v_add_f32_e32 v114, v114, v110
	v_add_f32_e32 v111, v115, v111
	v_min_f32_e32 v142, 0, v127
	v_mul_f32_e64 v127, |v127|, s49
	v_mul_f32_e64 v146, |v143|, s49
	v_min_f32_e32 v144, 0, v147
	v_mul_f32_e64 v147, |v147|, s49
	v_add_f32_e32 v145, v115, v145
	v_exp_f32_e32 v112, v112
	v_exp_f32_e32 v113, v113
	v_min_f32_e32 v110, 0, v114
	v_mul_f32_e64 v114, |v114|, s49
	v_mul_f32_e64 v115, |v111|, s49
	v_exp_f32_e32 v127, v127
	v_exp_f32_e32 v146, v146
	v_exp_f32_e32 v147, v147
	v_mul_f32_e64 v148, |v145|, s49
	v_exp_f32_e32 v114, v114
	v_exp_f32_e32 v115, v115
	v_exp_f32_e32 v148, v148
	v_add_f32_e32 v112, 1.0, v112
	v_add_f32_e32 v113, 1.0, v113
	v_add_f32_e32 v127, 1.0, v127
	v_add_f32_e32 v146, 1.0, v146
	v_add_f32_e32 v147, 1.0, v147
	v_log_f32_e32 v112, v112
	v_log_f32_e32 v113, v113
	v_add_f32_e32 v114, 1.0, v114
	v_add_f32_e32 v115, 1.0, v115
	v_log_f32_e32 v127, v127
	v_log_f32_e32 v146, v146
	v_log_f32_e32 v149, v147
	v_add_f32_e32 v147, 1.0, v148
	v_log_f32_e32 v114, v114
	v_log_f32_e32 v115, v115
	v_log_f32_e32 v148, v147
	v_min_f32_e32 v109, 0, v109
	v_xor_b32_e32 v113, 0x80000000, v113
	v_xor_b32_e32 v112, 0x80000000, v112
	v_min_f32_e32 v143, 0, v143
	v_xor_b32_e32 v147, 0x80000000, v146
	v_xor_b32_e32 v146, 0x80000000, v127
	v_min_f32_e32 v111, 0, v111
	v_pk_fma_f32 v[108:109], v[112:113], s[48:49], v[108:109] op_sel_hi:[1,0,1]
	v_xor_b32_e32 v113, 0x80000000, v115
	v_xor_b32_e32 v112, 0x80000000, v114
	v_min_f32_e32 v145, 0, v145
	v_pk_fma_f32 v[142:143], v[146:147], s[48:49], v[142:143] op_sel_hi:[1,0,1]
	v_xor_b32_e32 v147, 0x80000000, v148
	v_xor_b32_e32 v146, 0x80000000, v149
	v_pk_fma_f32 v[110:111], v[112:113], s[48:49], v[110:111] op_sel_hi:[1,0,1]
	v_pk_fma_f32 v[144:145], v[146:147], s[48:49], v[144:145] op_sel_hi:[1,0,1]
	v_pk_mul_f32 v[110:111], v[110:111], s[54:55] op_sel_hi:[1,0]
	v_pk_mul_f32 v[108:109], v[108:109], s[54:55] op_sel_hi:[1,0]
	v_pk_mul_f32 v[144:145], v[144:145], s[54:55] op_sel_hi:[1,0]
	v_pk_mul_f32 v[142:143], v[142:143], s[54:55] op_sel_hi:[1,0]
	ds_write_b128 v182, v[108:111] offset:24576
	v_add_u32_e32 v108, v176, v179
	ds_write_b128 v182, v[142:145] offset:16384
	s_waitcnt lgkmcnt(0)
	s_barrier
	ds_read2st64_b32 v[110:111], v108 offset1:2
	ds_read2st64_b32 v[112:113], v108 offset0:4 offset1:6
	ds_read2st64_b32 v[114:115], v108 offset0:8 offset1:10
	ds_read2st64_b32 v[142:143], v108 offset0:12 offset1:14
	ds_read2st64_b32 v[144:145], v108 offset0:16 offset1:18
	ds_read2st64_b32 v[146:147], v108 offset0:20 offset1:22
	ds_read2st64_b32 v[148:149], v108 offset0:24 offset1:26
	ds_read2st64_b32 v[150:151], v108 offset0:28 offset1:30
	s_waitcnt lgkmcnt(7)
	v_add_f32_e32 v166, 0, v110
	v_add_f32_e32 v167, v166, v111
	s_waitcnt lgkmcnt(6)
	v_add_f32_e32 v163, v167, v112
	v_add_f32_e32 v165, v163, v113
	s_waitcnt lgkmcnt(5)
	v_add_f32_e32 v161, v165, v114
	v_add_f32_e32 v162, v161, v115
	s_waitcnt lgkmcnt(4)
	v_add_f32_e32 v159, v162, v142
	v_add_f32_e32 v160, v159, v143
	s_waitcnt lgkmcnt(3)
	v_add_f32_e32 v115, v160, v144
	v_add_f32_e32 v127, v115, v145
	s_waitcnt lgkmcnt(2)
	v_add_f32_e32 v113, v127, v146
	v_add_f32_e32 v114, v113, v147
	s_waitcnt lgkmcnt(1)
	v_add_f32_e32 v111, v114, v148
	v_add_f32_e32 v112, v111, v149
	s_waitcnt lgkmcnt(0)
	v_add_f32_e32 v109, v112, v150
	v_add_f32_e32 v110, v109, v151
	ds_write_b32 v181, v110
	s_waitcnt lgkmcnt(0)
	s_barrier
	s_and_saveexec_b64 s[14:15], s[12:13]
	s_cbranch_execnz .LBB0_1673
	s_or_b64 exec, exec, s[14:15]
	v_cmp_lt_i32_e64 s[14:15], 1, v123
	s_and_saveexec_b64 s[16:17], s[14:15]
	s_cbranch_execnz .LBB0_1674

.LBB0_1614:
	s_or_b64 exec, exec, s[18:19]
	s_waitcnt vmcnt(16)
	v_lshlrev_b32_e32 v148, 16, v100
	v_and_b32_e32 v149, 0xffff0000, v100
	v_lshlrev_b32_e32 v146, 16, v101
	v_and_b32_e32 v147, 0xffff0000, v101
	v_add_f32_e32 v100, v166, v169
	v_add_f32_e32 v101, v167, v169
	ds_write2st64_b32 v108, v100, v101 offset1:2
	v_add_f32_e32 v100, v163, v169
	v_add_f32_e32 v101, v165, v169
	ds_write2st64_b32 v108, v100, v101 offset0:4 offset1:6
	v_add_f32_e32 v100, v161, v169
	v_add_f32_e32 v101, v162, v169
	ds_write2st64_b32 v108, v100, v101 offset0:8 offset1:10
	v_add_f32_e32 v100, v159, v169
	v_add_f32_e32 v101, v160, v169
	ds_write2st64_b32 v108, v100, v101 offset0:12 offset1:14
	v_add_f32_e32 v100, v115, v169
	v_add_f32_e32 v101, v127, v169
	ds_write2st64_b32 v108, v100, v101 offset0:16 offset1:18
	v_add_f32_e32 v100, v113, v169
	v_add_f32_e32 v101, v114, v169
	ds_write2st64_b32 v108, v100, v101 offset0:20 offset1:22
	v_add_f32_e32 v100, v111, v169
	v_add_f32_e32 v101, v112, v169
	ds_write2st64_b32 v108, v100, v101 offset0:24 offset1:26
	v_add_f32_e32 v100, v109, v169
	v_add_f32_e32 v101, v110, v169
	v_lshl_add_u32 v184, v158, 2, 0
	ds_write2st64_b32 v108, v100, v101 offset0:28 offset1:30
	v_lshlrev_b32_e32 v100, 9, v168
	v_add_u32_e32 v186, v184, v100
	v_lshlrev_b32_e32 v156, 16, v104
	v_and_b32_e32 v157, 0xffff0000, v104
	v_lshlrev_b32_e32 v154, 16, v105
	v_and_b32_e32 v155, 0xffff0000, v105
	v_lshlrev_b32_e32 v152, 16, v106
	v_and_b32_e32 v153, 0xffff0000, v106
	v_lshlrev_b32_e32 v150, 16, v107
	v_and_b32_e32 v151, 0xffff0000, v107
	s_waitcnt lgkmcnt(0)
	s_barrier
	ds_read_b128 v[104:107], v184 offset:16384
	ds_read_b128 v[108:111], v186
	v_and_b32_e32 v159, 0xffff0000, v96
	v_ashrrev_i32_e32 v100, 3, v185
	v_lshlrev_b32_e32 v144, 16, v102
	v_and_b32_e32 v145, 0xffff0000, v102
	s_waitcnt lgkmcnt(0)
	v_sub_f32_e32 v158, v108, v104
	v_mul_f32_e32 v158, 0x3fb8aa3b, v158
	v_exp_f32_e32 v160, v158
	v_sub_f32_e32 v158, v104, v108
	v_mul_f32_e32 v158, 0x3fb8aa3b, v158
	v_exp_f32_e32 v162, v158
	v_lshlrev_b32_e32 v158, 16, v96
	v_sub_f32_e32 v96, v109, v105
	v_mul_f32_e32 v96, 0x3fb8aa3b, v96
	v_exp_f32_e32 v161, v96
	v_sub_f32_e32 v96, v105, v109
	v_mul_f32_e32 v96, 0x3fb8aa3b, v96
	v_exp_f32_e32 v163, v96
	v_mul_f32_e32 v96, 0x3fb8aa3b, v109
	v_exp_f32_e32 v109, v96
	v_sub_f32_e32 v96, v110, v106
	v_pk_mul_f32 v[172:173], v[162:163], v[156:157]
	v_lshlrev_b32_e32 v162, 16, v97
	v_and_b32_e32 v163, 0xffff0000, v97
	v_sub_f32_e32 v97, v111, v107
	v_lshlrev_b32_e32 v142, 16, v103
	v_and_b32_e32 v143, 0xffff0000, v103
	v_and_b32_e32 v127, 0xffffffe0, v100
	ds_read_b128 v[100:103], v184 offset:16400
	ds_read_b128 v[112:115], v186 offset:16
	v_mul_f32_e32 v96, 0x3fb8aa3b, v96
	v_mul_f32_e32 v97, 0x3fb8aa3b, v97
	v_exp_f32_e32 v96, v96
	v_exp_f32_e32 v97, v97
	v_pk_mul_f32 v[162:163], v[162:163], s[56:57] op_sel_hi:[1,0]
	v_pk_mul_f32 v[158:159], v[158:159], s[56:57] op_sel_hi:[1,0]
	v_mul_f32_e32 v108, 0x3fb8aa3b, v108
	v_pk_mul_f32 v[188:189], v[162:163], v[96:97]
	s_waitcnt lgkmcnt(0)
	v_sub_f32_e32 v97, v100, v112
	v_pk_mul_f32 v[170:171], v[158:159], v[160:161]
	v_sub_f32_e32 v160, v106, v110
	v_sub_f32_e32 v161, v107, v111
	v_mul_f32_e32 v97, 0x3fb8aa3b, v97
	v_mul_f32_e32 v160, 0x3fb8aa3b, v160
	v_mul_f32_e32 v161, 0x3fb8aa3b, v161
	v_exp_f32_e32 v166, v97
	v_mul_f32_e32 v97, 0x3fb8aa3b, v112
	v_exp_f32_e32 v160, v160
	v_exp_f32_e32 v161, v161
	v_sub_f32_e32 v96, v112, v100
	v_exp_f32_e32 v112, v97
	v_sub_f32_e32 v97, v113, v101
	v_mul_f32_e32 v96, 0x3fb8aa3b, v96
	v_mul_f32_e32 v97, 0x3fb8aa3b, v97
	v_exp_f32_e32 v96, v96
	v_exp_f32_e32 v97, v97
	v_pk_mul_f32 v[190:191], v[160:161], v[154:155]
	v_lshlrev_b32_e32 v160, 16, v98
	v_and_b32_e32 v161, 0xffff0000, v98
	v_sub_f32_e32 v98, v101, v113
	v_mul_f32_e32 v98, 0x3fb8aa3b, v98
	v_pk_mul_f32 v[160:161], v[160:161], s[56:57] op_sel_hi:[1,0]
	v_exp_f32_e32 v167, v98
	v_pk_mul_f32 v[192:193], v[160:161], v[96:97]
	v_sub_f32_e32 v97, v102, v114
	v_mul_f32_e32 v98, 0x3fb8aa3b, v113
	v_mul_f32_e32 v97, 0x3fb8aa3b, v97
	v_exp_f32_e32 v113, v98
	v_exp_f32_e32 v98, v97
	v_mul_f32_e32 v97, 0x3fb8aa3b, v114
	v_sub_f32_e32 v96, v114, v102
	v_exp_f32_e32 v114, v97
	v_sub_f32_e32 v97, v115, v103
	v_pk_mul_f32 v[194:195], v[166:167], v[152:153]
	v_mul_f32_e32 v96, 0x3fb8aa3b, v96
	v_lshlrev_b32_e32 v166, 16, v99
	v_and_b32_e32 v167, 0xffff0000, v99
	v_mul_f32_e32 v97, 0x3fb8aa3b, v97
	v_sub_f32_e32 v99, v103, v115
	v_exp_f32_e32 v96, v96
	v_exp_f32_e32 v97, v97
	v_mul_f32_e32 v99, 0x3fb8aa3b, v99
	v_mul_f32_e32 v110, 0x3fb8aa3b, v110
	v_mul_f32_e32 v111, 0x3fb8aa3b, v111
	v_exp_f32_e32 v99, v99
	v_mul_f32_e32 v115, 0x3fb8aa3b, v115
	v_exp_f32_e32 v108, v108
	v_exp_f32_e32 v110, v110
	v_exp_f32_e32 v111, v111
	v_exp_f32_e32 v115, v115
	v_pk_mul_f32 v[166:167], v[166:167], s[56:57] op_sel_hi:[1,0]
	v_sub_u32_e32 v123, v184, v0
	v_pk_mul_f32 v[196:197], v[166:167], v[96:97]
	v_mul_lo_u32 v165, v168, s55
	v_pk_mul_f32 v[198:199], v[98:99], v[150:151]
	v_cvt_pk_bf16_f32 v96, v170, v171
	v_cvt_pk_bf16_f32 v97, v188, v189
	v_cvt_pk_bf16_f32 v98, v192, v193
	v_cvt_pk_bf16_f32 v99, v196, v197
	v_add_u32_e32 v183, v123, v165
	v_pk_mul_f32 v[108:109], v[158:159], v[108:109]
	v_pk_mul_f32 v[110:111], v[162:163], v[110:111]
	v_pk_mul_f32 v[112:113], v[160:161], v[112:113]
	v_pk_mul_f32 v[114:115], v[166:167], v[114:115]
	ds_write_b128 v183, v[96:99] offset:32768
	v_cvt_pk_bf16_f32 v96, v172, v173
	v_cvt_pk_bf16_f32 v97, v190, v191
	v_cvt_pk_bf16_f32 v98, v194, v195
	v_cvt_pk_bf16_f32 v99, v198, v199
	ds_write_b128 v183, v[96:99] offset:50176
	v_cvt_pk_bf16_f32 v96, v108, v109
	v_cvt_pk_bf16_f32 v97, v110, v111
	v_cvt_pk_bf16_f32 v98, v112, v113
	v_cvt_pk_bf16_f32 v99, v114, v115
	v_add3_u32 v0, s94, v0, v165
	ds_write_b128 v0, v[96:99]
	v_lshlrev_b32_e32 v96, 9, v164
	v_add_u32_e32 v189, v184, v96
	ds_read_b128 v[96:99], v189
	v_or_b32_e32 v108, v127, v131
	v_mul_lo_u32 v187, v108, s55
	ds_read_b128 v[108:111], v189 offset:16
	v_lshlrev_b32_e32 v114, 16, v60
	v_and_b32_e32 v115, 0xffff0000, v60
	s_waitcnt lgkmcnt(1)
	v_sub_f32_e32 v60, v97, v105
	v_mul_f32_e32 v60, 0x3fb8aa3b, v60
	v_exp_f32_e32 v113, v60
	v_sub_f32_e32 v60, v105, v97
	v_mul_f32_e32 v60, 0x3fb8aa3b, v60
	v_exp_f32_e32 v105, v60
	v_mul_f32_e32 v60, 0x3fb8aa3b, v97
	v_exp_f32_e32 v97, v60
	v_pk_mul_f32 v[164:165], v[114:115], s[56:57] op_sel_hi:[1,0]
	v_sub_f32_e32 v60, v98, v106
	v_lshlrev_b32_e32 v114, 16, v61
	v_and_b32_e32 v115, 0xffff0000, v61
	v_sub_f32_e32 v61, v99, v107
	v_mul_f32_e32 v60, 0x3fb8aa3b, v60
	v_mul_f32_e32 v61, 0x3fb8aa3b, v61
	v_exp_f32_e32 v60, v60
	v_exp_f32_e32 v61, v61
	v_pk_mul_f32 v[170:171], v[114:115], s[56:57] op_sel_hi:[1,0]
	v_lshlrev_b32_e32 v168, 16, v62
	v_and_b32_e32 v169, 0xffff0000, v62
	v_pk_mul_f32 v[114:115], v[170:171], v[60:61]
	s_waitcnt lgkmcnt(0)
	v_sub_f32_e32 v61, v100, v108
	v_mul_f32_e32 v61, 0x3fb8aa3b, v61
	v_sub_f32_e32 v60, v108, v100
	v_exp_f32_e32 v100, v61
	v_mul_f32_e32 v61, 0x3fb8aa3b, v108
	v_exp_f32_e32 v108, v61
	v_sub_f32_e32 v61, v109, v101
	v_mul_f32_e32 v60, 0x3fb8aa3b, v60
	v_mul_f32_e32 v61, 0x3fb8aa3b, v61
	v_exp_f32_e32 v60, v60
	v_exp_f32_e32 v61, v61
	v_sub_f32_e32 v62, v101, v109
	v_pk_mul_f32 v[168:169], v[168:169], s[56:57] op_sel_hi:[1,0]
	v_mul_f32_e32 v62, 0x3fb8aa3b, v62
	v_pk_mul_f32 v[190:191], v[168:169], v[60:61]
	v_sub_f32_e32 v61, v102, v110
	v_exp_f32_e32 v101, v62
	v_mul_f32_e32 v62, 0x3fb8aa3b, v109
	v_mul_f32_e32 v61, 0x3fb8aa3b, v61
	v_exp_f32_e32 v109, v62
	v_exp_f32_e32 v62, v61
	v_mul_f32_e32 v61, 0x3fb8aa3b, v110
	v_sub_f32_e32 v112, v96, v104
	v_sub_f32_e32 v60, v110, v102
	v_exp_f32_e32 v102, v61
	v_sub_f32_e32 v61, v111, v103
	v_mul_f32_e32 v112, 0x3fb8aa3b, v112
	v_sub_f32_e32 v104, v104, v96
	v_sub_f32_e32 v106, v106, v98
	v_sub_f32_e32 v107, v107, v99
	v_mul_f32_e32 v60, 0x3fb8aa3b, v60
	v_lshlrev_b32_e32 v172, 16, v63
	v_and_b32_e32 v173, 0xffff0000, v63
	v_mul_f32_e32 v61, 0x3fb8aa3b, v61
	v_sub_f32_e32 v63, v103, v111
	v_exp_f32_e32 v112, v112
	v_mul_f32_e32 v104, 0x3fb8aa3b, v104
	v_mul_f32_e32 v106, 0x3fb8aa3b, v106
	v_mul_f32_e32 v107, 0x3fb8aa3b, v107
	v_exp_f32_e32 v60, v60
	v_exp_f32_e32 v61, v61
	v_mul_f32_e32 v63, 0x3fb8aa3b, v63
	v_exp_f32_e32 v104, v104
	v_mul_f32_e32 v96, 0x3fb8aa3b, v96
	v_exp_f32_e32 v106, v106
	v_mul_f32_e32 v98, 0x3fb8aa3b, v98
	v_exp_f32_e32 v107, v107
	v_mul_f32_e32 v99, 0x3fb8aa3b, v99
	v_exp_f32_e32 v63, v63
	v_mul_f32_e32 v103, 0x3fb8aa3b, v111
	v_exp_f32_e32 v96, v96
	v_exp_f32_e32 v98, v98
	v_exp_f32_e32 v99, v99
	v_exp_f32_e32 v103, v103
	v_pk_mul_f32 v[172:173], v[172:173], s[56:57] op_sel_hi:[1,0]
	v_pk_mul_f32 v[112:113], v[164:165], v[112:113]
	v_pk_mul_f32 v[110:111], v[172:173], v[60:61]
	v_pk_mul_f32 v[104:105], v[104:105], v[148:149]
	v_pk_mul_f32 v[106:107], v[106:107], v[146:147]
	v_pk_mul_f32 v[100:101], v[100:101], v[144:145]
	v_pk_mul_f32 v[192:193], v[62:63], v[142:143]
	v_cvt_pk_bf16_f32 v60, v112, v113
	v_cvt_pk_bf16_f32 v61, v114, v115
	v_cvt_pk_bf16_f32 v62, v190, v191
	v_cvt_pk_bf16_f32 v63, v110, v111
	v_add_u32_e32 v123, 0, v116
	v_pk_mul_f32 v[96:97], v[164:165], v[96:97]
	v_pk_mul_f32 v[98:99], v[170:171], v[98:99]
	v_pk_mul_f32 v[108:109], v[168:169], v[108:109]
	v_pk_mul_f32 v[102:103], v[172:173], v[102:103]
	ds_write_b128 v183, v[60:63] offset:41472
	v_cvt_pk_bf16_f32 v60, v104, v105
	v_cvt_pk_bf16_f32 v61, v106, v107
	v_cvt_pk_bf16_f32 v62, v100, v101
	v_cvt_pk_bf16_f32 v63, v192, v193
	ds_write_b128 v183, v[60:63] offset:58880
	v_cvt_pk_bf16_f32 v60, v96, v97
	v_cvt_pk_bf16_f32 v61, v98, v99
	v_cvt_pk_bf16_f32 v62, v108, v109
	v_cvt_pk_bf16_f32 v63, v102, v103
	v_add_u32_e32 v190, v123, v187
	ds_write_b128 v0, v[60:63] offset:8704
	s_waitcnt lgkmcnt(0)
	s_barrier
	ds_read_b128 v[60:63], v190 offset:50176
	v_and_or_b32 v187, v122, 48, v131
	v_mad_u32_u24 v96, v187, s55, 0
	v_add_u32_e32 v191, v96, v116
	ds_read_b128 v[96:99], v191 offset:32768
	ds_read_b128 v[100:103], v191 offset:32832
	ds_read_b128 v[104:107], v190 offset:50240
	ds_read_b128 v[108:111], v190 offset:54528
	ds_read_b128 v[112:115], v190 offset:54592
	s_waitcnt lgkmcnt(4)
	v_mfma_f32_16x16x32_bf16 v[60:63], v[60:63], v[96:99], 0
	v_lshlrev_b32_e32 v117, 2, v117
	v_or_b32_e32 v192, v117, v127
	v_cmp_ge_i32_e32 vcc, v187, v192
	s_waitcnt lgkmcnt(1)
	v_mfma_f32_16x16x32_bf16 v[96:99], v[108:111], v[96:99], 0
	ds_read_b128 v[108:111], v190 offset:50304
	v_cmp_gt_i32_e64 s[18:19], v187, v192
	v_mul_u32_u24_e32 v117, 0x90, v187
	v_mfma_f32_16x16x32_bf16 v[60:63], v[104:107], v[100:103], v[60:63]
	ds_read_b128 v[104:107], v191 offset:32896
	ds_read_b128 v[194:197], v190 offset:54656
	v_or_b32_e32 v198, 17, v192
	v_or_b32_e32 v200, 18, v192
	s_waitcnt lgkmcnt(3)
	v_mfma_f32_16x16x32_bf16 v[96:99], v[112:115], v[100:103], v[96:99]
	ds_read_b128 v[100:103], v191 offset:32960
	ds_read_b128 v[112:115], v190 offset:50368
	v_bfe_u32 v122, v185, 2, 2
	v_or_b32_e32 v201, 19, v192
	s_waitcnt lgkmcnt(3)
	v_mfma_f32_16x16x32_bf16 v[60:63], v[108:111], v[104:107], v[60:63]
	ds_read_b128 v[108:111], v190 offset:54720
	v_add_u32_e32 v188, s95, v116
	v_add_u32_e32 v199, s94, v116
	s_waitcnt lgkmcnt(3)
	v_mfma_f32_16x16x32_bf16 v[96:99], v[194:197], v[104:107], v[96:99]
	v_or_b32_e32 v195, 2, v192
	v_or_b32_e32 v196, 3, v192
	v_or_b32_e32 v197, 16, v192
	s_waitcnt lgkmcnt(1)
	v_mfma_f32_16x16x32_bf16 v[60:63], v[112:115], v[100:103], v[60:63]
	v_lshrrev_b32_e32 v104, 1, v185
	v_lshlrev_b32_e32 v105, 4, v133
	v_and_or_b32 v194, v104, 24, v122
	s_waitcnt lgkmcnt(0)
	v_mfma_f32_16x16x32_bf16 v[96:99], v[108:111], v[100:103], v[96:99]
	v_lshlrev_b32_e32 v104, 1, v132
	s_nop 1
	v_cndmask_b32_e32 v60, 0, v60, vcc
	v_cmp_ge_i32_e32 vcc, v187, v195
	v_cndmask_b32_e64 v61, 0, v61, s[18:19]
	v_cvt_pk_bf16_f32 v60, v60, v61
	v_cndmask_b32_e32 v62, 0, v62, vcc
	v_cmp_ge_i32_e32 vcc, v187, v196
	v_and_b32_e32 v105, 48, v105
	v_add3_u32 v185, s73, v104, v105
	v_cndmask_b32_e32 v63, 0, v63, vcc
	v_cvt_pk_bf16_f32 v61, v62, v63
	v_lshlrev_b32_e32 v62, 1, v192
	v_cmp_ge_i32_e32 vcc, v187, v197
	v_add3_u32 v193, s95, v117, v62
	v_mad_u32_u24 v117, v194, s35, v185
	v_cndmask_b32_e32 v62, 0, v96, vcc
	v_cmp_ge_i32_e32 vcc, v187, v198
	v_mad_u32_u24 v122, v131, s57, v188
	v_mad_u32_u24 v116, v131, s55, v199
	v_cndmask_b32_e32 v63, 0, v97, vcc
	v_cmp_ge_i32_e32 vcc, v187, v200
	v_cvt_pk_bf16_f32 v62, v62, v63
	s_nop 0
	v_cndmask_b32_e32 v96, 0, v98, vcc
	v_cmp_ge_i32_e32 vcc, v187, v201
	s_nop 1
	v_cndmask_b32_e32 v97, 0, v99, vcc
	v_cvt_pk_bf16_f32 v63, v96, v97
	ds_write2_b64 v193, v[60:61], v[62:63] offset1:4
	s_waitcnt lgkmcnt(0)
	s_barrier
	ds_read_b64_tr_b16 v[62:63], v117 offset:2176
	ds_read_b64_tr_b16 v[60:61], v117
	ds_read_b64_tr_b16 v[98:99], v117 offset:2184
	ds_read_b64_tr_b16 v[96:97], v117 offset:8
	ds_read_b128 v[100:103], v122
	ds_read_b128 v[104:107], v122 offset:64
	ds_read_b128 v[112:115], v122 offset:2304
	ds_read_b128 v[206:209], v122 offset:2368
	ds_read_b128 v[214:217], v122 offset:4608
	ds_read_b128 v[218:221], v122 offset:4672
	ds_read_b128 v[226:229], v122 offset:6912
	ds_read_b128 v[230:233], v122 offset:6976
	s_waitcnt lgkmcnt(7)
	v_mfma_f32_16x16x32_bf16 v[108:111], v[60:63], v[100:103], 0
	ds_read_b64_tr_b16 v[234:235], v117 offset:17408
	ds_read_b64_tr_b16 v[236:237], v117 offset:19584
	v_mfma_f32_16x16x32_bf16 v[100:103], v[96:99], v[100:103], 0
	s_waitcnt lgkmcnt(7)
	v_mfma_f32_16x16x32_bf16 v[210:213], v[60:63], v[112:115], 0
	v_mfma_f32_16x16x32_bf16 v[112:115], v[96:99], v[112:115], 0
	s_waitcnt lgkmcnt(5)
	v_mfma_f32_16x16x32_bf16 v[222:225], v[60:63], v[214:217], 0
	v_mfma_f32_16x16x32_bf16 v[214:217], v[96:99], v[214:217], 0
	s_waitcnt lgkmcnt(3)
	v_mfma_f32_16x16x32_bf16 v[60:63], v[60:63], v[226:229], 0
	v_mfma_f32_16x16x32_bf16 v[96:99], v[96:99], v[226:229], 0
	ds_read_b64_tr_b16 v[228:229], v117 offset:19592
	ds_read_b64_tr_b16 v[226:227], v117 offset:17416
	s_waitcnt lgkmcnt(2)
	v_mfma_f32_16x16x32_bf16 v[108:111], v[234:237], v[104:107], v[108:111]
	s_waitcnt lgkmcnt(0)
	v_mfma_f32_16x16x32_bf16 v[100:103], v[226:229], v[104:107], v[100:103]
	v_mfma_f32_16x16x32_bf16 v[104:107], v[234:237], v[206:209], v[210:213]
	v_mfma_f32_16x16x32_bf16 v[112:115], v[226:229], v[206:209], v[112:115]
	v_mfma_f32_16x16x32_bf16 v[206:209], v[234:237], v[218:221], v[222:225]
	v_mfma_f32_16x16x32_bf16 v[210:213], v[226:229], v[218:221], v[214:217]
	s_nop 2
	ds_read_b128 v[214:217], v116
	ds_read_b128 v[218:221], v116 offset:64
	s_waitcnt vmcnt(7) lgkmcnt(1)
	v_mfma_f32_16x16x32_bf16 v[108:111], v[84:87], v[214:217], v[108:111]
	s_waitcnt vmcnt(3)
	v_mfma_f32_16x16x32_bf16 v[100:103], v[92:95], v[214:217], v[100:103]
	ds_read_b128 v[214:217], v116 offset:4352
	ds_read_b128 v[222:225], v116 offset:4416
	v_mfma_f32_16x16x32_bf16 v[96:99], v[226:229], v[230:233], v[96:99]
	s_waitcnt lgkmcnt(1)
	v_mfma_f32_16x16x32_bf16 v[104:107], v[84:87], v[214:217], v[104:107]
	v_mfma_f32_16x16x32_bf16 v[112:115], v[92:95], v[214:217], v[112:115]
	ds_read_b128 v[214:217], v116 offset:8704
	ds_read_b128 v[226:229], v116 offset:8768
	v_mfma_f32_16x16x32_bf16 v[60:63], v[234:237], v[230:233], v[60:63]
	s_waitcnt lgkmcnt(1)
	v_mfma_f32_16x16x32_bf16 v[206:209], v[84:87], v[214:217], v[206:209]
	v_mfma_f32_16x16x32_bf16 v[210:213], v[92:95], v[214:217], v[210:213]
	ds_read_b128 v[214:217], v116 offset:13056
	ds_read_b128 v[230:233], v116 offset:13120
	s_waitcnt lgkmcnt(1)
	v_mfma_f32_16x16x32_bf16 v[60:63], v[84:87], v[214:217], v[60:63]
	v_mfma_f32_16x16x32_bf16 v[84:87], v[92:95], v[214:217], v[96:99]
	v_mfma_f32_16x16x32_bf16 v[92:95], v[80:83], v[218:221], v[108:111]
	s_waitcnt vmcnt(2)
	v_mfma_f32_16x16x32_bf16 v[96:99], v[88:91], v[218:221], v[100:103]
	v_mfma_f32_16x16x32_bf16 v[100:103], v[80:83], v[222:225], v[104:107]
	v_mfma_f32_16x16x32_bf16 v[108:111], v[80:83], v[226:229], v[206:209]
	s_waitcnt lgkmcnt(0)
	v_mfma_f32_16x16x32_bf16 v[60:63], v[80:83], v[230:233], v[60:63]
	v_mfma_f32_16x16x32_bf16 v[80:83], v[88:91], v[230:233], v[84:87]
	v_mfma_f32_16x16x32_bf16 v[104:107], v[88:91], v[222:225], v[112:115]
	v_mfma_f32_16x16x32_bf16 v[112:115], v[88:91], v[226:229], v[210:213]
	s_nop 0
	ds_read_b128 v[84:87], v116 offset:128
	ds_read_b128 v[206:209], v116 offset:192
	s_waitcnt lgkmcnt(1)
	v_mfma_f32_16x16x32_bf16 v[88:91], v[68:71], v[84:87], v[92:95]
	s_waitcnt vmcnt(1)
	v_mfma_f32_16x16x32_bf16 v[84:87], v[76:79], v[84:87], v[96:99]
	s_nop 0
	ds_read_b128 v[92:95], v116 offset:4480
	s_nop 0
	ds_read_b128 v[96:99], v116 offset:4544
	s_waitcnt lgkmcnt(1)
	v_mfma_f32_16x16x32_bf16 v[100:103], v[68:71], v[92:95], v[100:103]
	v_mfma_f32_16x16x32_bf16 v[104:107], v[76:79], v[92:95], v[104:107]
	ds_read_b128 v[92:95], v116 offset:8832
	ds_read_b128 v[210:213], v116 offset:8896
	s_waitcnt lgkmcnt(1)
	v_mfma_f32_16x16x32_bf16 v[108:111], v[68:71], v[92:95], v[108:111]
	v_mfma_f32_16x16x32_bf16 v[112:115], v[76:79], v[92:95], v[112:115]
	ds_read_b128 v[92:95], v116 offset:13184
	ds_read_b128 v[214:217], v116 offset:13248
	s_waitcnt lgkmcnt(1)
	v_mfma_f32_16x16x32_bf16 v[60:63], v[68:71], v[92:95], v[60:63]
	v_mfma_f32_16x16x32_bf16 v[218:221], v[76:79], v[92:95], v[80:83]
	v_mfma_f32_16x16x32_bf16 v[88:91], v[64:67], v[206:209], v[88:91]
	s_waitcnt vmcnt(0)
	v_mfma_f32_16x16x32_bf16 v[92:95], v[72:75], v[206:209], v[84:87]
	v_mfma_f32_16x16x32_bf16 v[80:83], v[64:67], v[96:99], v[100:103]
	v_mfma_f32_16x16x32_bf16 v[84:87], v[72:75], v[96:99], v[104:107]
	v_mfma_f32_16x16x32_bf16 v[68:71], v[64:67], v[210:213], v[108:111]
	v_mfma_f32_16x16x32_bf16 v[76:79], v[72:75], v[210:213], v[112:115]
	s_waitcnt lgkmcnt(0)
	v_mfma_f32_16x16x32_bf16 v[64:67], v[64:67], v[214:217], v[60:63]
	v_mfma_f32_16x16x32_bf16 v[60:63], v[72:75], v[214:217], v[218:221]
	s_or_b32 s66, s62, 1
	s_cmp_lt_i32 s66, 45
	s_mov_b64 s[70:71], -1
	s_cbranch_scc1 .LBB0_1620
	s_cmp_lt_u32 s66, 61
	s_cbranch_scc1 .LBB0_1617
	s_sub_i32 s38, s62, 60
	s_mov_b64 s[70:71], 0
	s_mov_b64 s[64:65], s[30:31]
	s_mov_b64 s[68:69], s[38:39]

.LBB0_1626:
	s_or_b64 exec, exec, s[12:13]
	v_sub_u32_e32 v53, 0, v179
	v_sub_u32_e32 v54, 0, v202
	v_add_f32_e32 v52, v52, v40
	v_add_u32_e32 v53, v176, v53
	v_sub_u32_e32 v55, 0, v203
	ds_write_b32 v53, v52 offset:32256
	v_add_f32_e32 v51, v51, v40
	v_add_u32_e32 v52, v176, v54
	v_sub_u32_e32 v56, 0, v206
	ds_write_b32 v52, v51 offset:32256
	v_add_f32_e32 v50, v50, v40
	v_add_u32_e32 v51, v176, v55
	v_sub_u32_e32 v57, 0, v207
	ds_write_b32 v51, v50 offset:32256
	v_add_f32_e32 v49, v49, v40
	v_add_u32_e32 v50, v176, v56
	v_sub_u32_e32 v58, 0, v208
	ds_write_b32 v50, v49 offset:32256
	v_add_f32_e32 v48, v48, v40
	v_add_u32_e32 v49, v176, v57
	v_sub_u32_e32 v59, 0, v209
	ds_write_b32 v49, v48 offset:32256
	v_add_f32_e32 v47, v47, v40
	v_add_u32_e32 v48, v176, v58
	v_sub_u32_e32 v127, 0, v210
	ds_write_b32 v48, v47 offset:32256
	v_add_f32_e32 v46, v46, v40
	v_add_u32_e32 v47, v176, v59
	v_sub_u32_e32 v179, 0, v211
	ds_write_b32 v47, v46 offset:32256
	v_add_f32_e32 v45, v45, v40
	v_add_u32_e32 v46, v176, v127
	v_sub_u32_e32 v180, 0, v212
	ds_write_b32 v46, v45 offset:32256
	v_add_f32_e32 v44, v44, v40
	v_add_u32_e32 v45, v176, v179
	v_sub_u32_e32 v181, 0, v213
	ds_write_b32 v45, v44 offset:32256
	v_add_f32_e32 v43, v43, v40
	v_add_u32_e32 v44, v176, v180
	v_sub_u32_e32 v182, 0, v214
	ds_write_b32 v44, v43 offset:32256
	v_add_f32_e32 v42, v42, v40
	v_add_u32_e32 v43, v176, v181
	v_sub_u32_e32 v202, 0, v215
	ds_write_b32 v43, v42 offset:32256
	v_add_f32_e32 v41, v41, v40
	v_add_u32_e32 v42, v176, v182
	v_sub_u32_e32 v203, 0, v216
	ds_write_b32 v42, v41 offset:32256
	v_add_f32_e32 v39, v39, v40
	v_add_u32_e32 v41, v176, v202
	v_sub_u32_e32 v206, 0, v217
	ds_write_b32 v41, v39 offset:32256
	v_add_f32_e32 v38, v38, v40
	v_add_u32_e32 v39, v176, v203
	v_sub_u32_e32 v207, 0, v218
	ds_write_b32 v39, v38 offset:32256
	v_add_f32_e32 v37, v37, v40
	v_add_u32_e32 v38, v176, v206
	ds_write_b32 v38, v37 offset:32256
	v_add_f32_e32 v36, v36, v40
	v_add_u32_e32 v37, v176, v207
	ds_write_b32 v37, v36 offset:32256
	s_waitcnt lgkmcnt(0)
	s_barrier
	ds_read_b128 v[36:39], v186
	ds_read_b128 v[40:43], v184 offset:15872
	ds_read_b128 v[44:47], v184 offset:15888
	ds_read_b128 v[48:51], v186 offset:16
	s_waitcnt lgkmcnt(2)
	v_sub_f32_e32 v53, v40, v36
	v_mul_f32_e32 v53, 0x3fb8aa3b, v53
	v_sub_f32_e32 v55, v41, v37
	v_sub_f32_e32 v52, v36, v40
	v_exp_f32_e32 v54, v53
	v_sub_f32_e32 v53, v37, v41
	v_mul_f32_e32 v55, 0x3fb8aa3b, v55
	v_mul_f32_e32 v36, 0x3fb8aa3b, v36
	v_mul_f32_e32 v37, 0x3fb8aa3b, v37
	v_sub_f32_e32 v57, v42, v38
	v_exp_f32_e32 v55, v55
	v_exp_f32_e32 v36, v36
	v_exp_f32_e32 v37, v37
	v_mul_f32_e32 v57, 0x3fb8aa3b, v57
	v_sub_f32_e32 v59, v43, v39
	v_sub_f32_e32 v56, v38, v42
	v_exp_f32_e32 v58, v57
	v_mul_f32_e32 v38, 0x3fb8aa3b, v38
	v_sub_f32_e32 v57, v39, v43
	v_mul_f32_e32 v59, 0x3fb8aa3b, v59
	v_mul_f32_e32 v39, 0x3fb8aa3b, v39
	v_exp_f32_e32 v38, v38
	v_exp_f32_e32 v59, v59
	v_exp_f32_e32 v39, v39
	v_pk_mul_f32 v[54:55], v[54:55], v[156:157]
	v_pk_mul_f32 v[156:157], v[158:159], v[36:37]
	s_waitcnt lgkmcnt(0)
	v_sub_f32_e32 v37, v44, v48
	v_mul_f32_e32 v37, 0x3fb8aa3b, v37
	v_pk_mul_f32 v[58:59], v[58:59], v[154:155]
	v_pk_mul_f32 v[154:155], v[162:163], v[38:39]
	v_sub_f32_e32 v36, v48, v44
	v_exp_f32_e32 v38, v37
	v_sub_f32_e32 v37, v49, v45
	v_mul_f32_e32 v52, 0x3fb8aa3b, v52
	v_mul_f32_e32 v53, 0x3fb8aa3b, v53
	v_mul_f32_e32 v36, 0x3fb8aa3b, v36
	v_mul_f32_e32 v37, 0x3fb8aa3b, v37
	v_exp_f32_e32 v52, v52
	v_exp_f32_e32 v53, v53
	v_exp_f32_e32 v36, v36
	v_exp_f32_e32 v37, v37
	v_sub_f32_e32 v39, v45, v49
	v_mul_f32_e32 v39, 0x3fb8aa3b, v39
	v_exp_f32_e32 v39, v39
	v_pk_mul_f32 v[52:53], v[158:159], v[52:53]
	v_pk_mul_f32 v[158:159], v[160:161], v[36:37]
	v_sub_f32_e32 v37, v46, v50
	v_mul_f32_e32 v37, 0x3fb8aa3b, v37
	v_pk_mul_f32 v[152:153], v[38:39], v[152:153]
	v_mul_f32_e32 v36, 0x3fb8aa3b, v49
	v_exp_f32_e32 v38, v37
	v_mul_f32_e32 v37, 0x3fb8aa3b, v50
	v_exp_f32_e32 v49, v36
	v_sub_f32_e32 v36, v50, v46
	v_exp_f32_e32 v50, v37
	v_sub_f32_e32 v37, v51, v47
	v_mul_f32_e32 v56, 0x3fb8aa3b, v56
	v_mul_f32_e32 v57, 0x3fb8aa3b, v57
	v_mul_f32_e32 v48, 0x3fb8aa3b, v48
	v_mul_f32_e32 v36, 0x3fb8aa3b, v36
	v_mul_f32_e32 v37, 0x3fb8aa3b, v37
	v_sub_f32_e32 v39, v47, v51
	v_exp_f32_e32 v56, v56
	v_exp_f32_e32 v57, v57
	v_exp_f32_e32 v48, v48
	v_exp_f32_e32 v36, v36
	v_exp_f32_e32 v37, v37
	v_mul_f32_e32 v39, 0x3fb8aa3b, v39
	v_exp_f32_e32 v39, v39
	v_mul_f32_e32 v51, 0x3fb8aa3b, v51
	v_exp_f32_e32 v51, v51
	v_pk_mul_f32 v[56:57], v[162:163], v[56:57]
	v_pk_mul_f32 v[48:49], v[160:161], v[48:49]
	v_pk_mul_f32 v[160:161], v[166:167], v[36:37]
	v_pk_mul_f32 v[150:151], v[38:39], v[150:151]
	v_cvt_pk_bf16_f32 v36, v52, v53
	v_cvt_pk_bf16_f32 v37, v56, v57
	v_cvt_pk_bf16_f32 v38, v158, v159
	v_cvt_pk_bf16_f32 v39, v160, v161
	v_pk_mul_f32 v[50:51], v[166:167], v[50:51]
	ds_write_b128 v183, v[36:39] offset:32768
	v_cvt_pk_bf16_f32 v36, v54, v55
	v_cvt_pk_bf16_f32 v37, v58, v59
	v_cvt_pk_bf16_f32 v38, v152, v153
	v_cvt_pk_bf16_f32 v39, v150, v151
	ds_write_b128 v183, v[36:39] offset:50176
	v_cvt_pk_bf16_f32 v36, v156, v157
	v_cvt_pk_bf16_f32 v37, v154, v155
	v_cvt_pk_bf16_f32 v38, v48, v49
	v_cvt_pk_bf16_f32 v39, v50, v51
	ds_write_b128 v0, v[36:39]
	ds_read_b128 v[36:39], v189
	ds_read_b128 v[48:51], v189 offset:16
	s_waitcnt lgkmcnt(1)
	v_sub_f32_e32 v52, v36, v40
	v_sub_f32_e32 v40, v40, v36
	v_sub_f32_e32 v53, v37, v41
	v_sub_f32_e32 v41, v41, v37
	v_mul_f32_e32 v36, 0x3fb8aa3b, v36
	v_mul_f32_e32 v37, 0x3fb8aa3b, v37
	v_exp_f32_e32 v36, v36
	v_exp_f32_e32 v37, v37
	v_sub_f32_e32 v54, v38, v42
	v_sub_f32_e32 v42, v42, v38
	v_mul_f32_e32 v38, 0x3fb8aa3b, v38
	v_sub_f32_e32 v55, v39, v43
	v_sub_f32_e32 v43, v43, v39
	v_mul_f32_e32 v39, 0x3fb8aa3b, v39
	v_exp_f32_e32 v38, v38
	v_exp_f32_e32 v39, v39
	v_pk_mul_f32 v[56:57], v[164:165], v[36:37]
	s_waitcnt lgkmcnt(0)
	v_sub_f32_e32 v37, v44, v48
	v_mul_f32_e32 v37, 0x3fb8aa3b, v37
	v_pk_mul_f32 v[58:59], v[170:171], v[38:39]
	v_sub_f32_e32 v36, v48, v44
	v_exp_f32_e32 v38, v37
	v_sub_f32_e32 v37, v49, v45
	v_mul_f32_e32 v42, 0x3fb8aa3b, v42
	v_mul_f32_e32 v43, 0x3fb8aa3b, v43
	v_mul_f32_e32 v36, 0x3fb8aa3b, v36
	v_mul_f32_e32 v37, 0x3fb8aa3b, v37
	v_exp_f32_e32 v42, v42
	v_exp_f32_e32 v43, v43
	v_exp_f32_e32 v36, v36
	v_exp_f32_e32 v37, v37
	v_sub_f32_e32 v39, v45, v49
	v_mul_f32_e32 v39, 0x3fb8aa3b, v39
	v_exp_f32_e32 v39, v39
	v_pk_mul_f32 v[42:43], v[42:43], v[146:147]
	v_pk_mul_f32 v[146:147], v[168:169], v[36:37]
	v_sub_f32_e32 v37, v46, v50
	v_mul_f32_e32 v37, 0x3fb8aa3b, v37
	v_pk_mul_f32 v[144:145], v[38:39], v[144:145]
	v_mul_f32_e32 v36, 0x3fb8aa3b, v49
	v_exp_f32_e32 v38, v37
	v_mul_f32_e32 v37, 0x3fb8aa3b, v50
	v_exp_f32_e32 v45, v36
	v_sub_f32_e32 v36, v50, v46
	v_exp_f32_e32 v46, v37
	v_sub_f32_e32 v37, v51, v47
	v_mul_f32_e32 v52, 0x3fb8aa3b, v52
	v_mul_f32_e32 v53, 0x3fb8aa3b, v53
	v_mul_f32_e32 v54, 0x3fb8aa3b, v54
	v_mul_f32_e32 v55, 0x3fb8aa3b, v55
	v_mul_f32_e32 v36, 0x3fb8aa3b, v36
	v_mul_f32_e32 v37, 0x3fb8aa3b, v37
	v_sub_f32_e32 v39, v47, v51
	v_exp_f32_e32 v52, v52
	v_mul_f32_e32 v40, 0x3fb8aa3b, v40
	v_exp_f32_e32 v53, v53
	v_mul_f32_e32 v41, 0x3fb8aa3b, v41
	v_exp_f32_e32 v54, v54
	v_exp_f32_e32 v55, v55
	v_exp_f32_e32 v36, v36
	v_exp_f32_e32 v37, v37
	v_mul_f32_e32 v39, 0x3fb8aa3b, v39
	v_exp_f32_e32 v40, v40
	v_exp_f32_e32 v41, v41
	v_mul_f32_e32 v44, 0x3fb8aa3b, v48
	v_exp_f32_e32 v39, v39
	v_mul_f32_e32 v47, 0x3fb8aa3b, v51
	v_exp_f32_e32 v44, v44
	v_exp_f32_e32 v47, v47
	v_pk_mul_f32 v[52:53], v[164:165], v[52:53]
	v_pk_mul_f32 v[54:55], v[170:171], v[54:55]
	v_pk_mul_f32 v[48:49], v[172:173], v[36:37]
	v_pk_mul_f32 v[40:41], v[40:41], v[148:149]
	v_pk_mul_f32 v[50:51], v[38:39], v[142:143]
	v_cvt_pk_bf16_f32 v36, v52, v53
	v_cvt_pk_bf16_f32 v37, v54, v55
	v_cvt_pk_bf16_f32 v38, v146, v147
	v_cvt_pk_bf16_f32 v39, v48, v49
	v_pk_mul_f32 v[44:45], v[168:169], v[44:45]
	v_pk_mul_f32 v[46:47], v[172:173], v[46:47]
	ds_write_b128 v183, v[36:39] offset:41472
	v_cvt_pk_bf16_f32 v36, v40, v41
	v_cvt_pk_bf16_f32 v37, v42, v43
	v_cvt_pk_bf16_f32 v38, v144, v145
	v_cvt_pk_bf16_f32 v39, v50, v51
	ds_write_b128 v183, v[36:39] offset:58880
	v_cvt_pk_bf16_f32 v36, v56, v57
	v_cvt_pk_bf16_f32 v37, v58, v59
	v_cvt_pk_bf16_f32 v38, v44, v45
	v_cvt_pk_bf16_f32 v39, v46, v47
	ds_write_b128 v0, v[36:39] offset:8704
	s_waitcnt lgkmcnt(0)
	s_barrier
	ds_read_b128 v[36:39], v190 offset:50176
	ds_read_b128 v[40:43], v191 offset:32768
	ds_read_b128 v[44:47], v191 offset:32832
	ds_read_b128 v[48:51], v190 offset:50240
	s_waitcnt lgkmcnt(2)
	v_mfma_f32_16x16x32_bf16 v[36:39], v[36:39], v[40:43], 0
	ds_read_b128 v[52:55], v190 offset:54528
	ds_read_b128 v[56:59], v190 offset:54592
	v_mul_u32_u24_e32 v0, 0x90, v131
	v_add_u32_e32 v0, v188, v0
	s_waitcnt lgkmcnt(2)
	v_mfma_f32_16x16x32_bf16 v[36:39], v[48:51], v[44:47], v[36:39]
	ds_read_b128 v[48:51], v190 offset:50304
	s_waitcnt lgkmcnt(2)
	v_mfma_f32_16x16x32_bf16 v[40:43], v[52:55], v[40:43], 0
	s_waitcnt lgkmcnt(1)
	v_mfma_f32_16x16x32_bf16 v[40:43], v[56:59], v[44:47], v[40:43]
	ds_read_b128 v[44:47], v191 offset:32896
	ds_read_b128 v[52:55], v191 offset:32960
	ds_read_b128 v[56:59], v190 offset:50368
	s_waitcnt lgkmcnt(2)
	v_mfma_f32_16x16x32_bf16 v[36:39], v[48:51], v[44:47], v[36:39]
	ds_read_b128 v[48:51], v190 offset:54656
	ds_read_b128 v[142:145], v190 offset:54720
	s_waitcnt lgkmcnt(1)
	v_mfma_f32_16x16x32_bf16 v[40:43], v[48:51], v[44:47], v[40:43]
	v_or_b32_e32 v45, 1, v192
	v_cmp_le_i32_e32 vcc, v187, v45
	v_mul_u32_u24_e32 v44, 0x220, v194
	v_mfma_f32_16x16x32_bf16 v[36:39], v[56:59], v[52:55], v[36:39]
	v_add_u32_e32 v127, v185, v44
	s_waitcnt lgkmcnt(0)
	v_mfma_f32_16x16x32_bf16 v[40:43], v[142:145], v[52:55], v[40:43]
	s_nop 4
	v_cndmask_b32_e32 v37, 0, v37, vcc
	v_cmp_le_i32_e32 vcc, v187, v195
	v_cndmask_b32_e64 v36, v36, 0, s[18:19]
	v_cvt_pk_bf16_f32 v36, v36, v37
	v_cndmask_b32_e32 v38, 0, v38, vcc
	v_cmp_le_i32_e32 vcc, v187, v196
	s_nop 1
	v_cndmask_b32_e32 v39, 0, v39, vcc
	v_cmp_le_i32_e32 vcc, v187, v197
	v_cvt_pk_bf16_f32 v37, v38, v39
	s_nop 0
	v_cndmask_b32_e32 v38, 0, v40, vcc
	v_cmp_le_i32_e32 vcc, v187, v198
	s_nop 1
	v_cndmask_b32_e32 v39, 0, v41, vcc
	v_cmp_le_i32_e32 vcc, v187, v200
	v_cvt_pk_bf16_f32 v38, v38, v39
	s_nop 0
	v_cndmask_b32_e32 v40, 0, v42, vcc
	v_cmp_le_i32_e32 vcc, v187, v201
	s_nop 1
	v_cndmask_b32_e32 v41, 0, v43, vcc
	v_cvt_pk_bf16_f32 v39, v40, v41
	ds_write2_b64 v193, v[36:37], v[38:39] offset1:4
	s_waitcnt lgkmcnt(0)
	s_barrier
	ds_read_b64_tr_b16 v[38:39], v127 offset:2176
	ds_read_b64_tr_b16 v[36:37], v127
	ds_read_b64_tr_b16 v[42:43], v127 offset:2184
	ds_read_b64_tr_b16 v[40:41], v127 offset:8
	ds_read_b128 v[44:47], v0
	ds_read_b128 v[48:51], v0 offset:64
	s_waitcnt lgkmcnt(1)
	v_mfma_f32_16x16x32_bf16 v[52:55], v[36:39], v[44:47], v[88:91]
	ds_read_b128 v[56:59], v0 offset:2304
	s_nop 1
	ds_read_b128 v[88:91], v0 offset:2368
	v_mfma_f32_16x16x32_bf16 v[44:47], v[40:43], v[44:47], v[92:95]
	s_waitcnt lgkmcnt(1)
	v_mfma_f32_16x16x32_bf16 v[80:83], v[36:39], v[56:59], v[80:83]
	v_mfma_f32_16x16x32_bf16 v[56:59], v[40:43], v[56:59], v[84:87]
	s_nop 2
	ds_read_b128 v[84:87], v0 offset:4608
	ds_read_b128 v[92:95], v0 offset:4672
	s_waitcnt lgkmcnt(1)
	v_mfma_f32_16x16x32_bf16 v[68:71], v[36:39], v[84:87], v[68:71]
	v_mfma_f32_16x16x32_bf16 v[76:79], v[40:43], v[84:87], v[76:79]
	ds_read_b128 v[84:87], v0 offset:6912
	ds_read_b128 v[142:145], v0 offset:6976
	v_mul_u32_u24_e32 v0, 0x110, v131
	v_add_u32_e32 v0, v199, v0
	s_waitcnt lgkmcnt(1)
	v_mfma_f32_16x16x32_bf16 v[36:39], v[36:39], v[84:87], v[64:67]
	s_nop 2
	ds_read_b64_tr_b16 v[64:65], v127 offset:17408
	ds_read_b64_tr_b16 v[66:67], v127 offset:19584
	v_mfma_f32_16x16x32_bf16 v[40:43], v[40:43], v[84:87], v[60:63]
	s_nop 2
	ds_read_b64_tr_b16 v[62:63], v127 offset:19592
	ds_read_b64_tr_b16 v[60:61], v127 offset:17416
	s_waitcnt lgkmcnt(2)
	v_mfma_f32_16x16x32_bf16 v[52:55], v[64:67], v[48:51], v[52:55]
	s_waitcnt lgkmcnt(0)
	v_mfma_f32_16x16x32_bf16 v[44:47], v[60:63], v[48:51], v[44:47]
	v_mfma_f32_16x16x32_bf16 v[48:51], v[64:67], v[88:91], v[80:83]
	v_mfma_f32_16x16x32_bf16 v[56:59], v[60:63], v[88:91], v[56:59]
	v_mfma_f32_16x16x32_bf16 v[68:71], v[64:67], v[92:95], v[68:71]
	v_mfma_f32_16x16x32_bf16 v[76:79], v[60:63], v[92:95], v[76:79]
	v_mfma_f32_16x16x32_bf16 v[36:39], v[64:67], v[142:145], v[36:39]
	v_mfma_f32_16x16x32_bf16 v[40:43], v[60:63], v[142:145], v[40:43]
	ds_read_b128 v[60:63], v0
	ds_read_b128 v[64:67], v0 offset:64
	s_waitcnt vmcnt(7) lgkmcnt(1)
	v_mfma_f32_16x16x32_bf16 v[52:55], v[116:119], v[60:63], v[52:55]
	s_waitcnt vmcnt(3)
	v_mfma_f32_16x16x32_bf16 v[44:47], v[120:123], v[60:63], v[44:47]
	ds_read_b128 v[60:63], v0 offset:4352
	ds_read_b128 v[80:83], v0 offset:4416
	s_waitcnt lgkmcnt(1)
	v_mfma_f32_16x16x32_bf16 v[48:51], v[116:119], v[60:63], v[48:51]
	v_mfma_f32_16x16x32_bf16 v[56:59], v[120:123], v[60:63], v[56:59]
	ds_read_b128 v[60:63], v0 offset:8704
	ds_read_b128 v[84:87], v0 offset:8768
	s_waitcnt lgkmcnt(1)
	v_mfma_f32_16x16x32_bf16 v[68:71], v[116:119], v[60:63], v[68:71]
	v_mfma_f32_16x16x32_bf16 v[60:63], v[120:123], v[60:63], v[76:79]
	s_nop 2
	ds_read_b128 v[76:79], v0 offset:13056
	ds_read_b128 v[88:91], v0 offset:13120
	s_waitcnt lgkmcnt(1)
	v_mfma_f32_16x16x32_bf16 v[36:39], v[116:119], v[76:79], v[36:39]
	v_mfma_f32_16x16x32_bf16 v[40:43], v[120:123], v[76:79], v[40:43]
	v_mfma_f32_16x16x32_bf16 v[52:55], v[108:111], v[64:67], v[52:55]
	s_waitcnt vmcnt(2)
	v_mfma_f32_16x16x32_bf16 v[44:47], v[112:115], v[64:67], v[44:47]
	v_mfma_f32_16x16x32_bf16 v[48:51], v[108:111], v[80:83], v[48:51]
	v_mfma_f32_16x16x32_bf16 v[56:59], v[112:115], v[80:83], v[56:59]
	v_mfma_f32_16x16x32_bf16 v[64:67], v[108:111], v[84:87], v[68:71]
	v_mfma_f32_16x16x32_bf16 v[60:63], v[112:115], v[84:87], v[60:63]
	s_waitcnt lgkmcnt(0)
	v_mfma_f32_16x16x32_bf16 v[36:39], v[108:111], v[88:91], v[36:39]
	v_mfma_f32_16x16x32_bf16 v[40:43], v[112:115], v[88:91], v[40:43]
	ds_read_b128 v[68:71], v0 offset:128
	ds_read_b128 v[76:79], v0 offset:192
	s_waitcnt lgkmcnt(1)
	v_mfma_f32_16x16x32_bf16 v[52:55], v[100:103], v[68:71], v[52:55]
	s_waitcnt vmcnt(1)
	v_mfma_f32_16x16x32_bf16 v[44:47], v[104:107], v[68:71], v[44:47]
	ds_read_b128 v[68:71], v0 offset:4480
	ds_read_b128 v[84:87], v0 offset:4544
	s_waitcnt lgkmcnt(1)
	v_mfma_f32_16x16x32_bf16 v[48:51], v[100:103], v[68:71], v[48:51]
	v_mfma_f32_16x16x32_bf16 v[56:59], v[104:107], v[68:71], v[56:59]
	ds_read_b128 v[68:71], v0 offset:8832
	ds_read_b128 v[88:91], v0 offset:8896
	s_waitcnt lgkmcnt(1)
	v_mfma_f32_16x16x32_bf16 v[92:95], v[100:103], v[68:71], v[64:67]
	v_mfma_f32_16x16x32_bf16 v[68:71], v[104:107], v[68:71], v[60:63]
	s_nop 2
	ds_read_b128 v[60:63], v0 offset:13184
	ds_read_b128 v[108:111], v0 offset:13248
	s_waitcnt lgkmcnt(1)
	v_mfma_f32_16x16x32_bf16 v[36:39], v[100:103], v[60:63], v[36:39]
	v_mfma_f32_16x16x32_bf16 v[100:103], v[104:107], v[60:63], v[40:43]
	v_mfma_f32_16x16x32_bf16 v[80:83], v[72:75], v[76:79], v[52:55]
	s_waitcnt vmcnt(0)
	v_mfma_f32_16x16x32_bf16 v[76:79], v[96:99], v[76:79], v[44:47]
	v_mfma_f32_16x16x32_bf16 v[64:67], v[72:75], v[84:87], v[48:51]
	v_mfma_f32_16x16x32_bf16 v[60:63], v[96:99], v[84:87], v[56:59]
	v_mfma_f32_16x16x32_bf16 v[52:55], v[72:75], v[88:91], v[92:95]
	v_mfma_f32_16x16x32_bf16 v[48:51], v[96:99], v[88:91], v[68:71]
	s_waitcnt lgkmcnt(0)
	v_mfma_f32_16x16x32_bf16 v[40:43], v[72:75], v[108:111], v[36:39]
	v_mfma_f32_16x16x32_bf16 v[36:39], v[96:99], v[108:111], v[100:103]
	s_cmpk_gt_i32 s81, 0x3ff
	s_cbranch_scc1 .Lgca11_skip
	s_ashr_i32 s32, s81, 8
	s_lshl_b32 s32, s32, 12
	s_and_b32 s66, s81, 63
	s_lshl_b32 s66, s66, 6
	s_or_b32 s32, s32, s66
	s_bfe_u32 s66, s81, 0x20006
	s_lshl_b32 s66, s66, 7
	s_mov_b32 s100, s21
	s_mov_b32 s101, 0
	v_and_b32_e32 v230, 48, v204
	v_mov_b32_e32 v231, 0
	v_and_b32_e32 v232, 15, v204
	v_mov_b64_e32 v[234:235], s[46:47]
	v_or_b32_e32 v233, s32, v232
	v_mad_u64_u32 v[236:237], s[98:99], v233, s33, v[234:235]
	v_lshl_add_u64 v[236:237], v[236:237], 0, v[230:231]
	v_lshl_add_u64 v[236:237], v[236:237], 0, s[100:101]
	global_load_dwordx4 v[206:209], v[236:237], off offset:2048
	v_or_b32_e32 v233, 16, v232
	v_or_b32_e32 v233, s32, v233
	v_mad_u64_u32 v[236:237], s[98:99], v233, s33, v[234:235]
	v_lshl_add_u64 v[236:237], v[236:237], 0, v[230:231]
	v_lshl_add_u64 v[236:237], v[236:237], 0, s[100:101]
	global_load_dwordx4 v[210:213], v[236:237], off offset:2048
	v_or_b32_e32 v233, 32, v232
	v_or_b32_e32 v233, s32, v233
	v_mad_u64_u32 v[236:237], s[98:99], v233, s33, v[234:235]
	v_lshl_add_u64 v[236:237], v[236:237], 0, v[230:231]
	v_lshl_add_u64 v[236:237], v[236:237], 0, s[100:101]
	global_load_dwordx4 v[214:217], v[236:237], off offset:2048
	v_or_b32_e32 v233, 48, v232
	v_or_b32_e32 v233, s32, v233
	v_mad_u64_u32 v[236:237], s[98:99], v233, s33, v[234:235]
	v_lshl_add_u64 v[236:237], v[236:237], 0, v[230:231]
	v_lshl_add_u64 v[236:237], v[236:237], 0, s[100:101]
	global_load_dwordx4 v[218:221], v[236:237], off offset:2048
	v_lshrrev_b32_e32 v233, 6, v204
	v_lshlrev_b32_e32 v233, 4, v233
	v_or_b32_e32 v236, s66, v232
	v_add_u32_e32 v236, v236, v233
	v_lshlrev_b32_e32 v236, 5, v236
	v_and_b32_e32 v233, 16, v204
	v_add_u32_e32 v236, v236, v233
	v_mov_b32_e32 v237, 0
	v_lshl_add_u64 v[236:237], v[236:237], 0, s[50:51]
	v_mov_b32_e32 v222, 0
	v_mov_b32_e32 v223, 0
	v_mov_b32_e32 v224, 0
	v_mov_b32_e32 v225, 0
	v_and_b32_e32 v233, 63, v204
	v_cmp_gt_u32_e32 vcc, 32, v233
	s_and_saveexec_b64 s[70:71], vcc
	global_load_dwordx4 v[222:225], v[236:237], off
	s_or_b64 exec, exec, s[70:71]
	s_lshl_b32 s66, s66, 2
	s_add_u32 s86, s24, s66
	s_addc_u32 s87, s25, 0
	v_lshrrev_b32_e32 v233, 6, v204
	v_lshlrev_b32_e32 v236, 6, v233
	v_bfe_u32 v233, v204, 4, 2
	v_lshl_add_u32 v236, v233, 4, v236
	v_mov_b32_e32 v237, 0
	v_lshl_add_u64 v[236:237], v[236:237], 0, s[86:87]
	global_load_dwordx4 v[226:229], v[236:237], off
.Lgca11_skip:
	v_or_b32_e32 v84, v175, v132
	v_ashrrev_i32_e32 v85, 31, v84
	s_lshl_b32 s38, s84, 9
	v_lshl_add_u64 v[44:45], v[134:135], 0, s[38:39]
	v_lshlrev_b64 v[46:47], 1, v[84:85]
	v_lshl_add_u64 v[44:45], v[44:45], 0, v[46:47]
	v_add_co_u32_e32 v44, vcc, s21, v44
	v_lshl_add_u64 v[56:57], v[136:137], 0, s[38:39]
	s_nop 0
	v_addc_co_u32_e32 v45, vcc, 0, v45, vcc
	v_lshl_add_u64 v[56:57], v[56:57], 0, v[46:47]
	v_add_co_u32_e32 v56, vcc, s21, v56
	v_and_b32_e32 v86, 64, v205
	s_nop 0
	v_addc_co_u32_e32 v57, vcc, 0, v57, vcc
	global_load_dwordx4 v[72:75], v[44:45], off
	global_load_dwordx4 v[68:71], v[56:57], off
	v_lshl_add_u64 v[44:45], v[138:139], 0, s[38:39]
	v_lshl_add_u64 v[44:45], v[44:45], 0, v[46:47]
	v_add_co_u32_e32 v44, vcc, s21, v44
	v_lshl_add_u64 v[56:57], v[140:141], 0, s[38:39]
	s_nop 0
	v_addc_co_u32_e32 v45, vcc, 0, v45, vcc
	v_lshl_add_u64 v[46:47], v[56:57], 0, v[46:47]
	v_add_co_u32_e32 v46, vcc, s21, v46
	v_xor_b32_e32 v0, 16, v205
	s_nop 0
	v_addc_co_u32_e32 v47, vcc, 0, v47, vcc
	global_load_dwordx4 v[56:59], v[44:45], off
	s_nop 0
	global_load_dwordx4 v[44:47], v[46:47], off
	v_add_u32_e32 v86, 64, v86
	v_cmp_lt_i32_e32 vcc, v0, v86
	v_xor_b32_e32 v88, 32, v205
	s_nop 0
	v_cndmask_b32_e32 v0, v205, v0, vcc
	v_lshlrev_b32_e32 v175, 2, v0
	v_mul_f32_e32 v0, v81, v81
	v_fmac_f32_e32 v0, v80, v80
	v_fmac_f32_e32 v0, v82, v82
	v_fmac_f32_e32 v0, v83, v83
	v_fmac_f32_e32 v0, v76, v76
	v_fmac_f32_e32 v0, v77, v77
	v_fmac_f32_e32 v0, v78, v78
	v_fmac_f32_e32 v0, v79, v79
	ds_bpermute_b32 v87, v175, v0
	v_cmp_lt_i32_e32 vcc, v88, v86
	s_nop 1
	v_cndmask_b32_e32 v86, v205, v88, vcc
	v_lshlrev_b32_e32 v176, 2, v86
	s_waitcnt lgkmcnt(0)
	v_add_f32_e32 v86, v0, v87
	ds_bpermute_b32 v87, v176, v86
	v_lshlrev_b32_e32 v0, 2, v178
	v_lshlrev_b32_e32 v88, 2, v131
	v_cmp_gt_u32_e32 vcc, 16, v133
	v_add3_u32 v0, s96, v0, v88
	s_and_saveexec_b64 s[12:13], vcc
	s_cbranch_execz .LBB0_1628
	s_waitcnt lgkmcnt(0)
	v_add_f32_e32 v86, v86, v87
	ds_write_b32 v0, v86

.LBB0_1637:
	s_ashr_i32 s14, s81, 8
	s_and_b32 s67, s81, 63
	s_ashr_i32 s15, s14, 31
	s_bfe_u32 s82, s81, 0x20006
	v_mov_b32_e32 v187, v204
	s_lshl_b64 s[12:13], s[14:15], 12
	s_lshl_b32 s2, s67, 6
	s_or_b32 s12, s12, s2
	v_lshlrev_b32_e32 v0, 3, v187
	s_lshl_b32 s15, s82, 7
	s_lshl_b32 s2, s82, 8
	v_and_b32_e32 v158, 0x78, v0
	v_ashrrev_i32_e32 v168, 4, v187
	s_add_u32 s16, s46, s2
	s_addc_u32 s17, s47, 0
	v_lshlrev_b32_e32 v0, 1, v158
	v_ashrrev_i32_e32 v169, 31, v168
	v_lshl_add_u64 v[2:3], s[16:17], 0, v[0:1]
	v_lshl_add_u64 v[36:37], s[12:13], 0, v[168:169]
	v_add_u32_e32 v164, 32, v168
	v_mad_u64_u32 v[38:39], s[16:17], v36, s33, v[2:3]
	v_ashrrev_i32_e32 v165, 31, v164
	v_mad_i32_i24 v39, v37, s33, v39
	v_lshl_add_u64 v[36:37], s[12:13], 0, v[164:165]
	v_mad_u64_u32 v[2:3], s[16:17], v36, s33, v[2:3]
	v_and_b32_e32 v131, 15, v187
	v_mad_i32_i24 v3, v37, s33, v3
	global_load_dwordx4 v[96:99], v[38:39], off
	global_load_dwordx4 v[104:107], v[38:39], off offset:1024
	global_load_dwordx4 v[60:63], v[2:3], off
	global_load_dwordx4 v[100:103], v[2:3], off offset:1024
	v_or_b32_e32 v2, s12, v131
	v_mov_b64_e32 v[36:37], s[46:47]
	v_mad_u64_u32 v[134:135], s[16:17], v2, s33, v[36:37]
	v_or_b32_e32 v129, 16, v131
	v_mad_i32_i24 v135, s13, v174, v135
	v_and_b32_e32 v116, 48, v187
	v_mov_b32_e32 v117, v1
	v_or_b32_e32 v130, s12, v129
	v_lshl_add_u64 v[38:39], v[134:135], 0, v[116:117]
	v_mad_u64_u32 v[136:137], s[16:17], v130, s33, v[36:37]
	v_or_b32_e32 v177, 32, v131
	v_add_co_u32_e32 v38, vcc, s21, v38
	v_mad_i32_i24 v137, s13, v174, v137
	v_or_b32_e32 v128, s12, v177
	v_addc_co_u32_e32 v39, vcc, 0, v39, vcc
	v_lshl_add_u64 v[40:41], v[136:137], 0, v[116:117]
	v_mad_u64_u32 v[138:139], s[16:17], v128, s33, v[36:37]
	v_or_b32_e32 v125, 48, v131
	v_add_co_u32_e32 v40, vcc, s21, v40
	v_mad_i32_i24 v139, s13, v174, v139
	v_or_b32_e32 v124, s12, v125
	v_addc_co_u32_e32 v41, vcc, 0, v41, vcc
	global_load_dword v239, v[38:39], off offset:2048
	v_mov_b32_e32 v56, v206
	v_mov_b32_e32 v57, v207
	v_mov_b32_e32 v58, v208
	v_mov_b32_e32 v59, v209
	global_load_dword v239, v[40:41], off offset:2048
	v_mov_b32_e32 v52, v210
	v_mov_b32_e32 v53, v211
	v_mov_b32_e32 v54, v212
	v_mov_b32_e32 v55, v213
	v_lshl_add_u64 v[38:39], v[138:139], 0, v[116:117]
	v_mad_u64_u32 v[140:141], s[16:17], v124, s33, v[36:37]
	v_add_co_u32_e32 v38, vcc, s21, v38
	v_mad_i32_i24 v141, s13, v174, v141
	s_nop 0
	v_addc_co_u32_e32 v39, vcc, 0, v39, vcc
	v_lshl_add_u64 v[36:37], v[140:141], 0, v[116:117]
	v_add_co_u32_e32 v36, vcc, s21, v36
	v_ashrrev_i32_e32 v66, 6, v187
	s_nop 0
	v_addc_co_u32_e32 v37, vcc, 0, v37, vcc
	global_load_dword v239, v[38:39], off offset:2048
	v_mov_b32_e32 v44, v214
	v_mov_b32_e32 v45, v215
	v_mov_b32_e32 v46, v216
	v_mov_b32_e32 v47, v217
	s_nop 0
	global_load_dword v239, v[36:37], off offset:2048
	v_mov_b32_e32 v36, v218
	v_mov_b32_e32 v37, v219
	v_mov_b32_e32 v38, v220
	v_mov_b32_e32 v39, v221
	v_lshlrev_b32_e32 v122, 4, v66
	v_or_b32_e32 v40, s15, v131
	v_and_b32_e32 v133, 63, v187
	v_add_u32_e32 v48, v40, v122
	v_and_b32_e32 v40, 16, v187
	v_mov_b32_e32 v41, v1
	v_mov_b32_e32 v3, s13
	v_lshl_add_u64 v[50:51], s[50:51], 0, v[40:41]
	v_cmp_lt_u32_e32 vcc, 31, v133
	v_cmp_gt_u32_e64 s[12:13], 32, v133
	v_mov_b32_e32 v40, 0
	v_ashrrev_i32_e32 v49, 31, v48
	v_mov_b32_e32 v108, 0
	v_mov_b32_e32 v109, 0
	v_mov_b32_e32 v110, 0
	v_mov_b32_e32 v111, 0
	s_and_saveexec_b64 s[16:17], s[12:13]
	s_cbranch_execz .LBB0_1639
	v_lshlrev_b64 v[42:43], 5, v[48:49]
	v_lshl_add_u64 v[42:43], v[50:51], 0, v[42:43]
	global_load_dword v239, v[42:43], off
	v_mov_b32_e32 v108, v222
	v_mov_b32_e32 v109, v223
	v_mov_b32_e32 v110, v224
	v_mov_b32_e32 v111, v225
.LBB0_1639:
	s_or_b64 exec, exec, s[16:17]
	s_lshl_b32 s12, s15, 2
	s_add_u32 s12, s24, s12
	v_bfe_u32 v117, v187, 4, 2
	s_addc_u32 s13, s25, 0
	v_ashrrev_i32_e32 v123, 31, v122
	v_lshl_add_u64 v[42:43], v[122:123], 2, s[12:13]
	v_lshlrev_b32_e32 v64, 4, v117
	v_mov_b32_e32 v65, v1
	v_lshl_add_u64 v[64:65], v[42:43], 0, v[64:65]
	global_load_dword v239, v[64:65], off
	v_mov_b32_e32 v112, v226
	v_mov_b32_e32 v113, v227
	v_mov_b32_e32 v114, v228
	v_mov_b32_e32 v115, v229
	v_mov_b32_e32 v41, 0
	v_mov_b32_e32 v42, 0
	v_mov_b32_e32 v43, 0
	s_and_saveexec_b64 s[12:13], vcc
	s_cbranch_execz .LBB0_1641
	v_lshlrev_b64 v[40:41], 5, v[48:49]
	v_lshl_add_u64 v[40:41], v[50:51], 0, v[40:41]
	v_add_co_u32_e32 v40, vcc, 0x4000, v40
	s_nop 1
	v_addc_co_u32_e32 v41, vcc, 0, v41, vcc
	global_load_dwordx4 v[40:43], v[40:41], off

.LBB0_1649:
	v_lshlrev_b32_e32 v64, 1, v131
	v_lshlrev_b32_e32 v132, 5, v66
	v_and_b32_e32 v64, 24, v64
	v_and_b32_e32 v65, 3, v187
	s_lshl_b64 s[16:17], s[16:17], 22
	v_or3_b32 v72, v65, v64, v132
	s_add_u32 s14, s14, s16
	s_addc_u32 s15, s15, s17
	s_lshl_b32 s16, s67, 16
	v_ashrrev_i32_e32 v73, 31, v72
	v_lshlrev_b32_e32 v179, 3, v117
	v_lshlrev_b32_e32 v64, 9, v131
	v_and_b32_e32 v178, 0xffffffc0, v187
	s_add_u32 s14, s14, s16
	v_lshlrev_b64 v[118:119], 8, v[72:73]
	v_or_b32_e32 v72, 4, v72
	v_add3_u32 v148, 0, v64, v178
	v_lshlrev_b32_e32 v64, 2, v187
	s_addc_u32 s15, s15, 0
	v_lshlrev_b32_e32 v126, 1, v179
	v_mov_b32_e32 v127, v1
	v_ashrrev_i32_e32 v73, 31, v72
	v_and_b32_e32 v65, 0x1fc, v64
	v_lshl_add_u64 v[74:75], s[14:15], 0, v[126:127]
	v_lshlrev_b64 v[120:121], 8, v[72:73]
	v_add_u32_e32 v180, 0, v65
	v_add_u32_e32 v183, s92, v64
	v_add_u32_e32 v182, s92, v65
	v_lshl_add_u64 v[64:65], v[74:75], 0, v[118:119]
	v_lshl_add_u64 v[72:73], v[74:75], 0, v[120:121]
	global_load_dwordx4 v[84:87], v[64:65], off
	global_load_dwordx4 v[80:83], v[64:65], off offset:64
	global_load_dwordx4 v[68:71], v[64:65], off offset:128
	s_nop 0
	global_load_dwordx4 v[64:67], v[64:65], off offset:192
	s_nop 0
	global_load_dwordx4 v[92:95], v[72:73], off
	global_load_dwordx4 v[88:91], v[72:73], off offset:64
	global_load_dwordx4 v[76:79], v[72:73], off offset:128
	s_nop 0
	global_load_dwordx4 v[72:75], v[72:73], off offset:192
	s_nop 0
	v_mfma_f32_16x16x32_bf16 v[142:145], v[108:111], v[56:59], 0
	v_add_u32_e32 v184, v148, v116
	v_ashrrev_i32_e32 v123, 7, v187
	v_lshlrev_b32_e32 v181, 13, v123
	v_cmp_lt_i32_e64 s[12:13], 0, v123
	v_mov_b32_e32 v169, 0
	s_nop 0
	s_nop 1
	v_add_f32_e32 v127, v112, v142
	v_add_f32_e32 v143, v113, v143
	v_add_f32_e32 v147, v114, v144
	v_min_f32_e32 v142, 0, v127
	v_mul_f32_e64 v127, |v127|, s49
	v_mul_f32_e64 v146, |v143|, s49
	v_min_f32_e32 v144, 0, v147
	v_mul_f32_e64 v147, |v147|, s49
	v_add_f32_e32 v145, v115, v145
	v_exp_f32_e32 v127, v127
	v_exp_f32_e32 v146, v146
	v_exp_f32_e32 v147, v147
	v_mul_f32_e64 v149, |v145|, s49
	v_exp_f32_e32 v149, v149
	v_add_f32_e32 v127, 1.0, v127
	v_add_f32_e32 v146, 1.0, v146
	v_add_f32_e32 v147, 1.0, v147
	v_log_f32_e32 v127, v127
	v_log_f32_e32 v146, v146
	v_log_f32_e32 v150, v147
	v_add_f32_e32 v147, 1.0, v149
	v_log_f32_e32 v149, v147
	v_min_f32_e32 v143, 0, v143
	v_xor_b32_e32 v147, 0x80000000, v146
	v_xor_b32_e32 v146, 0x80000000, v127
	v_min_f32_e32 v145, 0, v145
	v_pk_fma_f32 v[142:143], v[146:147], s[48:49], v[142:143] op_sel_hi:[1,0,1]
	v_xor_b32_e32 v147, 0x80000000, v149
	v_xor_b32_e32 v146, 0x80000000, v150
	v_pk_fma_f32 v[144:145], v[146:147], s[48:49], v[144:145] op_sel_hi:[1,0,1]
	v_pk_mul_f32 v[142:143], v[142:143], s[54:55] op_sel_hi:[1,0]
	v_pk_mul_f32 v[144:145], v[144:145], s[54:55] op_sel_hi:[1,0]
	ds_write_b128 v184, v[142:145]
	v_mfma_f32_16x16x32_bf16 v[142:145], v[108:111], v[52:55], 0
	s_nop 7
	v_add_f32_e32 v127, v112, v142
	v_add_f32_e32 v143, v113, v143
	v_add_f32_e32 v147, v114, v144
	v_min_f32_e32 v142, 0, v127
	v_mul_f32_e64 v127, |v127|, s49
	v_mul_f32_e64 v146, |v143|, s49
	v_min_f32_e32 v144, 0, v147
	v_mul_f32_e64 v147, |v147|, s49
	v_add_f32_e32 v145, v115, v145
	v_exp_f32_e32 v127, v127
	v_exp_f32_e32 v146, v146
	v_exp_f32_e32 v147, v147
	v_mul_f32_e64 v148, |v145|, s49
	v_exp_f32_e32 v148, v148
	v_add_f32_e32 v127, 1.0, v127
	v_add_f32_e32 v146, 1.0, v146
	v_add_f32_e32 v147, 1.0, v147
	v_log_f32_e32 v127, v127
	v_log_f32_e32 v146, v146
	v_log_f32_e32 v149, v147
	v_add_f32_e32 v147, 1.0, v148
	v_log_f32_e32 v148, v147
	v_min_f32_e32 v143, 0, v143
	v_xor_b32_e32 v147, 0x80000000, v146
	v_xor_b32_e32 v146, 0x80000000, v127
	v_min_f32_e32 v145, 0, v145
	v_pk_fma_f32 v[142:143], v[146:147], s[48:49], v[142:143] op_sel_hi:[1,0,1]
	v_xor_b32_e32 v147, 0x80000000, v148
	v_xor_b32_e32 v146, 0x80000000, v149
	v_pk_fma_f32 v[144:145], v[146:147], s[48:49], v[144:145] op_sel_hi:[1,0,1]
	v_pk_mul_f32 v[142:143], v[142:143], s[54:55] op_sel_hi:[1,0]
	v_pk_mul_f32 v[144:145], v[144:145], s[54:55] op_sel_hi:[1,0]
	ds_write_b128 v184, v[142:145] offset:8192
	v_mfma_f32_16x16x32_bf16 v[142:145], v[108:111], v[44:47], 0
	v_mfma_f32_16x16x32_bf16 v[108:111], v[108:111], v[36:39], 0
	s_nop 6
	v_add_f32_e32 v127, v112, v142
	v_add_f32_e32 v112, v112, v108
	v_add_f32_e32 v109, v113, v109
	v_add_f32_e32 v143, v113, v143
	v_add_f32_e32 v147, v114, v144
	v_min_f32_e32 v108, 0, v112
	v_mul_f32_e64 v112, |v112|, s49
	v_mul_f32_e64 v113, |v109|, s49
	v_add_f32_e32 v114, v114, v110
	v_add_f32_e32 v111, v115, v111
	v_min_f32_e32 v142, 0, v127
	v_mul_f32_e64 v127, |v127|, s49
	v_mul_f32_e64 v146, |v143|, s49
	v_min_f32_e32 v144, 0, v147
	v_mul_f32_e64 v147, |v147|, s49
	v_add_f32_e32 v145, v115, v145
	v_exp_f32_e32 v112, v112
	v_exp_f32_e32 v113, v113
	v_min_f32_e32 v110, 0, v114
	v_mul_f32_e64 v114, |v114|, s49
	v_mul_f32_e64 v115, |v111|, s49
	v_exp_f32_e32 v127, v127
	v_exp_f32_e32 v146, v146
	v_exp_f32_e32 v147, v147
	v_mul_f32_e64 v148, |v145|, s49
	v_exp_f32_e32 v114, v114
	v_exp_f32_e32 v115, v115
	v_exp_f32_e32 v148, v148
	v_add_f32_e32 v112, 1.0, v112
	v_add_f32_e32 v113, 1.0, v113
	v_add_f32_e32 v127, 1.0, v127
	v_add_f32_e32 v146, 1.0, v146
	v_add_f32_e32 v147, 1.0, v147
	v_log_f32_e32 v112, v112
	v_log_f32_e32 v113, v113
	v_add_f32_e32 v114, 1.0, v114
	v_add_f32_e32 v115, 1.0, v115
	v_log_f32_e32 v127, v127
	v_log_f32_e32 v146, v146
	v_log_f32_e32 v149, v147
	v_add_f32_e32 v147, 1.0, v148
	v_log_f32_e32 v114, v114
	v_log_f32_e32 v115, v115
	v_log_f32_e32 v148, v147
	v_min_f32_e32 v109, 0, v109
	v_xor_b32_e32 v113, 0x80000000, v113
	v_xor_b32_e32 v112, 0x80000000, v112
	v_min_f32_e32 v143, 0, v143
	v_xor_b32_e32 v147, 0x80000000, v146
	v_xor_b32_e32 v146, 0x80000000, v127
	v_min_f32_e32 v111, 0, v111
	v_pk_fma_f32 v[108:109], v[112:113], s[48:49], v[108:109] op_sel_hi:[1,0,1]
	v_xor_b32_e32 v113, 0x80000000, v115
	v_xor_b32_e32 v112, 0x80000000, v114
	v_min_f32_e32 v145, 0, v145
	v_pk_fma_f32 v[142:143], v[146:147], s[48:49], v[142:143] op_sel_hi:[1,0,1]
	v_xor_b32_e32 v147, 0x80000000, v148
	v_xor_b32_e32 v146, 0x80000000, v149
	v_pk_fma_f32 v[110:111], v[112:113], s[48:49], v[110:111] op_sel_hi:[1,0,1]
	v_pk_fma_f32 v[144:145], v[146:147], s[48:49], v[144:145] op_sel_hi:[1,0,1]
	v_pk_mul_f32 v[110:111], v[110:111], s[54:55] op_sel_hi:[1,0]
	v_pk_mul_f32 v[108:109], v[108:109], s[54:55] op_sel_hi:[1,0]
	v_pk_mul_f32 v[144:145], v[144:145], s[54:55] op_sel_hi:[1,0]
	v_pk_mul_f32 v[142:143], v[142:143], s[54:55] op_sel_hi:[1,0]
	ds_write_b128 v184, v[108:111] offset:24576
	v_add_u32_e32 v108, v180, v181
	ds_write_b128 v184, v[142:145] offset:16384
	s_waitcnt lgkmcnt(0)
	s_barrier
	ds_read2st64_b32 v[110:111], v108 offset1:2
	ds_read2st64_b32 v[112:113], v108 offset0:4 offset1:6
	ds_read2st64_b32 v[114:115], v108 offset0:8 offset1:10
	ds_read2st64_b32 v[142:143], v108 offset0:12 offset1:14
	ds_read2st64_b32 v[144:145], v108 offset0:16 offset1:18
	ds_read2st64_b32 v[146:147], v108 offset0:20 offset1:22
	ds_read2st64_b32 v[148:149], v108 offset0:24 offset1:26
	ds_read2st64_b32 v[150:151], v108 offset0:28 offset1:30
	s_waitcnt lgkmcnt(7)
	v_add_f32_e32 v166, 0, v110
	v_add_f32_e32 v167, v166, v111
	s_waitcnt lgkmcnt(6)
	v_add_f32_e32 v163, v167, v112
	v_add_f32_e32 v165, v163, v113
	s_waitcnt lgkmcnt(5)
	v_add_f32_e32 v161, v165, v114
	v_add_f32_e32 v162, v161, v115
	s_waitcnt lgkmcnt(4)
	v_add_f32_e32 v159, v162, v142
	v_add_f32_e32 v160, v159, v143
	s_waitcnt lgkmcnt(3)
	v_add_f32_e32 v115, v160, v144
	v_add_f32_e32 v127, v115, v145
	s_waitcnt lgkmcnt(2)
	v_add_f32_e32 v113, v127, v146
	v_add_f32_e32 v114, v113, v147
	s_waitcnt lgkmcnt(1)
	v_add_f32_e32 v111, v114, v148
	v_add_f32_e32 v112, v111, v149
	s_waitcnt lgkmcnt(0)
	v_add_f32_e32 v109, v112, v150
	v_add_f32_e32 v110, v109, v151
	ds_write_b32 v183, v110
	s_waitcnt lgkmcnt(0)
	s_barrier
	s_and_saveexec_b64 s[14:15], s[12:13]
	s_cbranch_execnz .LBB0_1677
	s_or_b64 exec, exec, s[14:15]
	v_cmp_lt_i32_e64 s[14:15], 1, v123
	s_and_saveexec_b64 s[16:17], s[14:15]
	s_cbranch_execnz .LBB0_1678

.LBB0_1653:
	s_or_b64 exec, exec, s[18:19]
	s_waitcnt vmcnt(16)
	v_lshlrev_b32_e32 v148, 16, v100
	v_and_b32_e32 v149, 0xffff0000, v100
	v_lshlrev_b32_e32 v146, 16, v101
	v_and_b32_e32 v147, 0xffff0000, v101
	v_add_f32_e32 v100, v166, v169
	v_add_f32_e32 v101, v167, v169
	ds_write2st64_b32 v108, v100, v101 offset1:2
	v_add_f32_e32 v100, v163, v169
	v_add_f32_e32 v101, v165, v169
	ds_write2st64_b32 v108, v100, v101 offset0:4 offset1:6
	v_add_f32_e32 v100, v161, v169
	v_add_f32_e32 v101, v162, v169
	ds_write2st64_b32 v108, v100, v101 offset0:8 offset1:10
	v_add_f32_e32 v100, v159, v169
	v_add_f32_e32 v101, v160, v169
	ds_write2st64_b32 v108, v100, v101 offset0:12 offset1:14
	v_add_f32_e32 v100, v115, v169
	v_add_f32_e32 v101, v127, v169
	ds_write2st64_b32 v108, v100, v101 offset0:16 offset1:18
	v_add_f32_e32 v100, v113, v169
	v_add_f32_e32 v101, v114, v169
	ds_write2st64_b32 v108, v100, v101 offset0:20 offset1:22
	v_add_f32_e32 v100, v111, v169
	v_add_f32_e32 v101, v112, v169
	ds_write2st64_b32 v108, v100, v101 offset0:24 offset1:26
	v_add_f32_e32 v100, v109, v169
	v_add_f32_e32 v101, v110, v169
	v_lshl_add_u32 v186, v158, 2, 0
	ds_write2st64_b32 v108, v100, v101 offset0:28 offset1:30
	v_lshlrev_b32_e32 v100, 9, v168
	v_add_u32_e32 v188, v186, v100
	v_lshlrev_b32_e32 v156, 16, v104
	v_and_b32_e32 v157, 0xffff0000, v104
	v_lshlrev_b32_e32 v154, 16, v105
	v_and_b32_e32 v155, 0xffff0000, v105
	v_lshlrev_b32_e32 v152, 16, v106
	v_and_b32_e32 v153, 0xffff0000, v106
	v_lshlrev_b32_e32 v150, 16, v107
	v_and_b32_e32 v151, 0xffff0000, v107
	s_waitcnt lgkmcnt(0)
	s_barrier
	ds_read_b128 v[104:107], v186 offset:16384
	ds_read_b128 v[108:111], v188
	v_and_b32_e32 v159, 0xffff0000, v96
	v_ashrrev_i32_e32 v100, 3, v187
	v_lshlrev_b32_e32 v144, 16, v102
	v_and_b32_e32 v145, 0xffff0000, v102
	s_waitcnt lgkmcnt(0)
	v_sub_f32_e32 v158, v108, v104
	v_mul_f32_e32 v158, 0x3fb8aa3b, v158
	v_exp_f32_e32 v160, v158
	v_sub_f32_e32 v158, v104, v108
	v_mul_f32_e32 v158, 0x3fb8aa3b, v158
	v_exp_f32_e32 v162, v158
	v_lshlrev_b32_e32 v158, 16, v96
	v_sub_f32_e32 v96, v109, v105
	v_mul_f32_e32 v96, 0x3fb8aa3b, v96
	v_exp_f32_e32 v161, v96
	v_sub_f32_e32 v96, v105, v109
	v_mul_f32_e32 v96, 0x3fb8aa3b, v96
	v_exp_f32_e32 v163, v96
	v_mul_f32_e32 v96, 0x3fb8aa3b, v109
	v_exp_f32_e32 v109, v96
	v_sub_f32_e32 v96, v110, v106
	v_pk_mul_f32 v[172:173], v[162:163], v[156:157]
	v_lshlrev_b32_e32 v162, 16, v97
	v_and_b32_e32 v163, 0xffff0000, v97
	v_sub_f32_e32 v97, v111, v107
	v_lshlrev_b32_e32 v142, 16, v103
	v_and_b32_e32 v143, 0xffff0000, v103
	v_and_b32_e32 v127, 0xffffffe0, v100
	ds_read_b128 v[100:103], v186 offset:16400
	ds_read_b128 v[112:115], v188 offset:16
	v_mul_f32_e32 v96, 0x3fb8aa3b, v96
	v_mul_f32_e32 v97, 0x3fb8aa3b, v97
	v_exp_f32_e32 v96, v96
	v_exp_f32_e32 v97, v97
	v_pk_mul_f32 v[162:163], v[162:163], s[56:57] op_sel_hi:[1,0]
	v_pk_mul_f32 v[158:159], v[158:159], s[56:57] op_sel_hi:[1,0]
	v_mul_f32_e32 v108, 0x3fb8aa3b, v108
	v_pk_mul_f32 v[190:191], v[162:163], v[96:97]
	s_waitcnt lgkmcnt(0)
	v_sub_f32_e32 v97, v100, v112
	v_pk_mul_f32 v[170:171], v[158:159], v[160:161]
	v_sub_f32_e32 v160, v106, v110
	v_sub_f32_e32 v161, v107, v111
	v_mul_f32_e32 v97, 0x3fb8aa3b, v97
	v_mul_f32_e32 v160, 0x3fb8aa3b, v160
	v_mul_f32_e32 v161, 0x3fb8aa3b, v161
	v_exp_f32_e32 v166, v97
	v_mul_f32_e32 v97, 0x3fb8aa3b, v112
	v_exp_f32_e32 v160, v160
	v_exp_f32_e32 v161, v161
	v_sub_f32_e32 v96, v112, v100
	v_exp_f32_e32 v112, v97
	v_sub_f32_e32 v97, v113, v101
	v_mul_f32_e32 v96, 0x3fb8aa3b, v96
	v_mul_f32_e32 v97, 0x3fb8aa3b, v97
	v_exp_f32_e32 v96, v96
	v_exp_f32_e32 v97, v97
	v_pk_mul_f32 v[192:193], v[160:161], v[154:155]
	v_lshlrev_b32_e32 v160, 16, v98
	v_and_b32_e32 v161, 0xffff0000, v98
	v_sub_f32_e32 v98, v101, v113
	v_mul_f32_e32 v98, 0x3fb8aa3b, v98
	v_pk_mul_f32 v[160:161], v[160:161], s[56:57] op_sel_hi:[1,0]
	v_exp_f32_e32 v167, v98
	v_pk_mul_f32 v[194:195], v[160:161], v[96:97]
	v_sub_f32_e32 v97, v102, v114
	v_mul_f32_e32 v98, 0x3fb8aa3b, v113
	v_mul_f32_e32 v97, 0x3fb8aa3b, v97
	v_exp_f32_e32 v113, v98
	v_exp_f32_e32 v98, v97
	v_mul_f32_e32 v97, 0x3fb8aa3b, v114
	v_sub_f32_e32 v96, v114, v102
	v_exp_f32_e32 v114, v97
	v_sub_f32_e32 v97, v115, v103
	v_pk_mul_f32 v[196:197], v[166:167], v[152:153]
	v_mul_f32_e32 v96, 0x3fb8aa3b, v96
	v_lshlrev_b32_e32 v166, 16, v99
	v_and_b32_e32 v167, 0xffff0000, v99
	v_mul_f32_e32 v97, 0x3fb8aa3b, v97
	v_sub_f32_e32 v99, v103, v115
	v_exp_f32_e32 v96, v96
	v_exp_f32_e32 v97, v97
	v_mul_f32_e32 v99, 0x3fb8aa3b, v99
	v_mul_f32_e32 v110, 0x3fb8aa3b, v110
	v_mul_f32_e32 v111, 0x3fb8aa3b, v111
	v_exp_f32_e32 v99, v99
	v_mul_f32_e32 v115, 0x3fb8aa3b, v115
	v_exp_f32_e32 v108, v108
	v_exp_f32_e32 v110, v110
	v_exp_f32_e32 v111, v111
	v_exp_f32_e32 v115, v115
	v_pk_mul_f32 v[166:167], v[166:167], s[56:57] op_sel_hi:[1,0]
	v_sub_u32_e32 v123, v186, v0
	v_pk_mul_f32 v[198:199], v[166:167], v[96:97]
	v_mul_lo_u32 v165, v168, s55
	v_pk_mul_f32 v[200:201], v[98:99], v[150:151]
	v_cvt_pk_bf16_f32 v96, v170, v171
	v_cvt_pk_bf16_f32 v97, v190, v191
	v_cvt_pk_bf16_f32 v98, v194, v195
	v_cvt_pk_bf16_f32 v99, v198, v199
	v_add_u32_e32 v185, v123, v165
	v_pk_mul_f32 v[108:109], v[158:159], v[108:109]
	v_pk_mul_f32 v[110:111], v[162:163], v[110:111]
	v_pk_mul_f32 v[112:113], v[160:161], v[112:113]
	v_pk_mul_f32 v[114:115], v[166:167], v[114:115]
	ds_write_b128 v185, v[96:99] offset:32768
	v_cvt_pk_bf16_f32 v96, v172, v173
	v_cvt_pk_bf16_f32 v97, v192, v193
	v_cvt_pk_bf16_f32 v98, v196, v197
	v_cvt_pk_bf16_f32 v99, v200, v201
	ds_write_b128 v185, v[96:99] offset:50176
	v_cvt_pk_bf16_f32 v96, v108, v109
	v_cvt_pk_bf16_f32 v97, v110, v111
	v_cvt_pk_bf16_f32 v98, v112, v113
	v_cvt_pk_bf16_f32 v99, v114, v115
	v_add3_u32 v0, s94, v0, v165
	ds_write_b128 v0, v[96:99]
	v_lshlrev_b32_e32 v96, 9, v164
	v_add_u32_e32 v191, v186, v96
	ds_read_b128 v[96:99], v191
	v_or_b32_e32 v108, v127, v131
	v_mul_lo_u32 v189, v108, s55
	ds_read_b128 v[108:111], v191 offset:16
	v_lshlrev_b32_e32 v114, 16, v60
	v_and_b32_e32 v115, 0xffff0000, v60
	s_waitcnt lgkmcnt(1)
	v_sub_f32_e32 v60, v97, v105
	v_mul_f32_e32 v60, 0x3fb8aa3b, v60
	v_exp_f32_e32 v113, v60
	v_sub_f32_e32 v60, v105, v97
	v_mul_f32_e32 v60, 0x3fb8aa3b, v60
	v_exp_f32_e32 v105, v60
	v_mul_f32_e32 v60, 0x3fb8aa3b, v97
	v_exp_f32_e32 v97, v60
	v_pk_mul_f32 v[164:165], v[114:115], s[56:57] op_sel_hi:[1,0]
	v_sub_f32_e32 v60, v98, v106
	v_lshlrev_b32_e32 v114, 16, v61
	v_and_b32_e32 v115, 0xffff0000, v61
	v_sub_f32_e32 v61, v99, v107
	v_mul_f32_e32 v60, 0x3fb8aa3b, v60
	v_mul_f32_e32 v61, 0x3fb8aa3b, v61
	v_exp_f32_e32 v60, v60
	v_exp_f32_e32 v61, v61
	v_pk_mul_f32 v[170:171], v[114:115], s[56:57] op_sel_hi:[1,0]
	v_lshlrev_b32_e32 v168, 16, v62
	v_and_b32_e32 v169, 0xffff0000, v62
	v_pk_mul_f32 v[114:115], v[170:171], v[60:61]
	s_waitcnt lgkmcnt(0)
	v_sub_f32_e32 v61, v100, v108
	v_mul_f32_e32 v61, 0x3fb8aa3b, v61
	v_sub_f32_e32 v60, v108, v100
	v_exp_f32_e32 v100, v61
	v_mul_f32_e32 v61, 0x3fb8aa3b, v108
	v_exp_f32_e32 v108, v61
	v_sub_f32_e32 v61, v109, v101
	v_mul_f32_e32 v60, 0x3fb8aa3b, v60
	v_mul_f32_e32 v61, 0x3fb8aa3b, v61
	v_exp_f32_e32 v60, v60
	v_exp_f32_e32 v61, v61
	v_sub_f32_e32 v62, v101, v109
	v_pk_mul_f32 v[168:169], v[168:169], s[56:57] op_sel_hi:[1,0]
	v_mul_f32_e32 v62, 0x3fb8aa3b, v62
	v_pk_mul_f32 v[192:193], v[168:169], v[60:61]
	v_sub_f32_e32 v61, v102, v110
	v_exp_f32_e32 v101, v62
	v_mul_f32_e32 v62, 0x3fb8aa3b, v109
	v_mul_f32_e32 v61, 0x3fb8aa3b, v61
	v_exp_f32_e32 v109, v62
	v_exp_f32_e32 v62, v61
	v_mul_f32_e32 v61, 0x3fb8aa3b, v110
	v_sub_f32_e32 v112, v96, v104
	v_sub_f32_e32 v60, v110, v102
	v_exp_f32_e32 v102, v61
	v_sub_f32_e32 v61, v111, v103
	v_mul_f32_e32 v112, 0x3fb8aa3b, v112
	v_sub_f32_e32 v104, v104, v96
	v_sub_f32_e32 v106, v106, v98
	v_sub_f32_e32 v107, v107, v99
	v_mul_f32_e32 v60, 0x3fb8aa3b, v60
	v_lshlrev_b32_e32 v172, 16, v63
	v_and_b32_e32 v173, 0xffff0000, v63
	v_mul_f32_e32 v61, 0x3fb8aa3b, v61
	v_sub_f32_e32 v63, v103, v111
	v_exp_f32_e32 v112, v112
	v_mul_f32_e32 v104, 0x3fb8aa3b, v104
	v_mul_f32_e32 v106, 0x3fb8aa3b, v106
	v_mul_f32_e32 v107, 0x3fb8aa3b, v107
	v_exp_f32_e32 v60, v60
	v_exp_f32_e32 v61, v61
	v_mul_f32_e32 v63, 0x3fb8aa3b, v63
	v_exp_f32_e32 v104, v104
	v_mul_f32_e32 v96, 0x3fb8aa3b, v96
	v_exp_f32_e32 v106, v106
	v_mul_f32_e32 v98, 0x3fb8aa3b, v98
	v_exp_f32_e32 v107, v107
	v_mul_f32_e32 v99, 0x3fb8aa3b, v99
	v_exp_f32_e32 v63, v63
	v_mul_f32_e32 v103, 0x3fb8aa3b, v111
	v_exp_f32_e32 v96, v96
	v_exp_f32_e32 v98, v98
	v_exp_f32_e32 v99, v99
	v_exp_f32_e32 v103, v103
	v_pk_mul_f32 v[172:173], v[172:173], s[56:57] op_sel_hi:[1,0]
	v_pk_mul_f32 v[112:113], v[164:165], v[112:113]
	v_pk_mul_f32 v[110:111], v[172:173], v[60:61]
	v_pk_mul_f32 v[104:105], v[104:105], v[148:149]
	v_pk_mul_f32 v[106:107], v[106:107], v[146:147]
	v_pk_mul_f32 v[100:101], v[100:101], v[144:145]
	v_pk_mul_f32 v[194:195], v[62:63], v[142:143]
	v_cvt_pk_bf16_f32 v60, v112, v113
	v_cvt_pk_bf16_f32 v61, v114, v115
	v_cvt_pk_bf16_f32 v62, v192, v193
	v_cvt_pk_bf16_f32 v63, v110, v111
	v_add_u32_e32 v123, 0, v116
	v_pk_mul_f32 v[96:97], v[164:165], v[96:97]
	v_pk_mul_f32 v[98:99], v[170:171], v[98:99]
	v_pk_mul_f32 v[108:109], v[168:169], v[108:109]
	v_pk_mul_f32 v[102:103], v[172:173], v[102:103]
	ds_write_b128 v185, v[60:63] offset:41472
	v_cvt_pk_bf16_f32 v60, v104, v105
	v_cvt_pk_bf16_f32 v61, v106, v107
	v_cvt_pk_bf16_f32 v62, v100, v101
	v_cvt_pk_bf16_f32 v63, v194, v195
	ds_write_b128 v185, v[60:63] offset:58880
	v_cvt_pk_bf16_f32 v60, v96, v97
	v_cvt_pk_bf16_f32 v61, v98, v99
	v_cvt_pk_bf16_f32 v62, v108, v109
	v_cvt_pk_bf16_f32 v63, v102, v103
	v_add_u32_e32 v192, v123, v189
	ds_write_b128 v0, v[60:63] offset:8704
	s_waitcnt lgkmcnt(0)
	s_barrier
	ds_read_b128 v[60:63], v192 offset:50176
	v_and_or_b32 v189, v122, 48, v131
	v_mad_u32_u24 v96, v189, s55, 0
	v_add_u32_e32 v193, v96, v116
	ds_read_b128 v[96:99], v193 offset:32768
	ds_read_b128 v[100:103], v193 offset:32832
	ds_read_b128 v[104:107], v192 offset:50240
	ds_read_b128 v[108:111], v192 offset:54528
	ds_read_b128 v[112:115], v192 offset:54592
	s_waitcnt lgkmcnt(4)
	v_mfma_f32_16x16x32_bf16 v[60:63], v[60:63], v[96:99], 0
	v_lshlrev_b32_e32 v117, 2, v117
	v_or_b32_e32 v194, v117, v127
	v_cmp_ge_i32_e32 vcc, v189, v194
	s_waitcnt lgkmcnt(1)
	v_mfma_f32_16x16x32_bf16 v[96:99], v[108:111], v[96:99], 0
	ds_read_b128 v[108:111], v192 offset:50304
	v_cmp_gt_i32_e64 s[18:19], v189, v194
	v_mul_u32_u24_e32 v117, 0x90, v189
	v_mfma_f32_16x16x32_bf16 v[60:63], v[104:107], v[100:103], v[60:63]
	ds_read_b128 v[104:107], v193 offset:32896
	ds_read_b128 v[196:199], v192 offset:54656
	v_or_b32_e32 v200, 17, v194
	v_or_b32_e32 v202, 18, v194
	s_waitcnt lgkmcnt(3)
	v_mfma_f32_16x16x32_bf16 v[96:99], v[112:115], v[100:103], v[96:99]
	ds_read_b128 v[100:103], v193 offset:32960
	ds_read_b128 v[112:115], v192 offset:50368
	v_bfe_u32 v122, v187, 2, 2
	v_or_b32_e32 v203, 19, v194
	s_waitcnt lgkmcnt(3)
	v_mfma_f32_16x16x32_bf16 v[60:63], v[108:111], v[104:107], v[60:63]
	ds_read_b128 v[108:111], v192 offset:54720
	v_add_u32_e32 v190, s95, v116
	v_add_u32_e32 v201, s94, v116
	s_waitcnt lgkmcnt(3)
	v_mfma_f32_16x16x32_bf16 v[96:99], v[196:199], v[104:107], v[96:99]
	v_or_b32_e32 v197, 2, v194
	v_or_b32_e32 v198, 3, v194
	v_or_b32_e32 v199, 16, v194
	s_waitcnt lgkmcnt(1)
	v_mfma_f32_16x16x32_bf16 v[60:63], v[112:115], v[100:103], v[60:63]
	v_lshrrev_b32_e32 v104, 1, v187
	v_lshlrev_b32_e32 v105, 4, v133
	v_and_or_b32 v196, v104, 24, v122
	s_waitcnt lgkmcnt(0)
	v_mfma_f32_16x16x32_bf16 v[96:99], v[108:111], v[100:103], v[96:99]
	v_lshlrev_b32_e32 v104, 1, v132
	s_nop 1
	v_cndmask_b32_e32 v60, 0, v60, vcc
	v_cmp_ge_i32_e32 vcc, v189, v197
	v_cndmask_b32_e64 v61, 0, v61, s[18:19]
	v_cvt_pk_bf16_f32 v60, v60, v61
	v_cndmask_b32_e32 v62, 0, v62, vcc
	v_cmp_ge_i32_e32 vcc, v189, v198
	v_and_b32_e32 v105, 48, v105
	v_add3_u32 v187, s73, v104, v105
	v_cndmask_b32_e32 v63, 0, v63, vcc
	v_cvt_pk_bf16_f32 v61, v62, v63
	v_lshlrev_b32_e32 v62, 1, v194
	v_cmp_ge_i32_e32 vcc, v189, v199
	v_add3_u32 v195, s95, v117, v62
	v_mad_u32_u24 v117, v196, s35, v187
	v_cndmask_b32_e32 v62, 0, v96, vcc
	v_cmp_ge_i32_e32 vcc, v189, v200
	v_mad_u32_u24 v122, v131, s57, v190
	v_mad_u32_u24 v116, v131, s55, v201
	v_cndmask_b32_e32 v63, 0, v97, vcc
	v_cmp_ge_i32_e32 vcc, v189, v202
	v_cvt_pk_bf16_f32 v62, v62, v63
	s_nop 0
	v_cndmask_b32_e32 v96, 0, v98, vcc
	v_cmp_ge_i32_e32 vcc, v189, v203
	s_nop 1
	v_cndmask_b32_e32 v97, 0, v99, vcc
	v_cvt_pk_bf16_f32 v63, v96, v97
	ds_write2_b64 v195, v[60:61], v[62:63] offset1:4
	s_waitcnt lgkmcnt(0)
	s_barrier
	ds_read_b64_tr_b16 v[62:63], v117 offset:2176
	ds_read_b64_tr_b16 v[60:61], v117
	ds_read_b64_tr_b16 v[98:99], v117 offset:2184
	ds_read_b64_tr_b16 v[96:97], v117 offset:8
	ds_read_b128 v[100:103], v122
	ds_read_b128 v[104:107], v122 offset:64
	ds_read_b128 v[112:115], v122 offset:2304
	ds_read_b128 v[206:209], v122 offset:2368
	ds_read_b128 v[214:217], v122 offset:4608
	ds_read_b128 v[218:221], v122 offset:4672
	ds_read_b128 v[226:229], v122 offset:6912
	ds_read_b128 v[230:233], v122 offset:6976
	s_waitcnt lgkmcnt(7)
	v_mfma_f32_16x16x32_bf16 v[108:111], v[60:63], v[100:103], 0
	ds_read_b64_tr_b16 v[234:235], v117 offset:17408
	ds_read_b64_tr_b16 v[236:237], v117 offset:19584
	v_mfma_f32_16x16x32_bf16 v[100:103], v[96:99], v[100:103], 0
	s_waitcnt lgkmcnt(7)
	v_mfma_f32_16x16x32_bf16 v[210:213], v[60:63], v[112:115], 0
	v_mfma_f32_16x16x32_bf16 v[112:115], v[96:99], v[112:115], 0
	s_waitcnt lgkmcnt(5)
	v_mfma_f32_16x16x32_bf16 v[222:225], v[60:63], v[214:217], 0
	v_mfma_f32_16x16x32_bf16 v[214:217], v[96:99], v[214:217], 0
	s_waitcnt lgkmcnt(3)
	v_mfma_f32_16x16x32_bf16 v[60:63], v[60:63], v[226:229], 0
	v_mfma_f32_16x16x32_bf16 v[96:99], v[96:99], v[226:229], 0
	ds_read_b64_tr_b16 v[228:229], v117 offset:19592
	ds_read_b64_tr_b16 v[226:227], v117 offset:17416
	s_waitcnt lgkmcnt(2)
	v_mfma_f32_16x16x32_bf16 v[108:111], v[234:237], v[104:107], v[108:111]
	s_waitcnt lgkmcnt(0)
	v_mfma_f32_16x16x32_bf16 v[100:103], v[226:229], v[104:107], v[100:103]
	v_mfma_f32_16x16x32_bf16 v[104:107], v[234:237], v[206:209], v[210:213]
	v_mfma_f32_16x16x32_bf16 v[112:115], v[226:229], v[206:209], v[112:115]
	v_mfma_f32_16x16x32_bf16 v[206:209], v[234:237], v[218:221], v[222:225]
	v_mfma_f32_16x16x32_bf16 v[210:213], v[226:229], v[218:221], v[214:217]
	s_nop 2
	ds_read_b128 v[214:217], v116
	ds_read_b128 v[218:221], v116 offset:64
	s_waitcnt vmcnt(7) lgkmcnt(1)
	v_mfma_f32_16x16x32_bf16 v[108:111], v[84:87], v[214:217], v[108:111]
	s_waitcnt vmcnt(3)
	v_mfma_f32_16x16x32_bf16 v[100:103], v[92:95], v[214:217], v[100:103]
	ds_read_b128 v[214:217], v116 offset:4352
	ds_read_b128 v[222:225], v116 offset:4416
	v_mfma_f32_16x16x32_bf16 v[96:99], v[226:229], v[230:233], v[96:99]
	s_waitcnt lgkmcnt(1)
	v_mfma_f32_16x16x32_bf16 v[104:107], v[84:87], v[214:217], v[104:107]
	v_mfma_f32_16x16x32_bf16 v[112:115], v[92:95], v[214:217], v[112:115]
	ds_read_b128 v[214:217], v116 offset:8704
	ds_read_b128 v[226:229], v116 offset:8768
	v_mfma_f32_16x16x32_bf16 v[60:63], v[234:237], v[230:233], v[60:63]
	s_waitcnt lgkmcnt(1)
	v_mfma_f32_16x16x32_bf16 v[206:209], v[84:87], v[214:217], v[206:209]
	v_mfma_f32_16x16x32_bf16 v[210:213], v[92:95], v[214:217], v[210:213]
	ds_read_b128 v[214:217], v116 offset:13056
	ds_read_b128 v[230:233], v116 offset:13120
	s_waitcnt lgkmcnt(1)
	v_mfma_f32_16x16x32_bf16 v[60:63], v[84:87], v[214:217], v[60:63]
	v_mfma_f32_16x16x32_bf16 v[84:87], v[92:95], v[214:217], v[96:99]
	v_mfma_f32_16x16x32_bf16 v[92:95], v[80:83], v[218:221], v[108:111]
	s_waitcnt vmcnt(2)
	v_mfma_f32_16x16x32_bf16 v[96:99], v[88:91], v[218:221], v[100:103]
	v_mfma_f32_16x16x32_bf16 v[100:103], v[80:83], v[222:225], v[104:107]
	v_mfma_f32_16x16x32_bf16 v[108:111], v[80:83], v[226:229], v[206:209]
	s_waitcnt lgkmcnt(0)
	v_mfma_f32_16x16x32_bf16 v[60:63], v[80:83], v[230:233], v[60:63]
	v_mfma_f32_16x16x32_bf16 v[80:83], v[88:91], v[230:233], v[84:87]
	v_mfma_f32_16x16x32_bf16 v[104:107], v[88:91], v[222:225], v[112:115]
	v_mfma_f32_16x16x32_bf16 v[112:115], v[88:91], v[226:229], v[210:213]
	s_nop 0
	ds_read_b128 v[84:87], v116 offset:128
	ds_read_b128 v[206:209], v116 offset:192
	s_waitcnt lgkmcnt(1)
	v_mfma_f32_16x16x32_bf16 v[88:91], v[68:71], v[84:87], v[92:95]
	s_waitcnt vmcnt(1)
	v_mfma_f32_16x16x32_bf16 v[84:87], v[76:79], v[84:87], v[96:99]
	s_nop 0
	ds_read_b128 v[92:95], v116 offset:4480
	s_nop 0
	ds_read_b128 v[96:99], v116 offset:4544
	s_waitcnt lgkmcnt(1)
	v_mfma_f32_16x16x32_bf16 v[100:103], v[68:71], v[92:95], v[100:103]
	v_mfma_f32_16x16x32_bf16 v[104:107], v[76:79], v[92:95], v[104:107]
	ds_read_b128 v[92:95], v116 offset:8832
	ds_read_b128 v[210:213], v116 offset:8896
	s_waitcnt lgkmcnt(1)
	v_mfma_f32_16x16x32_bf16 v[108:111], v[68:71], v[92:95], v[108:111]
	v_mfma_f32_16x16x32_bf16 v[112:115], v[76:79], v[92:95], v[112:115]
	ds_read_b128 v[92:95], v116 offset:13184
	ds_read_b128 v[214:217], v116 offset:13248
	s_waitcnt lgkmcnt(1)
	v_mfma_f32_16x16x32_bf16 v[60:63], v[68:71], v[92:95], v[60:63]
	v_mfma_f32_16x16x32_bf16 v[218:221], v[76:79], v[92:95], v[80:83]
	v_mfma_f32_16x16x32_bf16 v[88:91], v[64:67], v[206:209], v[88:91]
	s_waitcnt vmcnt(0)
	v_mfma_f32_16x16x32_bf16 v[92:95], v[72:75], v[206:209], v[84:87]
	v_mfma_f32_16x16x32_bf16 v[80:83], v[64:67], v[96:99], v[100:103]
	v_mfma_f32_16x16x32_bf16 v[84:87], v[72:75], v[96:99], v[104:107]
	v_mfma_f32_16x16x32_bf16 v[68:71], v[64:67], v[210:213], v[108:111]
	v_mfma_f32_16x16x32_bf16 v[76:79], v[72:75], v[210:213], v[112:115]
	s_waitcnt lgkmcnt(0)
	v_mfma_f32_16x16x32_bf16 v[64:67], v[64:67], v[214:217], v[60:63]
	v_mfma_f32_16x16x32_bf16 v[60:63], v[72:75], v[214:217], v[218:221]
	s_or_b32 s66, s62, 1
	s_cmp_lt_i32 s66, 45
	s_mov_b64 s[70:71], -1
	s_cbranch_scc1 .LBB0_1659
	s_cmp_lt_u32 s66, 61
	s_cbranch_scc1 .LBB0_1656
	s_sub_i32 s38, s62, 60
	s_mov_b64 s[70:71], 0
	s_mov_b64 s[64:65], s[30:31]
	s_mov_b64 s[68:69], s[38:39]

.LBB0_1665:
	s_or_b64 exec, exec, s[12:13]
	v_sub_u32_e32 v53, 0, v181
	v_sub_u32_e32 v54, 0, v206
	v_add_f32_e32 v52, v52, v40
	v_add_u32_e32 v53, v180, v53
	v_sub_u32_e32 v55, 0, v207
	ds_write_b32 v53, v52 offset:32256
	v_add_f32_e32 v51, v51, v40
	v_add_u32_e32 v52, v180, v54
	v_sub_u32_e32 v56, 0, v208
	ds_write_b32 v52, v51 offset:32256
	v_add_f32_e32 v50, v50, v40
	v_add_u32_e32 v51, v180, v55
	v_sub_u32_e32 v57, 0, v209
	ds_write_b32 v51, v50 offset:32256
	v_add_f32_e32 v49, v49, v40
	v_add_u32_e32 v50, v180, v56
	v_sub_u32_e32 v58, 0, v210
	ds_write_b32 v50, v49 offset:32256
	v_add_f32_e32 v48, v48, v40
	v_add_u32_e32 v49, v180, v57
	v_sub_u32_e32 v59, 0, v211
	ds_write_b32 v49, v48 offset:32256
	v_add_f32_e32 v47, v47, v40
	v_add_u32_e32 v48, v180, v58
	v_sub_u32_e32 v127, 0, v212
	ds_write_b32 v48, v47 offset:32256
	v_add_f32_e32 v46, v46, v40
	v_add_u32_e32 v47, v180, v59
	v_sub_u32_e32 v181, 0, v213
	ds_write_b32 v47, v46 offset:32256
	v_add_f32_e32 v45, v45, v40
	v_add_u32_e32 v46, v180, v127
	v_sub_u32_e32 v182, 0, v214
	ds_write_b32 v46, v45 offset:32256
	v_add_f32_e32 v44, v44, v40
	v_add_u32_e32 v45, v180, v181
	v_sub_u32_e32 v183, 0, v215
	ds_write_b32 v45, v44 offset:32256
	v_add_f32_e32 v43, v43, v40
	v_add_u32_e32 v44, v180, v182
	v_sub_u32_e32 v184, 0, v216
	ds_write_b32 v44, v43 offset:32256
	v_add_f32_e32 v42, v42, v40
	v_add_u32_e32 v43, v180, v183
	v_sub_u32_e32 v206, 0, v217
	ds_write_b32 v43, v42 offset:32256
	v_add_f32_e32 v41, v41, v40
	v_add_u32_e32 v42, v180, v184
	v_sub_u32_e32 v207, 0, v218
	ds_write_b32 v42, v41 offset:32256
	v_add_f32_e32 v39, v39, v40
	v_add_u32_e32 v41, v180, v206
	v_sub_u32_e32 v208, 0, v219
	ds_write_b32 v41, v39 offset:32256
	v_add_f32_e32 v38, v38, v40
	v_add_u32_e32 v39, v180, v207
	v_sub_u32_e32 v209, 0, v220
	ds_write_b32 v39, v38 offset:32256
	v_add_f32_e32 v37, v37, v40
	v_add_u32_e32 v38, v180, v208
	ds_write_b32 v38, v37 offset:32256
	v_add_f32_e32 v36, v36, v40
	v_add_u32_e32 v37, v180, v209
	ds_write_b32 v37, v36 offset:32256
	s_waitcnt lgkmcnt(0)
	s_barrier
	ds_read_b128 v[36:39], v188
	ds_read_b128 v[40:43], v186 offset:15872
	ds_read_b128 v[44:47], v186 offset:15888
	ds_read_b128 v[48:51], v188 offset:16
	s_waitcnt lgkmcnt(2)
	v_sub_f32_e32 v53, v40, v36
	v_mul_f32_e32 v53, 0x3fb8aa3b, v53
	v_sub_f32_e32 v55, v41, v37
	v_sub_f32_e32 v52, v36, v40
	v_exp_f32_e32 v54, v53
	v_sub_f32_e32 v53, v37, v41
	v_mul_f32_e32 v55, 0x3fb8aa3b, v55
	v_mul_f32_e32 v36, 0x3fb8aa3b, v36
	v_mul_f32_e32 v37, 0x3fb8aa3b, v37
	v_sub_f32_e32 v57, v42, v38
	v_exp_f32_e32 v55, v55
	v_exp_f32_e32 v36, v36
	v_exp_f32_e32 v37, v37
	v_mul_f32_e32 v57, 0x3fb8aa3b, v57
	v_sub_f32_e32 v59, v43, v39
	v_sub_f32_e32 v56, v38, v42
	v_exp_f32_e32 v58, v57
	v_mul_f32_e32 v38, 0x3fb8aa3b, v38
	v_sub_f32_e32 v57, v39, v43
	v_mul_f32_e32 v59, 0x3fb8aa3b, v59
	v_mul_f32_e32 v39, 0x3fb8aa3b, v39
	v_exp_f32_e32 v38, v38
	v_exp_f32_e32 v59, v59
	v_exp_f32_e32 v39, v39
	v_pk_mul_f32 v[54:55], v[54:55], v[156:157]
	v_pk_mul_f32 v[156:157], v[158:159], v[36:37]
	s_waitcnt lgkmcnt(0)
	v_sub_f32_e32 v37, v44, v48
	v_mul_f32_e32 v37, 0x3fb8aa3b, v37
	v_pk_mul_f32 v[58:59], v[58:59], v[154:155]
	v_pk_mul_f32 v[154:155], v[162:163], v[38:39]
	v_sub_f32_e32 v36, v48, v44
	v_exp_f32_e32 v38, v37
	v_sub_f32_e32 v37, v49, v45
	v_mul_f32_e32 v52, 0x3fb8aa3b, v52
	v_mul_f32_e32 v53, 0x3fb8aa3b, v53
	v_mul_f32_e32 v36, 0x3fb8aa3b, v36
	v_mul_f32_e32 v37, 0x3fb8aa3b, v37
	v_exp_f32_e32 v52, v52
	v_exp_f32_e32 v53, v53
	v_exp_f32_e32 v36, v36
	v_exp_f32_e32 v37, v37
	v_sub_f32_e32 v39, v45, v49
	v_mul_f32_e32 v39, 0x3fb8aa3b, v39
	v_exp_f32_e32 v39, v39
	v_pk_mul_f32 v[52:53], v[158:159], v[52:53]
	v_pk_mul_f32 v[158:159], v[160:161], v[36:37]
	v_sub_f32_e32 v37, v46, v50
	v_mul_f32_e32 v37, 0x3fb8aa3b, v37
	v_pk_mul_f32 v[152:153], v[38:39], v[152:153]
	v_mul_f32_e32 v36, 0x3fb8aa3b, v49
	v_exp_f32_e32 v38, v37
	v_mul_f32_e32 v37, 0x3fb8aa3b, v50
	v_exp_f32_e32 v49, v36
	v_sub_f32_e32 v36, v50, v46
	v_exp_f32_e32 v50, v37
	v_sub_f32_e32 v37, v51, v47
	v_mul_f32_e32 v56, 0x3fb8aa3b, v56
	v_mul_f32_e32 v57, 0x3fb8aa3b, v57
	v_mul_f32_e32 v48, 0x3fb8aa3b, v48
	v_mul_f32_e32 v36, 0x3fb8aa3b, v36
	v_mul_f32_e32 v37, 0x3fb8aa3b, v37
	v_sub_f32_e32 v39, v47, v51
	v_exp_f32_e32 v56, v56
	v_exp_f32_e32 v57, v57
	v_exp_f32_e32 v48, v48
	v_exp_f32_e32 v36, v36
	v_exp_f32_e32 v37, v37
	v_mul_f32_e32 v39, 0x3fb8aa3b, v39
	v_exp_f32_e32 v39, v39
	v_mul_f32_e32 v51, 0x3fb8aa3b, v51
	v_exp_f32_e32 v51, v51
	v_pk_mul_f32 v[56:57], v[162:163], v[56:57]
	v_pk_mul_f32 v[48:49], v[160:161], v[48:49]
	v_pk_mul_f32 v[160:161], v[166:167], v[36:37]
	v_pk_mul_f32 v[150:151], v[38:39], v[150:151]
	v_cvt_pk_bf16_f32 v36, v52, v53
	v_cvt_pk_bf16_f32 v37, v56, v57
	v_cvt_pk_bf16_f32 v38, v158, v159
	v_cvt_pk_bf16_f32 v39, v160, v161
	v_pk_mul_f32 v[50:51], v[166:167], v[50:51]
	ds_write_b128 v185, v[36:39] offset:32768
	v_cvt_pk_bf16_f32 v36, v54, v55
	v_cvt_pk_bf16_f32 v37, v58, v59
	v_cvt_pk_bf16_f32 v38, v152, v153
	v_cvt_pk_bf16_f32 v39, v150, v151
	ds_write_b128 v185, v[36:39] offset:50176
	v_cvt_pk_bf16_f32 v36, v156, v157
	v_cvt_pk_bf16_f32 v37, v154, v155
	v_cvt_pk_bf16_f32 v38, v48, v49
	v_cvt_pk_bf16_f32 v39, v50, v51
	ds_write_b128 v0, v[36:39]
	ds_read_b128 v[36:39], v191
	ds_read_b128 v[48:51], v191 offset:16
	s_waitcnt lgkmcnt(1)
	v_sub_f32_e32 v52, v36, v40
	v_sub_f32_e32 v40, v40, v36
	v_sub_f32_e32 v53, v37, v41
	v_sub_f32_e32 v41, v41, v37
	v_mul_f32_e32 v36, 0x3fb8aa3b, v36
	v_mul_f32_e32 v37, 0x3fb8aa3b, v37
	v_exp_f32_e32 v36, v36
	v_exp_f32_e32 v37, v37
	v_sub_f32_e32 v54, v38, v42
	v_sub_f32_e32 v42, v42, v38
	v_mul_f32_e32 v38, 0x3fb8aa3b, v38
	v_sub_f32_e32 v55, v39, v43
	v_sub_f32_e32 v43, v43, v39
	v_mul_f32_e32 v39, 0x3fb8aa3b, v39
	v_exp_f32_e32 v38, v38
	v_exp_f32_e32 v39, v39
	v_pk_mul_f32 v[56:57], v[164:165], v[36:37]
	s_waitcnt lgkmcnt(0)
	v_sub_f32_e32 v37, v44, v48
	v_mul_f32_e32 v37, 0x3fb8aa3b, v37
	v_pk_mul_f32 v[58:59], v[170:171], v[38:39]
	v_sub_f32_e32 v36, v48, v44
	v_exp_f32_e32 v38, v37
	v_sub_f32_e32 v37, v49, v45
	v_mul_f32_e32 v42, 0x3fb8aa3b, v42
	v_mul_f32_e32 v43, 0x3fb8aa3b, v43
	v_mul_f32_e32 v36, 0x3fb8aa3b, v36
	v_mul_f32_e32 v37, 0x3fb8aa3b, v37
	v_exp_f32_e32 v42, v42
	v_exp_f32_e32 v43, v43
	v_exp_f32_e32 v36, v36
	v_exp_f32_e32 v37, v37
	v_sub_f32_e32 v39, v45, v49
	v_mul_f32_e32 v39, 0x3fb8aa3b, v39
	v_exp_f32_e32 v39, v39
	v_pk_mul_f32 v[42:43], v[42:43], v[146:147]
	v_pk_mul_f32 v[146:147], v[168:169], v[36:37]
	v_sub_f32_e32 v37, v46, v50
	v_mul_f32_e32 v37, 0x3fb8aa3b, v37
	v_pk_mul_f32 v[144:145], v[38:39], v[144:145]
	v_mul_f32_e32 v36, 0x3fb8aa3b, v49
	v_exp_f32_e32 v38, v37
	v_mul_f32_e32 v37, 0x3fb8aa3b, v50
	v_exp_f32_e32 v45, v36
	v_sub_f32_e32 v36, v50, v46
	v_exp_f32_e32 v46, v37
	v_sub_f32_e32 v37, v51, v47
	v_mul_f32_e32 v52, 0x3fb8aa3b, v52
	v_mul_f32_e32 v53, 0x3fb8aa3b, v53
	v_mul_f32_e32 v54, 0x3fb8aa3b, v54
	v_mul_f32_e32 v55, 0x3fb8aa3b, v55
	v_mul_f32_e32 v36, 0x3fb8aa3b, v36
	v_mul_f32_e32 v37, 0x3fb8aa3b, v37
	v_sub_f32_e32 v39, v47, v51
	v_exp_f32_e32 v52, v52
	v_mul_f32_e32 v40, 0x3fb8aa3b, v40
	v_exp_f32_e32 v53, v53
	v_mul_f32_e32 v41, 0x3fb8aa3b, v41
	v_exp_f32_e32 v54, v54
	v_exp_f32_e32 v55, v55
	v_exp_f32_e32 v36, v36
	v_exp_f32_e32 v37, v37
	v_mul_f32_e32 v39, 0x3fb8aa3b, v39
	v_exp_f32_e32 v40, v40
	v_exp_f32_e32 v41, v41
	v_mul_f32_e32 v44, 0x3fb8aa3b, v48
	v_exp_f32_e32 v39, v39
	v_mul_f32_e32 v47, 0x3fb8aa3b, v51
	v_exp_f32_e32 v44, v44
	v_exp_f32_e32 v47, v47
	v_pk_mul_f32 v[52:53], v[164:165], v[52:53]
	v_pk_mul_f32 v[54:55], v[170:171], v[54:55]
	v_pk_mul_f32 v[48:49], v[172:173], v[36:37]
	v_pk_mul_f32 v[40:41], v[40:41], v[148:149]
	v_pk_mul_f32 v[50:51], v[38:39], v[142:143]
	v_cvt_pk_bf16_f32 v36, v52, v53
	v_cvt_pk_bf16_f32 v37, v54, v55
	v_cvt_pk_bf16_f32 v38, v146, v147
	v_cvt_pk_bf16_f32 v39, v48, v49
	v_pk_mul_f32 v[44:45], v[168:169], v[44:45]
	v_pk_mul_f32 v[46:47], v[172:173], v[46:47]
	ds_write_b128 v185, v[36:39] offset:41472
	v_cvt_pk_bf16_f32 v36, v40, v41
	v_cvt_pk_bf16_f32 v37, v42, v43
	v_cvt_pk_bf16_f32 v38, v144, v145
	v_cvt_pk_bf16_f32 v39, v50, v51
	ds_write_b128 v185, v[36:39] offset:58880
	v_cvt_pk_bf16_f32 v36, v56, v57
	v_cvt_pk_bf16_f32 v37, v58, v59
	v_cvt_pk_bf16_f32 v38, v44, v45
	v_cvt_pk_bf16_f32 v39, v46, v47
	ds_write_b128 v0, v[36:39] offset:8704
	s_waitcnt lgkmcnt(0)
	s_barrier
	ds_read_b128 v[36:39], v192 offset:50176
	ds_read_b128 v[40:43], v193 offset:32768
	ds_read_b128 v[44:47], v193 offset:32832
	ds_read_b128 v[48:51], v192 offset:50240
	s_waitcnt lgkmcnt(2)
	v_mfma_f32_16x16x32_bf16 v[36:39], v[36:39], v[40:43], 0
	ds_read_b128 v[52:55], v192 offset:54528
	ds_read_b128 v[56:59], v192 offset:54592
	v_mul_u32_u24_e32 v0, 0x90, v131
	v_add_u32_e32 v0, v190, v0
	s_waitcnt lgkmcnt(2)
	v_mfma_f32_16x16x32_bf16 v[36:39], v[48:51], v[44:47], v[36:39]
	ds_read_b128 v[48:51], v192 offset:50304
	s_waitcnt lgkmcnt(2)
	v_mfma_f32_16x16x32_bf16 v[40:43], v[52:55], v[40:43], 0
	s_waitcnt lgkmcnt(1)
	v_mfma_f32_16x16x32_bf16 v[40:43], v[56:59], v[44:47], v[40:43]
	ds_read_b128 v[44:47], v193 offset:32896
	ds_read_b128 v[52:55], v193 offset:32960
	ds_read_b128 v[56:59], v192 offset:50368
	s_waitcnt lgkmcnt(2)
	v_mfma_f32_16x16x32_bf16 v[36:39], v[48:51], v[44:47], v[36:39]
	ds_read_b128 v[48:51], v192 offset:54656
	ds_read_b128 v[142:145], v192 offset:54720
	s_waitcnt lgkmcnt(1)
	v_mfma_f32_16x16x32_bf16 v[40:43], v[48:51], v[44:47], v[40:43]
	v_or_b32_e32 v45, 1, v194
	v_cmp_le_i32_e32 vcc, v189, v45
	v_mul_u32_u24_e32 v44, 0x220, v196
	v_mfma_f32_16x16x32_bf16 v[36:39], v[56:59], v[52:55], v[36:39]
	v_add_u32_e32 v127, v187, v44
	s_waitcnt lgkmcnt(0)
	v_mfma_f32_16x16x32_bf16 v[40:43], v[142:145], v[52:55], v[40:43]
	s_nop 4
	v_cndmask_b32_e32 v37, 0, v37, vcc
	v_cmp_le_i32_e32 vcc, v189, v197
	v_cndmask_b32_e64 v36, v36, 0, s[18:19]
	v_cvt_pk_bf16_f32 v36, v36, v37
	v_cndmask_b32_e32 v38, 0, v38, vcc
	v_cmp_le_i32_e32 vcc, v189, v198
	s_nop 1
	v_cndmask_b32_e32 v39, 0, v39, vcc
	v_cmp_le_i32_e32 vcc, v189, v199
	v_cvt_pk_bf16_f32 v37, v38, v39
	s_nop 0
	v_cndmask_b32_e32 v38, 0, v40, vcc
	v_cmp_le_i32_e32 vcc, v189, v200
	s_nop 1
	v_cndmask_b32_e32 v39, 0, v41, vcc
	v_cmp_le_i32_e32 vcc, v189, v202
	v_cvt_pk_bf16_f32 v38, v38, v39
	s_nop 0
	v_cndmask_b32_e32 v40, 0, v42, vcc
	v_cmp_le_i32_e32 vcc, v189, v203
	s_nop 1
	v_cndmask_b32_e32 v41, 0, v43, vcc
	v_cvt_pk_bf16_f32 v39, v40, v41
	ds_write2_b64 v195, v[36:37], v[38:39] offset1:4
	s_waitcnt lgkmcnt(0)
	s_barrier
	ds_read_b64_tr_b16 v[38:39], v127 offset:2176
	ds_read_b64_tr_b16 v[36:37], v127
	ds_read_b64_tr_b16 v[42:43], v127 offset:2184
	ds_read_b64_tr_b16 v[40:41], v127 offset:8
	ds_read_b128 v[44:47], v0
	ds_read_b128 v[48:51], v0 offset:64
	s_waitcnt lgkmcnt(1)
	v_mfma_f32_16x16x32_bf16 v[52:55], v[36:39], v[44:47], v[88:91]
	ds_read_b128 v[56:59], v0 offset:2304
	s_nop 1
	ds_read_b128 v[88:91], v0 offset:2368
	v_mfma_f32_16x16x32_bf16 v[44:47], v[40:43], v[44:47], v[92:95]
	s_waitcnt lgkmcnt(1)
	v_mfma_f32_16x16x32_bf16 v[80:83], v[36:39], v[56:59], v[80:83]
	v_mfma_f32_16x16x32_bf16 v[56:59], v[40:43], v[56:59], v[84:87]
	s_nop 2
	ds_read_b128 v[84:87], v0 offset:4608
	ds_read_b128 v[92:95], v0 offset:4672
	s_waitcnt lgkmcnt(1)
	v_mfma_f32_16x16x32_bf16 v[68:71], v[36:39], v[84:87], v[68:71]
	v_mfma_f32_16x16x32_bf16 v[76:79], v[40:43], v[84:87], v[76:79]
	ds_read_b128 v[84:87], v0 offset:6912
	ds_read_b128 v[142:145], v0 offset:6976
	v_mul_u32_u24_e32 v0, 0x110, v131
	v_add_u32_e32 v0, v201, v0
	s_waitcnt lgkmcnt(1)
	v_mfma_f32_16x16x32_bf16 v[36:39], v[36:39], v[84:87], v[64:67]
	s_nop 2
	ds_read_b64_tr_b16 v[64:65], v127 offset:17408
	ds_read_b64_tr_b16 v[66:67], v127 offset:19584
	v_mfma_f32_16x16x32_bf16 v[40:43], v[40:43], v[84:87], v[60:63]
	s_nop 2
	ds_read_b64_tr_b16 v[62:63], v127 offset:19592
	ds_read_b64_tr_b16 v[60:61], v127 offset:17416
	s_waitcnt lgkmcnt(2)
	v_mfma_f32_16x16x32_bf16 v[52:55], v[64:67], v[48:51], v[52:55]
	s_waitcnt lgkmcnt(0)
	v_mfma_f32_16x16x32_bf16 v[44:47], v[60:63], v[48:51], v[44:47]
	v_mfma_f32_16x16x32_bf16 v[48:51], v[64:67], v[88:91], v[80:83]
	v_mfma_f32_16x16x32_bf16 v[56:59], v[60:63], v[88:91], v[56:59]
	v_mfma_f32_16x16x32_bf16 v[68:71], v[64:67], v[92:95], v[68:71]
	v_mfma_f32_16x16x32_bf16 v[76:79], v[60:63], v[92:95], v[76:79]
	v_mfma_f32_16x16x32_bf16 v[36:39], v[64:67], v[142:145], v[36:39]
	v_mfma_f32_16x16x32_bf16 v[40:43], v[60:63], v[142:145], v[40:43]
	ds_read_b128 v[60:63], v0
	ds_read_b128 v[64:67], v0 offset:64
	s_waitcnt vmcnt(7) lgkmcnt(1)
	v_mfma_f32_16x16x32_bf16 v[52:55], v[116:119], v[60:63], v[52:55]
	s_waitcnt vmcnt(3)
	v_mfma_f32_16x16x32_bf16 v[44:47], v[120:123], v[60:63], v[44:47]
	ds_read_b128 v[60:63], v0 offset:4352
	ds_read_b128 v[80:83], v0 offset:4416
	s_waitcnt lgkmcnt(1)
	v_mfma_f32_16x16x32_bf16 v[48:51], v[116:119], v[60:63], v[48:51]
	v_mfma_f32_16x16x32_bf16 v[56:59], v[120:123], v[60:63], v[56:59]
	ds_read_b128 v[60:63], v0 offset:8704
	ds_read_b128 v[84:87], v0 offset:8768
	s_waitcnt lgkmcnt(1)
	v_mfma_f32_16x16x32_bf16 v[68:71], v[116:119], v[60:63], v[68:71]
	v_mfma_f32_16x16x32_bf16 v[60:63], v[120:123], v[60:63], v[76:79]
	s_nop 2
	ds_read_b128 v[76:79], v0 offset:13056
	ds_read_b128 v[88:91], v0 offset:13120
	s_waitcnt lgkmcnt(1)
	v_mfma_f32_16x16x32_bf16 v[36:39], v[116:119], v[76:79], v[36:39]
	v_mfma_f32_16x16x32_bf16 v[40:43], v[120:123], v[76:79], v[40:43]
	v_mfma_f32_16x16x32_bf16 v[52:55], v[108:111], v[64:67], v[52:55]
	s_waitcnt vmcnt(2)
	v_mfma_f32_16x16x32_bf16 v[44:47], v[112:115], v[64:67], v[44:47]
	v_mfma_f32_16x16x32_bf16 v[48:51], v[108:111], v[80:83], v[48:51]
	v_mfma_f32_16x16x32_bf16 v[56:59], v[112:115], v[80:83], v[56:59]
	v_mfma_f32_16x16x32_bf16 v[64:67], v[108:111], v[84:87], v[68:71]
	v_mfma_f32_16x16x32_bf16 v[60:63], v[112:115], v[84:87], v[60:63]
	s_waitcnt lgkmcnt(0)
	v_mfma_f32_16x16x32_bf16 v[36:39], v[108:111], v[88:91], v[36:39]
	v_mfma_f32_16x16x32_bf16 v[40:43], v[112:115], v[88:91], v[40:43]
	ds_read_b128 v[68:71], v0 offset:128
	ds_read_b128 v[76:79], v0 offset:192
	s_waitcnt lgkmcnt(1)
	v_mfma_f32_16x16x32_bf16 v[52:55], v[100:103], v[68:71], v[52:55]
	s_waitcnt vmcnt(1)
	v_mfma_f32_16x16x32_bf16 v[44:47], v[104:107], v[68:71], v[44:47]
	ds_read_b128 v[68:71], v0 offset:4480
	ds_read_b128 v[84:87], v0 offset:4544
	s_waitcnt lgkmcnt(1)
	v_mfma_f32_16x16x32_bf16 v[48:51], v[100:103], v[68:71], v[48:51]
	v_mfma_f32_16x16x32_bf16 v[56:59], v[104:107], v[68:71], v[56:59]
	ds_read_b128 v[68:71], v0 offset:8832
	ds_read_b128 v[88:91], v0 offset:8896
	s_waitcnt lgkmcnt(1)
	v_mfma_f32_16x16x32_bf16 v[92:95], v[100:103], v[68:71], v[64:67]
	v_mfma_f32_16x16x32_bf16 v[68:71], v[104:107], v[68:71], v[60:63]
	s_nop 2
	ds_read_b128 v[60:63], v0 offset:13184
	ds_read_b128 v[108:111], v0 offset:13248
	s_waitcnt lgkmcnt(1)
	v_mfma_f32_16x16x32_bf16 v[36:39], v[100:103], v[60:63], v[36:39]
	v_mfma_f32_16x16x32_bf16 v[100:103], v[104:107], v[60:63], v[40:43]
	v_mfma_f32_16x16x32_bf16 v[80:83], v[72:75], v[76:79], v[52:55]
	s_waitcnt vmcnt(0)
	v_mfma_f32_16x16x32_bf16 v[76:79], v[96:99], v[76:79], v[44:47]
	v_mfma_f32_16x16x32_bf16 v[64:67], v[72:75], v[84:87], v[48:51]
	v_mfma_f32_16x16x32_bf16 v[60:63], v[96:99], v[84:87], v[56:59]
	v_mfma_f32_16x16x32_bf16 v[52:55], v[72:75], v[88:91], v[92:95]
	v_mfma_f32_16x16x32_bf16 v[48:51], v[96:99], v[88:91], v[68:71]
	s_waitcnt lgkmcnt(0)
	v_mfma_f32_16x16x32_bf16 v[40:43], v[72:75], v[108:111], v[36:39]
	v_mfma_f32_16x16x32_bf16 v[36:39], v[96:99], v[108:111], v[100:103]
	s_add_i32 s85, s81, s61
	s_cmpk_gt_i32 s85, 0x3ff
	s_cbranch_scc1 .Lgcb11_skip
	s_ashr_i32 s32, s85, 8
	s_lshl_b32 s32, s32, 12
	s_and_b32 s66, s85, 63
	s_lshl_b32 s66, s66, 6
	s_or_b32 s32, s32, s66
	s_bfe_u32 s66, s85, 0x20006
	s_lshl_b32 s66, s66, 7
	s_mov_b32 s100, s21
	s_mov_b32 s101, 0
	v_and_b32_e32 v230, 48, v204
	v_mov_b32_e32 v231, 0
	v_and_b32_e32 v232, 15, v204
	v_mov_b64_e32 v[234:235], s[46:47]
	v_or_b32_e32 v233, s32, v232
	v_mad_u64_u32 v[236:237], s[98:99], v233, s33, v[234:235]
	v_lshl_add_u64 v[236:237], v[236:237], 0, v[230:231]
	v_lshl_add_u64 v[236:237], v[236:237], 0, s[100:101]
	global_load_dwordx4 v[206:209], v[236:237], off offset:2048
	v_or_b32_e32 v233, 16, v232
	v_or_b32_e32 v233, s32, v233
	v_mad_u64_u32 v[236:237], s[98:99], v233, s33, v[234:235]
	v_lshl_add_u64 v[236:237], v[236:237], 0, v[230:231]
	v_lshl_add_u64 v[236:237], v[236:237], 0, s[100:101]
	global_load_dwordx4 v[210:213], v[236:237], off offset:2048
	v_or_b32_e32 v233, 32, v232
	v_or_b32_e32 v233, s32, v233
	v_mad_u64_u32 v[236:237], s[98:99], v233, s33, v[234:235]
	v_lshl_add_u64 v[236:237], v[236:237], 0, v[230:231]
	v_lshl_add_u64 v[236:237], v[236:237], 0, s[100:101]
	global_load_dwordx4 v[214:217], v[236:237], off offset:2048
	v_or_b32_e32 v233, 48, v232
	v_or_b32_e32 v233, s32, v233
	v_mad_u64_u32 v[236:237], s[98:99], v233, s33, v[234:235]
	v_lshl_add_u64 v[236:237], v[236:237], 0, v[230:231]
	v_lshl_add_u64 v[236:237], v[236:237], 0, s[100:101]
	global_load_dwordx4 v[218:221], v[236:237], off offset:2048
	v_lshrrev_b32_e32 v233, 6, v204
	v_lshlrev_b32_e32 v233, 4, v233
	v_or_b32_e32 v236, s66, v232
	v_add_u32_e32 v236, v236, v233
	v_lshlrev_b32_e32 v236, 5, v236
	v_and_b32_e32 v233, 16, v204
	v_add_u32_e32 v236, v236, v233
	v_mov_b32_e32 v237, 0
	v_lshl_add_u64 v[236:237], v[236:237], 0, s[50:51]
	v_mov_b32_e32 v222, 0
	v_mov_b32_e32 v223, 0
	v_mov_b32_e32 v224, 0
	v_mov_b32_e32 v225, 0
	v_and_b32_e32 v233, 63, v204
	v_cmp_gt_u32_e32 vcc, 32, v233
	s_and_saveexec_b64 s[70:71], vcc
	global_load_dwordx4 v[222:225], v[236:237], off
	s_or_b64 exec, exec, s[70:71]
	s_lshl_b32 s66, s66, 2
	s_add_u32 s86, s24, s66
	s_addc_u32 s87, s25, 0
	v_lshrrev_b32_e32 v233, 6, v204
	v_lshlrev_b32_e32 v236, 6, v233
	v_bfe_u32 v233, v204, 4, 2
	v_lshl_add_u32 v236, v233, 4, v236
	v_mov_b32_e32 v237, 0
	v_lshl_add_u64 v[236:237], v[236:237], 0, s[86:87]
	global_load_dwordx4 v[226:229], v[236:237], off
.Lgcb11_skip:
	v_or_b32_e32 v84, v179, v132
	v_ashrrev_i32_e32 v85, 31, v84
	s_lshl_b32 s38, s82, 9
	v_lshl_add_u64 v[44:45], v[134:135], 0, s[38:39]
	v_lshlrev_b64 v[46:47], 1, v[84:85]
	v_lshl_add_u64 v[44:45], v[44:45], 0, v[46:47]
	v_add_co_u32_e32 v44, vcc, s21, v44
	v_lshl_add_u64 v[56:57], v[136:137], 0, s[38:39]
	s_nop 0
	v_addc_co_u32_e32 v45, vcc, 0, v45, vcc
	v_lshl_add_u64 v[56:57], v[56:57], 0, v[46:47]
	v_add_co_u32_e32 v56, vcc, s21, v56
	v_mul_f32_e32 v0, v81, v81
	s_nop 0
	v_addc_co_u32_e32 v57, vcc, 0, v57, vcc
	global_load_dwordx4 v[72:75], v[44:45], off
	global_load_dwordx4 v[68:71], v[56:57], off
	v_lshl_add_u64 v[44:45], v[138:139], 0, s[38:39]
	v_lshl_add_u64 v[44:45], v[44:45], 0, v[46:47]
	v_add_co_u32_e32 v44, vcc, s21, v44
	v_lshl_add_u64 v[56:57], v[140:141], 0, s[38:39]
	s_nop 0
	v_addc_co_u32_e32 v45, vcc, 0, v45, vcc
	v_lshl_add_u64 v[46:47], v[56:57], 0, v[46:47]
	v_add_co_u32_e32 v46, vcc, s21, v46
	v_fmac_f32_e32 v0, v80, v80
	s_nop 0
	v_addc_co_u32_e32 v47, vcc, 0, v47, vcc
	global_load_dwordx4 v[56:59], v[44:45], off
	s_nop 0
	global_load_dwordx4 v[44:47], v[46:47], off
	v_fmac_f32_e32 v0, v82, v82
	v_fmac_f32_e32 v0, v83, v83
	v_fmac_f32_e32 v0, v76, v76
	v_fmac_f32_e32 v0, v77, v77
	v_fmac_f32_e32 v0, v78, v78
	v_fmac_f32_e32 v0, v79, v79
	ds_bpermute_b32 v86, v175, v0
	v_lshlrev_b32_e32 v88, 2, v131
	v_cmp_gt_u32_e32 vcc, 16, v133
	s_waitcnt lgkmcnt(0)
	v_add_f32_e32 v86, v0, v86
	ds_bpermute_b32 v87, v176, v86
	v_lshlrev_b32_e32 v0, 2, v178
	v_add3_u32 v0, s96, v0, v88
	s_and_saveexec_b64 s[12:13], vcc
	s_cbranch_execz .LBB0_1667
	s_waitcnt lgkmcnt(0)
	v_add_f32_e32 v86, v86, v87
	ds_write_b32 v0, v86

.LBB0_1736:
	s_waitcnt lgkmcnt(0)
	s_add_u32 s16, s30, 0x7a00000
	s_addc_u32 s17, s31, 0
	s_add_u32 s18, s30, 0x32c0000
	s_addc_u32 s19, s31, 0
	s_add_u32 s34, s28, 0x4000000
	v_mov_b32_e32 v9, 0
	s_addc_u32 s35, s29, 0
	v_mov_b32_e32 v10, v9
	v_mov_b32_e32 v11, v9
	s_add_u32 s36, s30, 0x14a00000
	v_mov_b32_e32 v8, v9
	s_waitcnt vmcnt(0)
	v_mov_b64_e32 v[22:23], v[10:11]
	v_mov_b64_e32 v[26:27], v[10:11]
	v_mov_b64_e32 v[30:31], v[10:11]
	v_mov_b64_e32 v[34:35], v[10:11]
	s_addc_u32 s37, s31, 0
	s_mov_b32 s39, 0
	s_movk_i32 s0, 0x1a00
	s_mov_b32 s1, 0x7a00000
	s_movk_i32 s20, 0x1000
	s_movk_i32 s21, 0x220
	s_mov_b32 s33, 0xbfb8aa3b
	s_mov_b32 s40, 0x3f317218
	s_mov_b32 s42, 0x3d800000
	s_movk_i32 s41, 0x110
	s_movk_i32 s43, 0x90
	s_mov_b32 s44, 0x3db504f3
	s_mov_b32 s46, 0x3b800000
	s_mov_b32 s48, 0x358637bd
	s_mov_b32 s45, 0x800000
	v_mov_b32_e32 v174, 0x1a00
	s_mov_b32 s49, s97
	v_mov_b64_e32 v[20:21], v[8:9]
	v_mov_b64_e32 v[24:25], v[8:9]
	v_mov_b64_e32 v[28:29], v[8:9]
	v_mov_b64_e32 v[32:33], v[8:9]
	s_ashr_i32 s61, s49, 8
	s_add_i32 s61, s61, 4
	s_lshl_b32 s61, s61, 12
	s_and_b32 s62, s49, 63
	s_lshl_b32 s62, s62, 6
	s_or_b32 s61, s61, s62
	s_bfe_u32 s62, s49, 0x20006
	s_lshl_b32 s63, s62, 7
	s_mov_b32 s66, s20
	s_mov_b32 s67, 0
	v_and_b32_e32 v230, 48, v204
	v_mov_b32_e32 v231, 0
	v_and_b32_e32 v232, 15, v204
	v_mov_b64_e32 v[234:235], s[16:17]
	v_or_b32_e32 v233, s61, v232
	v_mad_u64_u32 v[236:237], s[64:65], v233, s0, v[234:235]
	v_lshl_add_u64 v[236:237], v[236:237], 0, v[230:231]
	v_lshl_add_u64 v[236:237], v[236:237], 0, s[66:67]
	global_load_dwordx4 v[206:209], v[236:237], off offset:2048
	v_or_b32_e32 v233, 16, v232
	v_or_b32_e32 v233, s61, v233
	v_mad_u64_u32 v[236:237], s[64:65], v233, s0, v[234:235]
	v_lshl_add_u64 v[236:237], v[236:237], 0, v[230:231]
	v_lshl_add_u64 v[236:237], v[236:237], 0, s[66:67]
	global_load_dwordx4 v[210:213], v[236:237], off offset:2048
	v_or_b32_e32 v233, 32, v232
	v_or_b32_e32 v233, s61, v233
	v_mad_u64_u32 v[236:237], s[64:65], v233, s0, v[234:235]
	v_lshl_add_u64 v[236:237], v[236:237], 0, v[230:231]
	v_lshl_add_u64 v[236:237], v[236:237], 0, s[66:67]
	global_load_dwordx4 v[214:217], v[236:237], off offset:2048
	v_or_b32_e32 v233, 48, v232
	v_or_b32_e32 v233, s61, v233
	v_mad_u64_u32 v[236:237], s[64:65], v233, s0, v[234:235]
	v_lshl_add_u64 v[236:237], v[236:237], 0, v[230:231]
	v_lshl_add_u64 v[236:237], v[236:237], 0, s[66:67]
	global_load_dwordx4 v[218:221], v[236:237], off offset:2048
	v_lshrrev_b32_e32 v233, 6, v204
	v_lshlrev_b32_e32 v233, 4, v233
	v_or_b32_e32 v236, s63, v232
	v_add_u32_e32 v236, v236, v233
	v_lshlrev_b32_e32 v236, 5, v236
	v_and_b32_e32 v233, 16, v204
	v_add_u32_e32 v236, v236, v233
	v_mov_b32_e32 v237, 0
	v_lshl_add_u64 v[236:237], v[236:237], 0, s[18:19]
	v_mov_b32_e32 v222, 0
	v_mov_b32_e32 v223, 0
	v_mov_b32_e32 v224, 0
	v_mov_b32_e32 v225, 0
	v_and_b32_e32 v233, 63, v204
	v_cmp_gt_u32_e32 vcc, 32, v233
	s_and_saveexec_b64 s[70:71], vcc
	global_load_dwordx4 v[222:225], v[236:237], off
	s_or_b64 exec, exec, s[70:71]
	s_lshl_b32 s63, s63, 2
	s_add_u32 s74, s24, s63
	s_addc_u32 s75, s25, 0
	v_lshrrev_b32_e32 v233, 6, v204
	v_lshlrev_b32_e32 v236, 6, v233
	v_bfe_u32 v233, v204, 4, 2
	v_lshl_add_u32 v236, v233, 4, v236
	v_mov_b32_e32 v237, 0
	v_lshl_add_u64 v[236:237], v[236:237], 0, s[74:75]
	global_load_dwordx4 v[226:229], v[236:237], off
	s_waitcnt vmcnt(0)
	s_branch .LBB0_1739

.LBB0_1741:
	s_ashr_i32 s2, s49, 8
	s_add_i32 s10, s2, 4
	s_and_b32 s55, s49, 63
	s_ashr_i32 s11, s10, 31
	s_bfe_u32 s60, s49, 0x20006
	v_mov_b32_e32 v185, v204
	s_lshl_b64 s[8:9], s[10:11], 12
	s_lshl_b32 s2, s55, 6
	s_or_b32 s8, s8, s2
	v_lshlrev_b32_e32 v8, 3, v185
	s_lshl_b32 s11, s60, 7
	s_lshl_b32 s2, s60, 8
	v_and_b32_e32 v158, 0x78, v8
	v_ashrrev_i32_e32 v168, 4, v185
	s_add_u32 s12, s16, s2
	s_addc_u32 s13, s17, 0
	v_lshlrev_b32_e32 v8, 1, v158
	v_ashrrev_i32_e32 v169, 31, v168
	v_lshl_add_u64 v[10:11], s[12:13], 0, v[8:9]
	v_lshl_add_u64 v[36:37], s[8:9], 0, v[168:169]
	v_add_u32_e32 v164, 32, v168
	v_mad_u64_u32 v[38:39], s[12:13], v36, s0, v[10:11]
	v_ashrrev_i32_e32 v165, 31, v164
	v_mad_i32_i24 v39, v37, s0, v39
	v_lshl_add_u64 v[36:37], s[8:9], 0, v[164:165]
	v_and_b32_e32 v131, 15, v185
	v_mad_u64_u32 v[10:11], s[12:13], v36, s0, v[10:11]
	v_mad_i32_i24 v11, v37, s0, v11
	v_or_b32_e32 v124, s8, v131
	v_mov_b64_e32 v[36:37], s[16:17]
	v_mad_u64_u32 v[134:135], s[12:13], v124, s0, v[36:37]
	v_or_b32_e32 v129, 16, v131
	v_mad_i32_i24 v135, s9, v174, v135
	v_and_b32_e32 v116, 48, v185
	v_mov_b32_e32 v117, v9
	v_or_b32_e32 v130, s8, v129
	global_load_dwordx4 v[96:99], v[38:39], off
	global_load_dwordx4 v[104:107], v[38:39], off offset:1024
	global_load_dwordx4 v[60:63], v[10:11], off
	global_load_dwordx4 v[100:103], v[10:11], off offset:1024
	v_lshl_add_u64 v[10:11], v[134:135], 0, v[116:117]
	v_mad_u64_u32 v[136:137], s[12:13], v130, s0, v[36:37]
	v_or_b32_e32 v177, 32, v131
	v_add_co_u32_e32 v10, vcc, s20, v10
	v_mad_i32_i24 v137, s9, v174, v137
	v_or_b32_e32 v128, s8, v177
	v_addc_co_u32_e32 v11, vcc, 0, v11, vcc
	v_lshl_add_u64 v[38:39], v[136:137], 0, v[116:117]
	v_mad_u64_u32 v[138:139], s[12:13], v128, s0, v[36:37]
	v_add_co_u32_e32 v38, vcc, s20, v38
	v_mad_i32_i24 v139, s9, v174, v139
	s_nop 0
	v_addc_co_u32_e32 v39, vcc, 0, v39, vcc
	global_load_dword v239, v[10:11], off offset:2048
	v_mov_b32_e32 v56, v206
	v_mov_b32_e32 v57, v207
	v_mov_b32_e32 v58, v208
	v_mov_b32_e32 v59, v209
	global_load_dword v239, v[38:39], off offset:2048
	v_mov_b32_e32 v52, v210
	v_mov_b32_e32 v53, v211
	v_mov_b32_e32 v54, v212
	v_mov_b32_e32 v55, v213
	v_lshl_add_u64 v[10:11], v[138:139], 0, v[116:117]
	v_add_co_u32_e32 v38, vcc, s20, v10
	v_ashrrev_i32_e32 v66, 6, v185
	s_nop 0
	v_addc_co_u32_e32 v39, vcc, 0, v11, vcc
	v_or_b32_e32 v11, 48, v131
	v_or_b32_e32 v10, s8, v11
	v_mad_u64_u32 v[140:141], s[12:13], v10, s0, v[36:37]
	v_mad_i32_i24 v141, s9, v174, v141
	v_lshl_add_u64 v[36:37], v[140:141], 0, v[116:117]
	v_add_co_u32_e32 v36, vcc, s20, v36
	v_lshlrev_b32_e32 v122, 4, v66
	s_nop 0
	v_addc_co_u32_e32 v37, vcc, 0, v37, vcc
	global_load_dword v239, v[38:39], off offset:2048
	v_mov_b32_e32 v44, v214
	v_mov_b32_e32 v45, v215
	v_mov_b32_e32 v46, v216
	v_mov_b32_e32 v47, v217
	s_nop 0
	global_load_dword v239, v[36:37], off offset:2048
	v_mov_b32_e32 v36, v218
	v_mov_b32_e32 v37, v219
	v_mov_b32_e32 v38, v220
	v_mov_b32_e32 v39, v221
	v_or_b32_e32 v40, s11, v131
	v_and_b32_e32 v133, 63, v185
	v_add_u32_e32 v48, v40, v122
	v_and_b32_e32 v40, 16, v185
	v_mov_b32_e32 v41, v9
	v_mov_b32_e32 v125, s9
	v_lshl_add_u64 v[50:51], s[18:19], 0, v[40:41]
	v_cmp_lt_u32_e32 vcc, 31, v133
	v_cmp_gt_u32_e64 s[8:9], 32, v133
	v_mov_b32_e32 v40, 0
	v_ashrrev_i32_e32 v49, 31, v48
	v_mov_b32_e32 v108, 0
	v_mov_b32_e32 v109, 0
	v_mov_b32_e32 v110, 0
	v_mov_b32_e32 v111, 0
	s_and_saveexec_b64 s[12:13], s[8:9]
	s_cbranch_execz .LBB0_1743
	v_lshlrev_b64 v[42:43], 5, v[48:49]
	v_lshl_add_u64 v[42:43], v[50:51], 0, v[42:43]
	global_load_dword v239, v[42:43], off
	v_mov_b32_e32 v108, v222
	v_mov_b32_e32 v109, v223
	v_mov_b32_e32 v110, v224
	v_mov_b32_e32 v111, v225
.LBB0_1743:
	s_or_b64 exec, exec, s[12:13]
	s_lshl_b32 s8, s11, 2
	s_add_u32 s8, s24, s8
	v_bfe_u32 v117, v185, 4, 2
	s_addc_u32 s9, s25, 0
	v_ashrrev_i32_e32 v123, 31, v122
	v_lshl_add_u64 v[42:43], v[122:123], 2, s[8:9]
	v_lshlrev_b32_e32 v64, 4, v117
	v_mov_b32_e32 v65, v9
	v_lshl_add_u64 v[64:65], v[42:43], 0, v[64:65]
	global_load_dword v239, v[64:65], off
	v_mov_b32_e32 v112, v226
	v_mov_b32_e32 v113, v227
	v_mov_b32_e32 v114, v228
	v_mov_b32_e32 v115, v229
	v_mov_b32_e32 v41, 0
	v_mov_b32_e32 v42, 0
	v_mov_b32_e32 v43, 0
	s_and_saveexec_b64 s[8:9], vcc
	s_cbranch_execz .LBB0_1745
	v_lshlrev_b64 v[40:41], 5, v[48:49]
	v_lshl_add_u64 v[40:41], v[50:51], 0, v[40:41]
	v_add_co_u32_e32 v40, vcc, 0x4000, v40
	s_nop 1
	v_addc_co_u32_e32 v41, vcc, 0, v41, vcc
	global_load_dwordx4 v[40:43], v[40:41], off

.LBB0_1753:
	v_lshlrev_b32_e32 v64, 1, v131
	v_lshlrev_b32_e32 v132, 5, v66
	v_and_b32_e32 v64, 24, v64
	v_and_b32_e32 v65, 3, v185
	s_lshl_b64 s[12:13], s[12:13], 22
	v_or3_b32 v72, v65, v64, v132
	s_add_u32 s10, s10, s12
	s_addc_u32 s11, s11, s13
	s_lshl_b32 s12, s55, 16
	v_ashrrev_i32_e32 v73, 31, v72
	v_lshlrev_b32_e32 v175, 3, v117
	v_lshlrev_b32_e32 v64, 9, v131
	v_and_b32_e32 v178, 0xffffffc0, v185
	s_add_u32 s10, s10, s12
	v_lshlrev_b64 v[118:119], 8, v[72:73]
	v_or_b32_e32 v72, 4, v72
	v_add3_u32 v148, 0, v64, v178
	v_lshlrev_b32_e32 v64, 2, v185
	s_addc_u32 s11, s11, 0
	v_lshlrev_b32_e32 v126, 1, v175
	v_mov_b32_e32 v127, v9
	v_ashrrev_i32_e32 v73, 31, v72
	v_and_b32_e32 v65, 0x1fc, v64
	v_lshl_add_u64 v[74:75], s[10:11], 0, v[126:127]
	v_lshlrev_b64 v[120:121], 8, v[72:73]
	v_add_u32_e32 v176, 0, v65
	v_add_u32_e32 v181, s92, v64
	v_add_u32_e32 v180, s92, v65
	v_lshl_add_u64 v[64:65], v[74:75], 0, v[118:119]
	v_lshl_add_u64 v[72:73], v[74:75], 0, v[120:121]
	global_load_dwordx4 v[84:87], v[64:65], off
	global_load_dwordx4 v[80:83], v[64:65], off offset:64
	global_load_dwordx4 v[68:71], v[64:65], off offset:128
	s_nop 0
	global_load_dwordx4 v[64:67], v[64:65], off offset:192
	s_nop 0
	global_load_dwordx4 v[92:95], v[72:73], off
	global_load_dwordx4 v[88:91], v[72:73], off offset:64
	global_load_dwordx4 v[76:79], v[72:73], off offset:128
	s_nop 0
	global_load_dwordx4 v[72:75], v[72:73], off offset:192
	s_nop 0
	v_mfma_f32_16x16x32_bf16 v[142:145], v[108:111], v[56:59], 0
	v_add_u32_e32 v182, v148, v116
	v_ashrrev_i32_e32 v123, 7, v185
	v_lshlrev_b32_e32 v179, 13, v123
	v_cmp_lt_i32_e64 s[8:9], 0, v123
	v_mov_b32_e32 v169, 0
	s_nop 0
	s_nop 1
	v_add_f32_e32 v127, v112, v142
	v_add_f32_e32 v143, v113, v143
	v_add_f32_e32 v147, v114, v144
	v_min_f32_e32 v142, 0, v127
	v_mul_f32_e64 v127, |v127|, s33
	v_mul_f32_e64 v146, |v143|, s33
	v_min_f32_e32 v144, 0, v147
	v_mul_f32_e64 v147, |v147|, s33
	v_add_f32_e32 v145, v115, v145
	v_exp_f32_e32 v127, v127
	v_exp_f32_e32 v146, v146
	v_exp_f32_e32 v147, v147
	v_mul_f32_e64 v149, |v145|, s33
	v_exp_f32_e32 v149, v149
	v_add_f32_e32 v127, 1.0, v127
	v_add_f32_e32 v146, 1.0, v146
	v_add_f32_e32 v147, 1.0, v147
	v_log_f32_e32 v127, v127
	v_log_f32_e32 v146, v146
	v_log_f32_e32 v150, v147
	v_add_f32_e32 v147, 1.0, v149
	v_log_f32_e32 v149, v147
	v_min_f32_e32 v143, 0, v143
	v_xor_b32_e32 v147, 0x80000000, v146
	v_xor_b32_e32 v146, 0x80000000, v127
	v_min_f32_e32 v145, 0, v145
	v_pk_fma_f32 v[142:143], v[146:147], s[40:41], v[142:143] op_sel_hi:[1,0,1]
	v_xor_b32_e32 v147, 0x80000000, v149
	v_xor_b32_e32 v146, 0x80000000, v150
	v_pk_fma_f32 v[144:145], v[146:147], s[40:41], v[144:145] op_sel_hi:[1,0,1]
	v_pk_mul_f32 v[142:143], v[142:143], s[42:43] op_sel_hi:[1,0]
	v_pk_mul_f32 v[144:145], v[144:145], s[42:43] op_sel_hi:[1,0]
	ds_write_b128 v182, v[142:145]
	v_mfma_f32_16x16x32_bf16 v[142:145], v[108:111], v[52:55], 0
	s_nop 7
	v_add_f32_e32 v127, v112, v142
	v_add_f32_e32 v143, v113, v143
	v_add_f32_e32 v147, v114, v144
	v_min_f32_e32 v142, 0, v127
	v_mul_f32_e64 v127, |v127|, s33
	v_mul_f32_e64 v146, |v143|, s33
	v_min_f32_e32 v144, 0, v147
	v_mul_f32_e64 v147, |v147|, s33
	v_add_f32_e32 v145, v115, v145
	v_exp_f32_e32 v127, v127
	v_exp_f32_e32 v146, v146
	v_exp_f32_e32 v147, v147
	v_mul_f32_e64 v148, |v145|, s33
	v_exp_f32_e32 v148, v148
	v_add_f32_e32 v127, 1.0, v127
	v_add_f32_e32 v146, 1.0, v146
	v_add_f32_e32 v147, 1.0, v147
	v_log_f32_e32 v127, v127
	v_log_f32_e32 v146, v146
	v_log_f32_e32 v149, v147
	v_add_f32_e32 v147, 1.0, v148
	v_log_f32_e32 v148, v147
	v_min_f32_e32 v143, 0, v143
	v_xor_b32_e32 v147, 0x80000000, v146
	v_xor_b32_e32 v146, 0x80000000, v127
	v_min_f32_e32 v145, 0, v145
	v_pk_fma_f32 v[142:143], v[146:147], s[40:41], v[142:143] op_sel_hi:[1,0,1]
	v_xor_b32_e32 v147, 0x80000000, v148
	v_xor_b32_e32 v146, 0x80000000, v149
	v_pk_fma_f32 v[144:145], v[146:147], s[40:41], v[144:145] op_sel_hi:[1,0,1]
	v_pk_mul_f32 v[142:143], v[142:143], s[42:43] op_sel_hi:[1,0]
	v_pk_mul_f32 v[144:145], v[144:145], s[42:43] op_sel_hi:[1,0]
	ds_write_b128 v182, v[142:145] offset:8192
	v_mfma_f32_16x16x32_bf16 v[142:145], v[108:111], v[44:47], 0
	v_mfma_f32_16x16x32_bf16 v[108:111], v[108:111], v[36:39], 0
	s_nop 6
	v_add_f32_e32 v127, v112, v142
	v_add_f32_e32 v112, v112, v108
	v_add_f32_e32 v109, v113, v109
	v_add_f32_e32 v143, v113, v143
	v_add_f32_e32 v147, v114, v144
	v_min_f32_e32 v108, 0, v112
	v_mul_f32_e64 v112, |v112|, s33
	v_mul_f32_e64 v113, |v109|, s33
	v_add_f32_e32 v114, v114, v110
	v_add_f32_e32 v111, v115, v111
	v_min_f32_e32 v142, 0, v127
	v_mul_f32_e64 v127, |v127|, s33
	v_mul_f32_e64 v146, |v143|, s33
	v_min_f32_e32 v144, 0, v147
	v_mul_f32_e64 v147, |v147|, s33
	v_add_f32_e32 v145, v115, v145
	v_exp_f32_e32 v112, v112
	v_exp_f32_e32 v113, v113
	v_min_f32_e32 v110, 0, v114
	v_mul_f32_e64 v114, |v114|, s33
	v_mul_f32_e64 v115, |v111|, s33
	v_exp_f32_e32 v127, v127
	v_exp_f32_e32 v146, v146
	v_exp_f32_e32 v147, v147
	v_mul_f32_e64 v148, |v145|, s33
	v_exp_f32_e32 v114, v114
	v_exp_f32_e32 v115, v115
	v_exp_f32_e32 v148, v148
	v_add_f32_e32 v112, 1.0, v112
	v_add_f32_e32 v113, 1.0, v113
	v_add_f32_e32 v127, 1.0, v127
	v_add_f32_e32 v146, 1.0, v146
	v_add_f32_e32 v147, 1.0, v147
	v_log_f32_e32 v112, v112
	v_log_f32_e32 v113, v113
	v_add_f32_e32 v114, 1.0, v114
	v_add_f32_e32 v115, 1.0, v115
	v_log_f32_e32 v127, v127
	v_log_f32_e32 v146, v146
	v_log_f32_e32 v149, v147
	v_add_f32_e32 v147, 1.0, v148
	v_log_f32_e32 v114, v114
	v_log_f32_e32 v115, v115
	v_log_f32_e32 v148, v147
	v_min_f32_e32 v109, 0, v109
	v_xor_b32_e32 v113, 0x80000000, v113
	v_xor_b32_e32 v112, 0x80000000, v112
	v_min_f32_e32 v143, 0, v143
	v_xor_b32_e32 v147, 0x80000000, v146
	v_xor_b32_e32 v146, 0x80000000, v127
	v_min_f32_e32 v111, 0, v111
	v_pk_fma_f32 v[108:109], v[112:113], s[40:41], v[108:109] op_sel_hi:[1,0,1]
	v_xor_b32_e32 v113, 0x80000000, v115
	v_xor_b32_e32 v112, 0x80000000, v114
	v_min_f32_e32 v145, 0, v145
	v_pk_fma_f32 v[142:143], v[146:147], s[40:41], v[142:143] op_sel_hi:[1,0,1]
	v_xor_b32_e32 v147, 0x80000000, v148
	v_xor_b32_e32 v146, 0x80000000, v149
	v_pk_fma_f32 v[110:111], v[112:113], s[40:41], v[110:111] op_sel_hi:[1,0,1]
	v_pk_fma_f32 v[144:145], v[146:147], s[40:41], v[144:145] op_sel_hi:[1,0,1]
	v_pk_mul_f32 v[110:111], v[110:111], s[42:43] op_sel_hi:[1,0]
	v_pk_mul_f32 v[108:109], v[108:109], s[42:43] op_sel_hi:[1,0]
	v_pk_mul_f32 v[144:145], v[144:145], s[42:43] op_sel_hi:[1,0]
	v_pk_mul_f32 v[142:143], v[142:143], s[42:43] op_sel_hi:[1,0]
	ds_write_b128 v182, v[108:111] offset:24576
	v_add_u32_e32 v108, v176, v179
	ds_write_b128 v182, v[142:145] offset:16384
	s_waitcnt lgkmcnt(0)
	s_barrier
	ds_read2st64_b32 v[110:111], v108 offset1:2
	ds_read2st64_b32 v[112:113], v108 offset0:4 offset1:6
	ds_read2st64_b32 v[114:115], v108 offset0:8 offset1:10
	ds_read2st64_b32 v[142:143], v108 offset0:12 offset1:14
	ds_read2st64_b32 v[144:145], v108 offset0:16 offset1:18
	ds_read2st64_b32 v[146:147], v108 offset0:20 offset1:22
	ds_read2st64_b32 v[148:149], v108 offset0:24 offset1:26
	ds_read2st64_b32 v[150:151], v108 offset0:28 offset1:30
	s_waitcnt lgkmcnt(7)
	v_add_f32_e32 v166, 0, v110
	v_add_f32_e32 v167, v166, v111
	s_waitcnt lgkmcnt(6)
	v_add_f32_e32 v163, v167, v112
	v_add_f32_e32 v165, v163, v113
	s_waitcnt lgkmcnt(5)
	v_add_f32_e32 v161, v165, v114
	v_add_f32_e32 v162, v161, v115
	s_waitcnt lgkmcnt(4)
	v_add_f32_e32 v159, v162, v142
	v_add_f32_e32 v160, v159, v143
	s_waitcnt lgkmcnt(3)
	v_add_f32_e32 v115, v160, v144
	v_add_f32_e32 v127, v115, v145
	s_waitcnt lgkmcnt(2)
	v_add_f32_e32 v113, v127, v146
	v_add_f32_e32 v114, v113, v147
	s_waitcnt lgkmcnt(1)
	v_add_f32_e32 v111, v114, v148
	v_add_f32_e32 v112, v111, v149
	s_waitcnt lgkmcnt(0)
	v_add_f32_e32 v109, v112, v150
	v_add_f32_e32 v110, v109, v151
	ds_write_b32 v181, v110
	s_waitcnt lgkmcnt(0)
	s_barrier
	s_and_saveexec_b64 s[10:11], s[8:9]
	s_cbranch_execnz .LBB0_1816
	s_or_b64 exec, exec, s[10:11]
	v_cmp_lt_i32_e64 s[10:11], 1, v123
	s_and_saveexec_b64 s[12:13], s[10:11]
	s_cbranch_execnz .LBB0_1817

.LBB0_1757:
	s_or_b64 exec, exec, s[14:15]
	s_waitcnt vmcnt(16)
	v_lshlrev_b32_e32 v148, 16, v100
	v_and_b32_e32 v149, 0xffff0000, v100
	v_lshlrev_b32_e32 v146, 16, v101
	v_and_b32_e32 v147, 0xffff0000, v101
	v_add_f32_e32 v100, v166, v169
	v_add_f32_e32 v101, v167, v169
	ds_write2st64_b32 v108, v100, v101 offset1:2
	v_add_f32_e32 v100, v163, v169
	v_add_f32_e32 v101, v165, v169
	ds_write2st64_b32 v108, v100, v101 offset0:4 offset1:6
	v_add_f32_e32 v100, v161, v169
	v_add_f32_e32 v101, v162, v169
	ds_write2st64_b32 v108, v100, v101 offset0:8 offset1:10
	v_add_f32_e32 v100, v159, v169
	v_add_f32_e32 v101, v160, v169
	ds_write2st64_b32 v108, v100, v101 offset0:12 offset1:14
	v_add_f32_e32 v100, v115, v169
	v_add_f32_e32 v101, v127, v169
	ds_write2st64_b32 v108, v100, v101 offset0:16 offset1:18
	v_add_f32_e32 v100, v113, v169
	v_add_f32_e32 v101, v114, v169
	ds_write2st64_b32 v108, v100, v101 offset0:20 offset1:22
	v_add_f32_e32 v100, v111, v169
	v_add_f32_e32 v101, v112, v169
	ds_write2st64_b32 v108, v100, v101 offset0:24 offset1:26
	v_add_f32_e32 v100, v109, v169
	v_add_f32_e32 v101, v110, v169
	v_lshl_add_u32 v184, v158, 2, 0
	ds_write2st64_b32 v108, v100, v101 offset0:28 offset1:30
	v_lshlrev_b32_e32 v100, 9, v168
	v_add_u32_e32 v186, v184, v100
	v_lshlrev_b32_e32 v156, 16, v104
	v_and_b32_e32 v157, 0xffff0000, v104
	v_lshlrev_b32_e32 v154, 16, v105
	v_and_b32_e32 v155, 0xffff0000, v105
	v_lshlrev_b32_e32 v152, 16, v106
	v_and_b32_e32 v153, 0xffff0000, v106
	v_lshlrev_b32_e32 v150, 16, v107
	v_and_b32_e32 v151, 0xffff0000, v107
	s_waitcnt lgkmcnt(0)
	s_barrier
	ds_read_b128 v[104:107], v184 offset:16384
	ds_read_b128 v[108:111], v186
	v_and_b32_e32 v159, 0xffff0000, v96
	v_ashrrev_i32_e32 v100, 3, v185
	v_lshlrev_b32_e32 v144, 16, v102
	v_and_b32_e32 v145, 0xffff0000, v102
	s_waitcnt lgkmcnt(0)
	v_sub_f32_e32 v158, v108, v104
	v_mul_f32_e32 v158, 0x3fb8aa3b, v158
	v_exp_f32_e32 v160, v158
	v_sub_f32_e32 v158, v104, v108
	v_mul_f32_e32 v158, 0x3fb8aa3b, v158
	v_exp_f32_e32 v162, v158
	v_lshlrev_b32_e32 v158, 16, v96
	v_sub_f32_e32 v96, v109, v105
	v_mul_f32_e32 v96, 0x3fb8aa3b, v96
	v_exp_f32_e32 v161, v96
	v_sub_f32_e32 v96, v105, v109
	v_mul_f32_e32 v96, 0x3fb8aa3b, v96
	v_exp_f32_e32 v163, v96
	v_mul_f32_e32 v96, 0x3fb8aa3b, v109
	v_exp_f32_e32 v109, v96
	v_sub_f32_e32 v96, v110, v106
	v_pk_mul_f32 v[172:173], v[162:163], v[156:157]
	v_lshlrev_b32_e32 v162, 16, v97
	v_and_b32_e32 v163, 0xffff0000, v97
	v_sub_f32_e32 v97, v111, v107
	v_lshlrev_b32_e32 v142, 16, v103
	v_and_b32_e32 v143, 0xffff0000, v103
	v_and_b32_e32 v127, 0xffffffe0, v100
	ds_read_b128 v[100:103], v184 offset:16400
	ds_read_b128 v[112:115], v186 offset:16
	v_mul_f32_e32 v96, 0x3fb8aa3b, v96
	v_mul_f32_e32 v97, 0x3fb8aa3b, v97
	v_exp_f32_e32 v96, v96
	v_exp_f32_e32 v97, v97
	v_pk_mul_f32 v[162:163], v[162:163], s[44:45] op_sel_hi:[1,0]
	v_pk_mul_f32 v[158:159], v[158:159], s[44:45] op_sel_hi:[1,0]
	v_mul_f32_e32 v108, 0x3fb8aa3b, v108
	v_pk_mul_f32 v[188:189], v[162:163], v[96:97]
	s_waitcnt lgkmcnt(0)
	v_sub_f32_e32 v97, v100, v112
	v_pk_mul_f32 v[170:171], v[158:159], v[160:161]
	v_sub_f32_e32 v160, v106, v110
	v_sub_f32_e32 v161, v107, v111
	v_mul_f32_e32 v97, 0x3fb8aa3b, v97
	v_mul_f32_e32 v160, 0x3fb8aa3b, v160
	v_mul_f32_e32 v161, 0x3fb8aa3b, v161
	v_exp_f32_e32 v166, v97
	v_mul_f32_e32 v97, 0x3fb8aa3b, v112
	v_exp_f32_e32 v160, v160
	v_exp_f32_e32 v161, v161
	v_sub_f32_e32 v96, v112, v100
	v_exp_f32_e32 v112, v97
	v_sub_f32_e32 v97, v113, v101
	v_mul_f32_e32 v96, 0x3fb8aa3b, v96
	v_mul_f32_e32 v97, 0x3fb8aa3b, v97
	v_exp_f32_e32 v96, v96
	v_exp_f32_e32 v97, v97
	v_pk_mul_f32 v[190:191], v[160:161], v[154:155]
	v_lshlrev_b32_e32 v160, 16, v98
	v_and_b32_e32 v161, 0xffff0000, v98
	v_sub_f32_e32 v98, v101, v113
	v_mul_f32_e32 v98, 0x3fb8aa3b, v98
	v_pk_mul_f32 v[160:161], v[160:161], s[44:45] op_sel_hi:[1,0]
	v_exp_f32_e32 v167, v98
	v_pk_mul_f32 v[192:193], v[160:161], v[96:97]
	v_sub_f32_e32 v97, v102, v114
	v_mul_f32_e32 v98, 0x3fb8aa3b, v113
	v_mul_f32_e32 v97, 0x3fb8aa3b, v97
	v_exp_f32_e32 v113, v98
	v_exp_f32_e32 v98, v97
	v_mul_f32_e32 v97, 0x3fb8aa3b, v114
	v_sub_f32_e32 v96, v114, v102
	v_exp_f32_e32 v114, v97
	v_sub_f32_e32 v97, v115, v103
	v_pk_mul_f32 v[194:195], v[166:167], v[152:153]
	v_mul_f32_e32 v96, 0x3fb8aa3b, v96
	v_lshlrev_b32_e32 v166, 16, v99
	v_and_b32_e32 v167, 0xffff0000, v99
	v_mul_f32_e32 v97, 0x3fb8aa3b, v97
	v_sub_f32_e32 v99, v103, v115
	v_exp_f32_e32 v96, v96
	v_exp_f32_e32 v97, v97
	v_mul_f32_e32 v99, 0x3fb8aa3b, v99
	v_mul_f32_e32 v110, 0x3fb8aa3b, v110
	v_mul_f32_e32 v111, 0x3fb8aa3b, v111
	v_exp_f32_e32 v99, v99
	v_mul_f32_e32 v115, 0x3fb8aa3b, v115
	v_exp_f32_e32 v108, v108
	v_exp_f32_e32 v110, v110
	v_exp_f32_e32 v111, v111
	v_exp_f32_e32 v115, v115
	v_pk_mul_f32 v[166:167], v[166:167], s[44:45] op_sel_hi:[1,0]
	v_sub_u32_e32 v123, v184, v8
	v_pk_mul_f32 v[196:197], v[166:167], v[96:97]
	v_mul_lo_u32 v165, v168, s41
	v_pk_mul_f32 v[198:199], v[98:99], v[150:151]
	v_cvt_pk_bf16_f32 v96, v170, v171
	v_cvt_pk_bf16_f32 v97, v188, v189
	v_cvt_pk_bf16_f32 v98, v192, v193
	v_cvt_pk_bf16_f32 v99, v196, v197
	v_add_u32_e32 v183, v123, v165
	v_pk_mul_f32 v[108:109], v[158:159], v[108:109]
	v_pk_mul_f32 v[110:111], v[162:163], v[110:111]
	v_pk_mul_f32 v[112:113], v[160:161], v[112:113]
	v_pk_mul_f32 v[114:115], v[166:167], v[114:115]
	ds_write_b128 v183, v[96:99] offset:32768
	v_cvt_pk_bf16_f32 v96, v172, v173
	v_cvt_pk_bf16_f32 v97, v190, v191
	v_cvt_pk_bf16_f32 v98, v194, v195
	v_cvt_pk_bf16_f32 v99, v198, v199
	ds_write_b128 v183, v[96:99] offset:50176
	v_cvt_pk_bf16_f32 v96, v108, v109
	v_cvt_pk_bf16_f32 v97, v110, v111
	v_cvt_pk_bf16_f32 v98, v112, v113
	v_cvt_pk_bf16_f32 v99, v114, v115
	v_add3_u32 v8, s94, v8, v165
	ds_write_b128 v8, v[96:99]
	v_lshlrev_b32_e32 v96, 9, v164
	v_add_u32_e32 v189, v184, v96
	ds_read_b128 v[96:99], v189
	v_or_b32_e32 v108, v127, v131
	v_mul_lo_u32 v187, v108, s41
	ds_read_b128 v[108:111], v189 offset:16
	v_lshlrev_b32_e32 v114, 16, v60
	v_and_b32_e32 v115, 0xffff0000, v60
	s_waitcnt lgkmcnt(1)
	v_sub_f32_e32 v60, v97, v105
	v_mul_f32_e32 v60, 0x3fb8aa3b, v60
	v_exp_f32_e32 v113, v60
	v_sub_f32_e32 v60, v105, v97
	v_mul_f32_e32 v60, 0x3fb8aa3b, v60
	v_exp_f32_e32 v105, v60
	v_mul_f32_e32 v60, 0x3fb8aa3b, v97
	v_exp_f32_e32 v97, v60
	v_pk_mul_f32 v[164:165], v[114:115], s[44:45] op_sel_hi:[1,0]
	v_sub_f32_e32 v60, v98, v106
	v_lshlrev_b32_e32 v114, 16, v61
	v_and_b32_e32 v115, 0xffff0000, v61
	v_sub_f32_e32 v61, v99, v107
	v_mul_f32_e32 v60, 0x3fb8aa3b, v60
	v_mul_f32_e32 v61, 0x3fb8aa3b, v61
	v_exp_f32_e32 v60, v60
	v_exp_f32_e32 v61, v61
	v_pk_mul_f32 v[170:171], v[114:115], s[44:45] op_sel_hi:[1,0]
	v_lshlrev_b32_e32 v168, 16, v62
	v_and_b32_e32 v169, 0xffff0000, v62
	v_pk_mul_f32 v[114:115], v[170:171], v[60:61]
	s_waitcnt lgkmcnt(0)
	v_sub_f32_e32 v61, v100, v108
	v_mul_f32_e32 v61, 0x3fb8aa3b, v61
	v_sub_f32_e32 v60, v108, v100
	v_exp_f32_e32 v100, v61
	v_mul_f32_e32 v61, 0x3fb8aa3b, v108
	v_exp_f32_e32 v108, v61
	v_sub_f32_e32 v61, v109, v101
	v_mul_f32_e32 v60, 0x3fb8aa3b, v60
	v_mul_f32_e32 v61, 0x3fb8aa3b, v61
	v_exp_f32_e32 v60, v60
	v_exp_f32_e32 v61, v61
	v_sub_f32_e32 v62, v101, v109
	v_pk_mul_f32 v[168:169], v[168:169], s[44:45] op_sel_hi:[1,0]
	v_mul_f32_e32 v62, 0x3fb8aa3b, v62
	v_pk_mul_f32 v[190:191], v[168:169], v[60:61]
	v_sub_f32_e32 v61, v102, v110
	v_exp_f32_e32 v101, v62
	v_mul_f32_e32 v62, 0x3fb8aa3b, v109
	v_mul_f32_e32 v61, 0x3fb8aa3b, v61
	v_exp_f32_e32 v109, v62
	v_exp_f32_e32 v62, v61
	v_mul_f32_e32 v61, 0x3fb8aa3b, v110
	v_sub_f32_e32 v112, v96, v104
	v_sub_f32_e32 v60, v110, v102
	v_exp_f32_e32 v102, v61
	v_sub_f32_e32 v61, v111, v103
	v_mul_f32_e32 v112, 0x3fb8aa3b, v112
	v_sub_f32_e32 v104, v104, v96
	v_sub_f32_e32 v106, v106, v98
	v_sub_f32_e32 v107, v107, v99
	v_mul_f32_e32 v60, 0x3fb8aa3b, v60
	v_lshlrev_b32_e32 v172, 16, v63
	v_and_b32_e32 v173, 0xffff0000, v63
	v_mul_f32_e32 v61, 0x3fb8aa3b, v61
	v_sub_f32_e32 v63, v103, v111
	v_exp_f32_e32 v112, v112
	v_mul_f32_e32 v104, 0x3fb8aa3b, v104
	v_mul_f32_e32 v106, 0x3fb8aa3b, v106
	v_mul_f32_e32 v107, 0x3fb8aa3b, v107
	v_exp_f32_e32 v60, v60
	v_exp_f32_e32 v61, v61
	v_mul_f32_e32 v63, 0x3fb8aa3b, v63
	v_exp_f32_e32 v104, v104
	v_mul_f32_e32 v96, 0x3fb8aa3b, v96
	v_exp_f32_e32 v106, v106
	v_mul_f32_e32 v98, 0x3fb8aa3b, v98
	v_exp_f32_e32 v107, v107
	v_mul_f32_e32 v99, 0x3fb8aa3b, v99
	v_exp_f32_e32 v63, v63
	v_mul_f32_e32 v103, 0x3fb8aa3b, v111
	v_exp_f32_e32 v96, v96
	v_exp_f32_e32 v98, v98
	v_exp_f32_e32 v99, v99
	v_exp_f32_e32 v103, v103
	v_pk_mul_f32 v[172:173], v[172:173], s[44:45] op_sel_hi:[1,0]
	v_pk_mul_f32 v[112:113], v[164:165], v[112:113]
	v_pk_mul_f32 v[110:111], v[172:173], v[60:61]
	v_pk_mul_f32 v[104:105], v[104:105], v[148:149]
	v_pk_mul_f32 v[106:107], v[106:107], v[146:147]
	v_pk_mul_f32 v[100:101], v[100:101], v[144:145]
	v_pk_mul_f32 v[192:193], v[62:63], v[142:143]
	v_cvt_pk_bf16_f32 v60, v112, v113
	v_cvt_pk_bf16_f32 v61, v114, v115
	v_cvt_pk_bf16_f32 v62, v190, v191
	v_cvt_pk_bf16_f32 v63, v110, v111
	v_add_u32_e32 v123, 0, v116
	v_pk_mul_f32 v[96:97], v[164:165], v[96:97]
	v_pk_mul_f32 v[98:99], v[170:171], v[98:99]
	v_pk_mul_f32 v[108:109], v[168:169], v[108:109]
	v_pk_mul_f32 v[102:103], v[172:173], v[102:103]
	ds_write_b128 v183, v[60:63] offset:41472
	v_cvt_pk_bf16_f32 v60, v104, v105
	v_cvt_pk_bf16_f32 v61, v106, v107
	v_cvt_pk_bf16_f32 v62, v100, v101
	v_cvt_pk_bf16_f32 v63, v192, v193
	ds_write_b128 v183, v[60:63] offset:58880
	v_cvt_pk_bf16_f32 v60, v96, v97
	v_cvt_pk_bf16_f32 v61, v98, v99
	v_cvt_pk_bf16_f32 v62, v108, v109
	v_cvt_pk_bf16_f32 v63, v102, v103
	v_add_u32_e32 v190, v123, v187
	ds_write_b128 v8, v[60:63] offset:8704
	s_waitcnt lgkmcnt(0)
	s_barrier
	ds_read_b128 v[60:63], v190 offset:50176
	v_and_or_b32 v187, v122, 48, v131
	v_mad_u32_u24 v96, v187, s41, 0
	v_add_u32_e32 v191, v96, v116
	ds_read_b128 v[96:99], v191 offset:32768
	ds_read_b128 v[100:103], v191 offset:32832
	ds_read_b128 v[104:107], v190 offset:50240
	ds_read_b128 v[108:111], v190 offset:54528
	ds_read_b128 v[112:115], v190 offset:54592
	s_waitcnt lgkmcnt(4)
	v_mfma_f32_16x16x32_bf16 v[60:63], v[60:63], v[96:99], 0
	v_lshlrev_b32_e32 v117, 2, v117
	v_or_b32_e32 v192, v117, v127
	v_cmp_ge_i32_e32 vcc, v187, v192
	s_waitcnt lgkmcnt(1)
	v_mfma_f32_16x16x32_bf16 v[96:99], v[108:111], v[96:99], 0
	ds_read_b128 v[108:111], v190 offset:50304
	v_cmp_gt_i32_e64 s[14:15], v187, v192
	v_mul_u32_u24_e32 v117, 0x90, v187
	v_mfma_f32_16x16x32_bf16 v[60:63], v[104:107], v[100:103], v[60:63]
	ds_read_b128 v[104:107], v191 offset:32896
	ds_read_b128 v[194:197], v190 offset:54656
	v_or_b32_e32 v198, 17, v192
	v_or_b32_e32 v200, 18, v192
	s_waitcnt lgkmcnt(3)
	v_mfma_f32_16x16x32_bf16 v[96:99], v[112:115], v[100:103], v[96:99]
	ds_read_b128 v[100:103], v191 offset:32960
	ds_read_b128 v[112:115], v190 offset:50368
	v_bfe_u32 v122, v185, 2, 2
	v_or_b32_e32 v201, 19, v192
	s_waitcnt lgkmcnt(3)
	v_mfma_f32_16x16x32_bf16 v[60:63], v[108:111], v[104:107], v[60:63]
	ds_read_b128 v[108:111], v190 offset:54720
	v_add_u32_e32 v188, s95, v116
	v_add_u32_e32 v199, s94, v116
	s_waitcnt lgkmcnt(3)
	v_mfma_f32_16x16x32_bf16 v[96:99], v[194:197], v[104:107], v[96:99]
	v_or_b32_e32 v195, 2, v192
	v_or_b32_e32 v196, 3, v192
	v_or_b32_e32 v197, 16, v192
	s_waitcnt lgkmcnt(1)
	v_mfma_f32_16x16x32_bf16 v[60:63], v[112:115], v[100:103], v[60:63]
	v_lshrrev_b32_e32 v104, 1, v185
	v_lshlrev_b32_e32 v105, 4, v133
	v_and_or_b32 v194, v104, 24, v122
	s_waitcnt lgkmcnt(0)
	v_mfma_f32_16x16x32_bf16 v[96:99], v[108:111], v[100:103], v[96:99]
	v_lshlrev_b32_e32 v104, 1, v132
	s_nop 1
	v_cndmask_b32_e32 v60, 0, v60, vcc
	v_cmp_ge_i32_e32 vcc, v187, v195
	v_cndmask_b32_e64 v61, 0, v61, s[14:15]
	v_cvt_pk_bf16_f32 v60, v60, v61
	v_cndmask_b32_e32 v62, 0, v62, vcc
	v_cmp_ge_i32_e32 vcc, v187, v196
	v_and_b32_e32 v105, 48, v105
	v_add3_u32 v185, s73, v104, v105
	v_cndmask_b32_e32 v63, 0, v63, vcc
	v_cvt_pk_bf16_f32 v61, v62, v63
	v_lshlrev_b32_e32 v62, 1, v192
	v_cmp_ge_i32_e32 vcc, v187, v197
	v_add3_u32 v193, s95, v117, v62
	v_mad_u32_u24 v117, v194, s21, v185
	v_cndmask_b32_e32 v62, 0, v96, vcc
	v_cmp_ge_i32_e32 vcc, v187, v198
	v_mad_u32_u24 v122, v131, s43, v188
	v_mad_u32_u24 v116, v131, s41, v199
	v_cndmask_b32_e32 v63, 0, v97, vcc
	v_cmp_ge_i32_e32 vcc, v187, v200
	v_cvt_pk_bf16_f32 v62, v62, v63
	s_nop 0
	v_cndmask_b32_e32 v96, 0, v98, vcc
	v_cmp_ge_i32_e32 vcc, v187, v201
	s_nop 1
	v_cndmask_b32_e32 v97, 0, v99, vcc
	v_cvt_pk_bf16_f32 v63, v96, v97
	ds_write2_b64 v193, v[60:61], v[62:63] offset1:4
	s_waitcnt lgkmcnt(0)
	s_barrier
	ds_read_b64_tr_b16 v[62:63], v117 offset:2176
	ds_read_b64_tr_b16 v[60:61], v117
	ds_read_b64_tr_b16 v[98:99], v117 offset:2184
	ds_read_b64_tr_b16 v[96:97], v117 offset:8
	ds_read_b128 v[100:103], v122
	ds_read_b128 v[104:107], v122 offset:64
	ds_read_b128 v[112:115], v122 offset:2304
	ds_read_b128 v[206:209], v122 offset:2368
	ds_read_b128 v[214:217], v122 offset:4608
	ds_read_b128 v[218:221], v122 offset:4672
	ds_read_b128 v[226:229], v122 offset:6912
	ds_read_b128 v[230:233], v122 offset:6976
	s_waitcnt lgkmcnt(7)
	v_mfma_f32_16x16x32_bf16 v[108:111], v[60:63], v[100:103], 0
	ds_read_b64_tr_b16 v[234:235], v117 offset:17408
	ds_read_b64_tr_b16 v[236:237], v117 offset:19584
	v_mfma_f32_16x16x32_bf16 v[100:103], v[96:99], v[100:103], 0
	s_waitcnt lgkmcnt(7)
	v_mfma_f32_16x16x32_bf16 v[210:213], v[60:63], v[112:115], 0
	v_mfma_f32_16x16x32_bf16 v[112:115], v[96:99], v[112:115], 0
	s_waitcnt lgkmcnt(5)
	v_mfma_f32_16x16x32_bf16 v[222:225], v[60:63], v[214:217], 0
	v_mfma_f32_16x16x32_bf16 v[214:217], v[96:99], v[214:217], 0
	s_waitcnt lgkmcnt(3)
	v_mfma_f32_16x16x32_bf16 v[60:63], v[60:63], v[226:229], 0
	v_mfma_f32_16x16x32_bf16 v[96:99], v[96:99], v[226:229], 0
	ds_read_b64_tr_b16 v[228:229], v117 offset:19592
	ds_read_b64_tr_b16 v[226:227], v117 offset:17416
	s_waitcnt lgkmcnt(2)
	v_mfma_f32_16x16x32_bf16 v[108:111], v[234:237], v[104:107], v[108:111]
	s_waitcnt lgkmcnt(0)
	v_mfma_f32_16x16x32_bf16 v[100:103], v[226:229], v[104:107], v[100:103]
	v_mfma_f32_16x16x32_bf16 v[104:107], v[234:237], v[206:209], v[210:213]
	v_mfma_f32_16x16x32_bf16 v[112:115], v[226:229], v[206:209], v[112:115]
	v_mfma_f32_16x16x32_bf16 v[206:209], v[234:237], v[218:221], v[222:225]
	v_mfma_f32_16x16x32_bf16 v[210:213], v[226:229], v[218:221], v[214:217]
	s_nop 2
	ds_read_b128 v[214:217], v116
	ds_read_b128 v[218:221], v116 offset:64
	s_waitcnt vmcnt(7) lgkmcnt(1)
	v_mfma_f32_16x16x32_bf16 v[108:111], v[84:87], v[214:217], v[108:111]
	s_waitcnt vmcnt(3)
	v_mfma_f32_16x16x32_bf16 v[100:103], v[92:95], v[214:217], v[100:103]
	ds_read_b128 v[214:217], v116 offset:4352
	ds_read_b128 v[222:225], v116 offset:4416
	v_mfma_f32_16x16x32_bf16 v[96:99], v[226:229], v[230:233], v[96:99]
	s_waitcnt lgkmcnt(1)
	v_mfma_f32_16x16x32_bf16 v[104:107], v[84:87], v[214:217], v[104:107]
	v_mfma_f32_16x16x32_bf16 v[112:115], v[92:95], v[214:217], v[112:115]
	ds_read_b128 v[214:217], v116 offset:8704
	ds_read_b128 v[226:229], v116 offset:8768
	v_mfma_f32_16x16x32_bf16 v[60:63], v[234:237], v[230:233], v[60:63]
	s_waitcnt lgkmcnt(1)
	v_mfma_f32_16x16x32_bf16 v[206:209], v[84:87], v[214:217], v[206:209]
	v_mfma_f32_16x16x32_bf16 v[210:213], v[92:95], v[214:217], v[210:213]
	ds_read_b128 v[214:217], v116 offset:13056
	ds_read_b128 v[230:233], v116 offset:13120
	s_waitcnt lgkmcnt(1)
	v_mfma_f32_16x16x32_bf16 v[60:63], v[84:87], v[214:217], v[60:63]
	v_mfma_f32_16x16x32_bf16 v[84:87], v[92:95], v[214:217], v[96:99]
	v_mfma_f32_16x16x32_bf16 v[92:95], v[80:83], v[218:221], v[108:111]
	s_waitcnt vmcnt(2)
	v_mfma_f32_16x16x32_bf16 v[96:99], v[88:91], v[218:221], v[100:103]
	v_mfma_f32_16x16x32_bf16 v[100:103], v[80:83], v[222:225], v[104:107]
	v_mfma_f32_16x16x32_bf16 v[108:111], v[80:83], v[226:229], v[206:209]
	s_waitcnt lgkmcnt(0)
	v_mfma_f32_16x16x32_bf16 v[60:63], v[80:83], v[230:233], v[60:63]
	v_mfma_f32_16x16x32_bf16 v[80:83], v[88:91], v[230:233], v[84:87]
	v_mfma_f32_16x16x32_bf16 v[104:107], v[88:91], v[222:225], v[112:115]
	v_mfma_f32_16x16x32_bf16 v[112:115], v[88:91], v[226:229], v[210:213]
	s_nop 0
	ds_read_b128 v[84:87], v116 offset:128
	ds_read_b128 v[206:209], v116 offset:192
	s_waitcnt lgkmcnt(1)
	v_mfma_f32_16x16x32_bf16 v[88:91], v[68:71], v[84:87], v[92:95]
	s_waitcnt vmcnt(1)
	v_mfma_f32_16x16x32_bf16 v[84:87], v[76:79], v[84:87], v[96:99]
	s_nop 0
	ds_read_b128 v[92:95], v116 offset:4480
	s_nop 0
	ds_read_b128 v[96:99], v116 offset:4544
	s_waitcnt lgkmcnt(1)
	v_mfma_f32_16x16x32_bf16 v[100:103], v[68:71], v[92:95], v[100:103]
	v_mfma_f32_16x16x32_bf16 v[104:107], v[76:79], v[92:95], v[104:107]
	ds_read_b128 v[92:95], v116 offset:8832
	ds_read_b128 v[210:213], v116 offset:8896
	s_waitcnt lgkmcnt(1)
	v_mfma_f32_16x16x32_bf16 v[108:111], v[68:71], v[92:95], v[108:111]
	v_mfma_f32_16x16x32_bf16 v[112:115], v[76:79], v[92:95], v[112:115]
	ds_read_b128 v[92:95], v116 offset:13184
	ds_read_b128 v[214:217], v116 offset:13248
	s_waitcnt lgkmcnt(1)
	v_mfma_f32_16x16x32_bf16 v[60:63], v[68:71], v[92:95], v[60:63]
	v_mfma_f32_16x16x32_bf16 v[218:221], v[76:79], v[92:95], v[80:83]
	v_mfma_f32_16x16x32_bf16 v[88:91], v[64:67], v[206:209], v[88:91]
	s_waitcnt vmcnt(0)
	v_mfma_f32_16x16x32_bf16 v[92:95], v[72:75], v[206:209], v[84:87]
	v_mfma_f32_16x16x32_bf16 v[80:83], v[64:67], v[96:99], v[100:103]
	v_mfma_f32_16x16x32_bf16 v[84:87], v[72:75], v[96:99], v[104:107]
	v_mfma_f32_16x16x32_bf16 v[68:71], v[64:67], v[210:213], v[108:111]
	v_mfma_f32_16x16x32_bf16 v[76:79], v[72:75], v[210:213], v[112:115]
	s_waitcnt lgkmcnt(0)
	v_mfma_f32_16x16x32_bf16 v[64:67], v[64:67], v[214:217], v[60:63]
	v_mfma_f32_16x16x32_bf16 v[60:63], v[72:75], v[214:217], v[218:221]
	s_or_b32 s54, s50, 1
	s_cmp_lt_i32 s54, 45
	s_mov_b64 s[58:59], -1
	s_cbranch_scc1 .LBB0_1763
	s_cmp_lt_u32 s54, 61
	s_cbranch_scc1 .LBB0_1760
	s_sub_i32 s38, s50, 60
	s_mov_b64 s[58:59], 0
	s_mov_b64 s[52:53], s[30:31]
	s_mov_b64 s[56:57], s[38:39]

.LBB0_1769:
	s_or_b64 exec, exec, s[8:9]
	v_sub_u32_e32 v53, 0, v179
	v_sub_u32_e32 v54, 0, v202
	v_add_f32_e32 v52, v52, v40
	v_add_u32_e32 v53, v176, v53
	v_sub_u32_e32 v55, 0, v203
	ds_write_b32 v53, v52 offset:32256
	v_add_f32_e32 v51, v51, v40
	v_add_u32_e32 v52, v176, v54
	v_sub_u32_e32 v56, 0, v206
	ds_write_b32 v52, v51 offset:32256
	v_add_f32_e32 v50, v50, v40
	v_add_u32_e32 v51, v176, v55
	v_sub_u32_e32 v57, 0, v207
	ds_write_b32 v51, v50 offset:32256
	v_add_f32_e32 v49, v49, v40
	v_add_u32_e32 v50, v176, v56
	v_sub_u32_e32 v58, 0, v208
	ds_write_b32 v50, v49 offset:32256
	v_add_f32_e32 v48, v48, v40
	v_add_u32_e32 v49, v176, v57
	v_sub_u32_e32 v59, 0, v209
	ds_write_b32 v49, v48 offset:32256
	v_add_f32_e32 v47, v47, v40
	v_add_u32_e32 v48, v176, v58
	v_sub_u32_e32 v127, 0, v210
	ds_write_b32 v48, v47 offset:32256
	v_add_f32_e32 v46, v46, v40
	v_add_u32_e32 v47, v176, v59
	v_sub_u32_e32 v179, 0, v211
	ds_write_b32 v47, v46 offset:32256
	v_add_f32_e32 v45, v45, v40
	v_add_u32_e32 v46, v176, v127
	v_sub_u32_e32 v180, 0, v212
	ds_write_b32 v46, v45 offset:32256
	v_add_f32_e32 v44, v44, v40
	v_add_u32_e32 v45, v176, v179
	v_sub_u32_e32 v181, 0, v213
	ds_write_b32 v45, v44 offset:32256
	v_add_f32_e32 v43, v43, v40
	v_add_u32_e32 v44, v176, v180
	v_sub_u32_e32 v182, 0, v214
	ds_write_b32 v44, v43 offset:32256
	v_add_f32_e32 v42, v42, v40
	v_add_u32_e32 v43, v176, v181
	v_sub_u32_e32 v202, 0, v215
	ds_write_b32 v43, v42 offset:32256
	v_add_f32_e32 v41, v41, v40
	v_add_u32_e32 v42, v176, v182
	v_sub_u32_e32 v203, 0, v216
	ds_write_b32 v42, v41 offset:32256
	v_add_f32_e32 v39, v39, v40
	v_add_u32_e32 v41, v176, v202
	v_sub_u32_e32 v206, 0, v217
	ds_write_b32 v41, v39 offset:32256
	v_add_f32_e32 v38, v38, v40
	v_add_u32_e32 v39, v176, v203
	v_sub_u32_e32 v207, 0, v218
	ds_write_b32 v39, v38 offset:32256
	v_add_f32_e32 v37, v37, v40
	v_add_u32_e32 v38, v176, v206
	ds_write_b32 v38, v37 offset:32256
	v_add_f32_e32 v36, v36, v40
	v_add_u32_e32 v37, v176, v207
	ds_write_b32 v37, v36 offset:32256
	s_waitcnt lgkmcnt(0)
	s_barrier
	ds_read_b128 v[36:39], v186
	ds_read_b128 v[40:43], v184 offset:15872
	ds_read_b128 v[44:47], v184 offset:15888
	ds_read_b128 v[48:51], v186 offset:16
	s_waitcnt lgkmcnt(2)
	v_sub_f32_e32 v53, v40, v36
	v_mul_f32_e32 v53, 0x3fb8aa3b, v53
	v_sub_f32_e32 v55, v41, v37
	v_sub_f32_e32 v52, v36, v40
	v_exp_f32_e32 v54, v53
	v_sub_f32_e32 v53, v37, v41
	v_mul_f32_e32 v55, 0x3fb8aa3b, v55
	v_mul_f32_e32 v36, 0x3fb8aa3b, v36
	v_mul_f32_e32 v37, 0x3fb8aa3b, v37
	v_sub_f32_e32 v57, v42, v38
	v_exp_f32_e32 v55, v55
	v_exp_f32_e32 v36, v36
	v_exp_f32_e32 v37, v37
	v_mul_f32_e32 v57, 0x3fb8aa3b, v57
	v_sub_f32_e32 v59, v43, v39
	v_sub_f32_e32 v56, v38, v42
	v_exp_f32_e32 v58, v57
	v_mul_f32_e32 v38, 0x3fb8aa3b, v38
	v_sub_f32_e32 v57, v39, v43
	v_mul_f32_e32 v59, 0x3fb8aa3b, v59
	v_mul_f32_e32 v39, 0x3fb8aa3b, v39
	v_exp_f32_e32 v38, v38
	v_exp_f32_e32 v59, v59
	v_exp_f32_e32 v39, v39
	v_pk_mul_f32 v[54:55], v[54:55], v[156:157]
	v_pk_mul_f32 v[156:157], v[158:159], v[36:37]
	s_waitcnt lgkmcnt(0)
	v_sub_f32_e32 v37, v44, v48
	v_mul_f32_e32 v37, 0x3fb8aa3b, v37
	v_pk_mul_f32 v[58:59], v[58:59], v[154:155]
	v_pk_mul_f32 v[154:155], v[162:163], v[38:39]
	v_sub_f32_e32 v36, v48, v44
	v_exp_f32_e32 v38, v37
	v_sub_f32_e32 v37, v49, v45
	v_mul_f32_e32 v52, 0x3fb8aa3b, v52
	v_mul_f32_e32 v53, 0x3fb8aa3b, v53
	v_mul_f32_e32 v36, 0x3fb8aa3b, v36
	v_mul_f32_e32 v37, 0x3fb8aa3b, v37
	v_exp_f32_e32 v52, v52
	v_exp_f32_e32 v53, v53
	v_exp_f32_e32 v36, v36
	v_exp_f32_e32 v37, v37
	v_sub_f32_e32 v39, v45, v49
	v_mul_f32_e32 v39, 0x3fb8aa3b, v39
	v_exp_f32_e32 v39, v39
	v_pk_mul_f32 v[52:53], v[158:159], v[52:53]
	v_pk_mul_f32 v[158:159], v[160:161], v[36:37]
	v_sub_f32_e32 v37, v46, v50
	v_mul_f32_e32 v37, 0x3fb8aa3b, v37
	v_pk_mul_f32 v[152:153], v[38:39], v[152:153]
	v_mul_f32_e32 v36, 0x3fb8aa3b, v49
	v_exp_f32_e32 v38, v37
	v_mul_f32_e32 v37, 0x3fb8aa3b, v50
	v_exp_f32_e32 v49, v36
	v_sub_f32_e32 v36, v50, v46
	v_exp_f32_e32 v50, v37
	v_sub_f32_e32 v37, v51, v47
	v_mul_f32_e32 v56, 0x3fb8aa3b, v56
	v_mul_f32_e32 v57, 0x3fb8aa3b, v57
	v_mul_f32_e32 v48, 0x3fb8aa3b, v48
	v_mul_f32_e32 v36, 0x3fb8aa3b, v36
	v_mul_f32_e32 v37, 0x3fb8aa3b, v37
	v_sub_f32_e32 v39, v47, v51
	v_exp_f32_e32 v56, v56
	v_exp_f32_e32 v57, v57
	v_exp_f32_e32 v48, v48
	v_exp_f32_e32 v36, v36
	v_exp_f32_e32 v37, v37
	v_mul_f32_e32 v39, 0x3fb8aa3b, v39
	v_exp_f32_e32 v39, v39
	v_mul_f32_e32 v51, 0x3fb8aa3b, v51
	v_exp_f32_e32 v51, v51
	v_pk_mul_f32 v[56:57], v[162:163], v[56:57]
	v_pk_mul_f32 v[48:49], v[160:161], v[48:49]
	v_pk_mul_f32 v[160:161], v[166:167], v[36:37]
	v_pk_mul_f32 v[150:151], v[38:39], v[150:151]
	v_cvt_pk_bf16_f32 v36, v52, v53
	v_cvt_pk_bf16_f32 v37, v56, v57
	v_cvt_pk_bf16_f32 v38, v158, v159
	v_cvt_pk_bf16_f32 v39, v160, v161
	v_pk_mul_f32 v[50:51], v[166:167], v[50:51]
	ds_write_b128 v183, v[36:39] offset:32768
	v_cvt_pk_bf16_f32 v36, v54, v55
	v_cvt_pk_bf16_f32 v37, v58, v59
	v_cvt_pk_bf16_f32 v38, v152, v153
	v_cvt_pk_bf16_f32 v39, v150, v151
	ds_write_b128 v183, v[36:39] offset:50176
	v_cvt_pk_bf16_f32 v36, v156, v157
	v_cvt_pk_bf16_f32 v37, v154, v155
	v_cvt_pk_bf16_f32 v38, v48, v49
	v_cvt_pk_bf16_f32 v39, v50, v51
	ds_write_b128 v8, v[36:39]
	ds_read_b128 v[36:39], v189
	ds_read_b128 v[48:51], v189 offset:16
	s_waitcnt lgkmcnt(1)
	v_sub_f32_e32 v52, v36, v40
	v_sub_f32_e32 v40, v40, v36
	v_sub_f32_e32 v53, v37, v41
	v_sub_f32_e32 v41, v41, v37
	v_mul_f32_e32 v36, 0x3fb8aa3b, v36
	v_mul_f32_e32 v37, 0x3fb8aa3b, v37
	v_exp_f32_e32 v36, v36
	v_exp_f32_e32 v37, v37
	v_sub_f32_e32 v54, v38, v42
	v_sub_f32_e32 v42, v42, v38
	v_mul_f32_e32 v38, 0x3fb8aa3b, v38
	v_sub_f32_e32 v55, v39, v43
	v_sub_f32_e32 v43, v43, v39
	v_mul_f32_e32 v39, 0x3fb8aa3b, v39
	v_exp_f32_e32 v38, v38
	v_exp_f32_e32 v39, v39
	v_pk_mul_f32 v[56:57], v[164:165], v[36:37]
	s_waitcnt lgkmcnt(0)
	v_sub_f32_e32 v37, v44, v48
	v_mul_f32_e32 v37, 0x3fb8aa3b, v37
	v_pk_mul_f32 v[58:59], v[170:171], v[38:39]
	v_sub_f32_e32 v36, v48, v44
	v_exp_f32_e32 v38, v37
	v_sub_f32_e32 v37, v49, v45
	v_mul_f32_e32 v42, 0x3fb8aa3b, v42
	v_mul_f32_e32 v43, 0x3fb8aa3b, v43
	v_mul_f32_e32 v36, 0x3fb8aa3b, v36
	v_mul_f32_e32 v37, 0x3fb8aa3b, v37
	v_exp_f32_e32 v42, v42
	v_exp_f32_e32 v43, v43
	v_exp_f32_e32 v36, v36
	v_exp_f32_e32 v37, v37
	v_sub_f32_e32 v39, v45, v49
	v_mul_f32_e32 v39, 0x3fb8aa3b, v39
	v_exp_f32_e32 v39, v39
	v_pk_mul_f32 v[42:43], v[42:43], v[146:147]
	v_pk_mul_f32 v[146:147], v[168:169], v[36:37]
	v_sub_f32_e32 v37, v46, v50
	v_mul_f32_e32 v37, 0x3fb8aa3b, v37
	v_pk_mul_f32 v[144:145], v[38:39], v[144:145]
	v_mul_f32_e32 v36, 0x3fb8aa3b, v49
	v_exp_f32_e32 v38, v37
	v_mul_f32_e32 v37, 0x3fb8aa3b, v50
	v_exp_f32_e32 v45, v36
	v_sub_f32_e32 v36, v50, v46
	v_exp_f32_e32 v46, v37
	v_sub_f32_e32 v37, v51, v47
	v_mul_f32_e32 v52, 0x3fb8aa3b, v52
	v_mul_f32_e32 v53, 0x3fb8aa3b, v53
	v_mul_f32_e32 v54, 0x3fb8aa3b, v54
	v_mul_f32_e32 v55, 0x3fb8aa3b, v55
	v_mul_f32_e32 v36, 0x3fb8aa3b, v36
	v_mul_f32_e32 v37, 0x3fb8aa3b, v37
	v_sub_f32_e32 v39, v47, v51
	v_exp_f32_e32 v52, v52
	v_mul_f32_e32 v40, 0x3fb8aa3b, v40
	v_exp_f32_e32 v53, v53
	v_mul_f32_e32 v41, 0x3fb8aa3b, v41
	v_exp_f32_e32 v54, v54
	v_exp_f32_e32 v55, v55
	v_exp_f32_e32 v36, v36
	v_exp_f32_e32 v37, v37
	v_mul_f32_e32 v39, 0x3fb8aa3b, v39
	v_exp_f32_e32 v40, v40
	v_exp_f32_e32 v41, v41
	v_mul_f32_e32 v44, 0x3fb8aa3b, v48
	v_exp_f32_e32 v39, v39
	v_mul_f32_e32 v47, 0x3fb8aa3b, v51
	v_exp_f32_e32 v44, v44
	v_exp_f32_e32 v47, v47
	v_pk_mul_f32 v[52:53], v[164:165], v[52:53]
	v_pk_mul_f32 v[54:55], v[170:171], v[54:55]
	v_pk_mul_f32 v[48:49], v[172:173], v[36:37]
	v_pk_mul_f32 v[40:41], v[40:41], v[148:149]
	v_pk_mul_f32 v[50:51], v[38:39], v[142:143]
	v_cvt_pk_bf16_f32 v36, v52, v53
	v_cvt_pk_bf16_f32 v37, v54, v55
	v_cvt_pk_bf16_f32 v38, v146, v147
	v_cvt_pk_bf16_f32 v39, v48, v49
	v_pk_mul_f32 v[44:45], v[168:169], v[44:45]
	v_pk_mul_f32 v[46:47], v[172:173], v[46:47]
	ds_write_b128 v183, v[36:39] offset:41472
	v_cvt_pk_bf16_f32 v36, v40, v41
	v_cvt_pk_bf16_f32 v37, v42, v43
	v_cvt_pk_bf16_f32 v38, v144, v145
	v_cvt_pk_bf16_f32 v39, v50, v51
	ds_write_b128 v183, v[36:39] offset:58880
	v_cvt_pk_bf16_f32 v36, v56, v57
	v_cvt_pk_bf16_f32 v37, v58, v59
	v_cvt_pk_bf16_f32 v38, v44, v45
	v_cvt_pk_bf16_f32 v39, v46, v47
	ds_write_b128 v8, v[36:39] offset:8704
	s_waitcnt lgkmcnt(0)
	s_barrier
	ds_read_b128 v[36:39], v190 offset:50176
	ds_read_b128 v[40:43], v191 offset:32768
	ds_read_b128 v[44:47], v191 offset:32832
	ds_read_b128 v[48:51], v190 offset:50240
	s_waitcnt lgkmcnt(2)
	v_mfma_f32_16x16x32_bf16 v[36:39], v[36:39], v[40:43], 0
	ds_read_b128 v[52:55], v190 offset:54528
	ds_read_b128 v[56:59], v190 offset:54592
	v_mul_u32_u24_e32 v8, 0x90, v131
	v_add_u32_e32 v8, v188, v8
	s_waitcnt lgkmcnt(2)
	v_mfma_f32_16x16x32_bf16 v[36:39], v[48:51], v[44:47], v[36:39]
	ds_read_b128 v[48:51], v190 offset:50304
	s_waitcnt lgkmcnt(2)
	v_mfma_f32_16x16x32_bf16 v[40:43], v[52:55], v[40:43], 0
	s_waitcnt lgkmcnt(1)
	v_mfma_f32_16x16x32_bf16 v[40:43], v[56:59], v[44:47], v[40:43]
	ds_read_b128 v[44:47], v191 offset:32896
	ds_read_b128 v[52:55], v191 offset:32960
	ds_read_b128 v[56:59], v190 offset:50368
	s_waitcnt lgkmcnt(2)
	v_mfma_f32_16x16x32_bf16 v[36:39], v[48:51], v[44:47], v[36:39]
	ds_read_b128 v[48:51], v190 offset:54656
	ds_read_b128 v[142:145], v190 offset:54720
	s_waitcnt lgkmcnt(1)
	v_mfma_f32_16x16x32_bf16 v[40:43], v[48:51], v[44:47], v[40:43]
	v_or_b32_e32 v45, 1, v192
	v_cmp_le_i32_e32 vcc, v187, v45
	v_mul_u32_u24_e32 v44, 0x220, v194
	v_mfma_f32_16x16x32_bf16 v[36:39], v[56:59], v[52:55], v[36:39]
	v_add_u32_e32 v127, v185, v44
	s_waitcnt lgkmcnt(0)
	v_mfma_f32_16x16x32_bf16 v[40:43], v[142:145], v[52:55], v[40:43]
	s_nop 4
	v_cndmask_b32_e32 v37, 0, v37, vcc
	v_cmp_le_i32_e32 vcc, v187, v195
	v_cndmask_b32_e64 v36, v36, 0, s[14:15]
	v_cvt_pk_bf16_f32 v36, v36, v37
	v_cndmask_b32_e32 v38, 0, v38, vcc
	v_cmp_le_i32_e32 vcc, v187, v196
	s_nop 1
	v_cndmask_b32_e32 v39, 0, v39, vcc
	v_cmp_le_i32_e32 vcc, v187, v197
	v_cvt_pk_bf16_f32 v37, v38, v39
	s_nop 0
	v_cndmask_b32_e32 v38, 0, v40, vcc
	v_cmp_le_i32_e32 vcc, v187, v198
	s_nop 1
	v_cndmask_b32_e32 v39, 0, v41, vcc
	v_cmp_le_i32_e32 vcc, v187, v200
	v_cvt_pk_bf16_f32 v38, v38, v39
	s_nop 0
	v_cndmask_b32_e32 v40, 0, v42, vcc
	v_cmp_le_i32_e32 vcc, v187, v201
	s_nop 1
	v_cndmask_b32_e32 v41, 0, v43, vcc
	v_cvt_pk_bf16_f32 v39, v40, v41
	ds_write2_b64 v193, v[36:37], v[38:39] offset1:4
	s_waitcnt lgkmcnt(0)
	s_barrier
	ds_read_b64_tr_b16 v[38:39], v127 offset:2176
	ds_read_b64_tr_b16 v[36:37], v127
	ds_read_b64_tr_b16 v[42:43], v127 offset:2184
	ds_read_b64_tr_b16 v[40:41], v127 offset:8
	ds_read_b128 v[44:47], v8
	ds_read_b128 v[48:51], v8 offset:64
	s_waitcnt lgkmcnt(1)
	v_mfma_f32_16x16x32_bf16 v[52:55], v[36:39], v[44:47], v[88:91]
	ds_read_b128 v[56:59], v8 offset:2304
	s_nop 1
	ds_read_b128 v[88:91], v8 offset:2368
	v_mfma_f32_16x16x32_bf16 v[44:47], v[40:43], v[44:47], v[92:95]
	s_waitcnt lgkmcnt(1)
	v_mfma_f32_16x16x32_bf16 v[80:83], v[36:39], v[56:59], v[80:83]
	v_mfma_f32_16x16x32_bf16 v[56:59], v[40:43], v[56:59], v[84:87]
	s_nop 2
	ds_read_b128 v[84:87], v8 offset:4608
	ds_read_b128 v[92:95], v8 offset:4672
	s_waitcnt lgkmcnt(1)
	v_mfma_f32_16x16x32_bf16 v[68:71], v[36:39], v[84:87], v[68:71]
	v_mfma_f32_16x16x32_bf16 v[76:79], v[40:43], v[84:87], v[76:79]
	ds_read_b128 v[84:87], v8 offset:6912
	ds_read_b128 v[142:145], v8 offset:6976
	v_mul_u32_u24_e32 v8, 0x110, v131
	v_add_u32_e32 v8, v199, v8
	s_waitcnt lgkmcnt(1)
	v_mfma_f32_16x16x32_bf16 v[36:39], v[36:39], v[84:87], v[64:67]
	s_nop 2
	ds_read_b64_tr_b16 v[64:65], v127 offset:17408
	ds_read_b64_tr_b16 v[66:67], v127 offset:19584
	v_mfma_f32_16x16x32_bf16 v[40:43], v[40:43], v[84:87], v[60:63]
	s_nop 2
	ds_read_b64_tr_b16 v[62:63], v127 offset:19592
	ds_read_b64_tr_b16 v[60:61], v127 offset:17416
	s_waitcnt lgkmcnt(2)
	v_mfma_f32_16x16x32_bf16 v[52:55], v[64:67], v[48:51], v[52:55]
	s_waitcnt lgkmcnt(0)
	v_mfma_f32_16x16x32_bf16 v[44:47], v[60:63], v[48:51], v[44:47]
	v_mfma_f32_16x16x32_bf16 v[48:51], v[64:67], v[88:91], v[80:83]
	v_mfma_f32_16x16x32_bf16 v[56:59], v[60:63], v[88:91], v[56:59]
	v_mfma_f32_16x16x32_bf16 v[68:71], v[64:67], v[92:95], v[68:71]
	v_mfma_f32_16x16x32_bf16 v[76:79], v[60:63], v[92:95], v[76:79]
	v_mfma_f32_16x16x32_bf16 v[36:39], v[64:67], v[142:145], v[36:39]
	v_mfma_f32_16x16x32_bf16 v[40:43], v[60:63], v[142:145], v[40:43]
	ds_read_b128 v[60:63], v8
	ds_read_b128 v[64:67], v8 offset:64
	s_waitcnt vmcnt(7) lgkmcnt(1)
	v_mfma_f32_16x16x32_bf16 v[52:55], v[116:119], v[60:63], v[52:55]
	s_waitcnt vmcnt(3)
	v_mfma_f32_16x16x32_bf16 v[44:47], v[120:123], v[60:63], v[44:47]
	ds_read_b128 v[60:63], v8 offset:4352
	ds_read_b128 v[80:83], v8 offset:4416
	s_waitcnt lgkmcnt(1)
	v_mfma_f32_16x16x32_bf16 v[48:51], v[116:119], v[60:63], v[48:51]
	v_mfma_f32_16x16x32_bf16 v[56:59], v[120:123], v[60:63], v[56:59]
	ds_read_b128 v[60:63], v8 offset:8704
	ds_read_b128 v[84:87], v8 offset:8768
	s_waitcnt lgkmcnt(1)
	v_mfma_f32_16x16x32_bf16 v[68:71], v[116:119], v[60:63], v[68:71]
	v_mfma_f32_16x16x32_bf16 v[60:63], v[120:123], v[60:63], v[76:79]
	s_nop 2
	ds_read_b128 v[76:79], v8 offset:13056
	ds_read_b128 v[88:91], v8 offset:13120
	s_waitcnt lgkmcnt(1)
	v_mfma_f32_16x16x32_bf16 v[36:39], v[116:119], v[76:79], v[36:39]
	v_mfma_f32_16x16x32_bf16 v[40:43], v[120:123], v[76:79], v[40:43]
	v_mfma_f32_16x16x32_bf16 v[52:55], v[108:111], v[64:67], v[52:55]
	s_waitcnt vmcnt(2)
	v_mfma_f32_16x16x32_bf16 v[44:47], v[112:115], v[64:67], v[44:47]
	v_mfma_f32_16x16x32_bf16 v[48:51], v[108:111], v[80:83], v[48:51]
	v_mfma_f32_16x16x32_bf16 v[56:59], v[112:115], v[80:83], v[56:59]
	v_mfma_f32_16x16x32_bf16 v[64:67], v[108:111], v[84:87], v[68:71]
	v_mfma_f32_16x16x32_bf16 v[60:63], v[112:115], v[84:87], v[60:63]
	s_waitcnt lgkmcnt(0)
	v_mfma_f32_16x16x32_bf16 v[36:39], v[108:111], v[88:91], v[36:39]
	v_mfma_f32_16x16x32_bf16 v[40:43], v[112:115], v[88:91], v[40:43]
	ds_read_b128 v[68:71], v8 offset:128
	ds_read_b128 v[76:79], v8 offset:192
	s_waitcnt lgkmcnt(1)
	v_mfma_f32_16x16x32_bf16 v[52:55], v[100:103], v[68:71], v[52:55]
	s_waitcnt vmcnt(1)
	v_mfma_f32_16x16x32_bf16 v[44:47], v[104:107], v[68:71], v[44:47]
	ds_read_b128 v[68:71], v8 offset:4480
	ds_read_b128 v[84:87], v8 offset:4544
	s_waitcnt lgkmcnt(1)
	v_mfma_f32_16x16x32_bf16 v[48:51], v[100:103], v[68:71], v[48:51]
	v_mfma_f32_16x16x32_bf16 v[56:59], v[104:107], v[68:71], v[56:59]
	ds_read_b128 v[68:71], v8 offset:8832
	ds_read_b128 v[88:91], v8 offset:8896
	s_waitcnt lgkmcnt(1)
	v_mfma_f32_16x16x32_bf16 v[92:95], v[100:103], v[68:71], v[64:67]
	v_mfma_f32_16x16x32_bf16 v[68:71], v[104:107], v[68:71], v[60:63]
	s_nop 2
	ds_read_b128 v[60:63], v8 offset:13184
	ds_read_b128 v[108:111], v8 offset:13248
	s_waitcnt lgkmcnt(1)
	v_mfma_f32_16x16x32_bf16 v[36:39], v[100:103], v[60:63], v[36:39]
	v_mfma_f32_16x16x32_bf16 v[100:103], v[104:107], v[60:63], v[40:43]
	v_mfma_f32_16x16x32_bf16 v[80:83], v[72:75], v[76:79], v[52:55]
	s_waitcnt vmcnt(0)
	v_mfma_f32_16x16x32_bf16 v[76:79], v[96:99], v[76:79], v[44:47]
	v_mfma_f32_16x16x32_bf16 v[64:67], v[72:75], v[84:87], v[48:51]
	v_mfma_f32_16x16x32_bf16 v[60:63], v[96:99], v[84:87], v[56:59]
	v_mfma_f32_16x16x32_bf16 v[52:55], v[72:75], v[88:91], v[92:95]
	v_mfma_f32_16x16x32_bf16 v[48:51], v[96:99], v[88:91], v[68:71]
	s_waitcnt lgkmcnt(0)
	v_mfma_f32_16x16x32_bf16 v[40:43], v[72:75], v[108:111], v[36:39]
	v_mfma_f32_16x16x32_bf16 v[36:39], v[96:99], v[108:111], v[100:103]
	s_cmpk_gt_i32 s47, 0x3ff
	s_cbranch_scc1 .Lgca_skip
	s_ashr_i32 s61, s47, 8
	s_add_i32 s61, s61, 4
	s_lshl_b32 s61, s61, 12
	s_and_b32 s62, s47, 63
	s_lshl_b32 s62, s62, 6
	s_or_b32 s61, s61, s62
	s_bfe_u32 s62, s47, 0x20006
	s_lshl_b32 s63, s62, 7
	s_mov_b32 s66, s20
	s_mov_b32 s67, 0
	v_and_b32_e32 v230, 48, v204
	v_mov_b32_e32 v231, 0
	v_and_b32_e32 v232, 15, v204
	v_mov_b64_e32 v[234:235], s[16:17]
	v_or_b32_e32 v233, s61, v232
	v_mad_u64_u32 v[236:237], s[64:65], v233, s0, v[234:235]
	v_lshl_add_u64 v[236:237], v[236:237], 0, v[230:231]
	v_lshl_add_u64 v[236:237], v[236:237], 0, s[66:67]
	global_load_dwordx4 v[206:209], v[236:237], off offset:2048
	v_or_b32_e32 v233, 16, v232
	v_or_b32_e32 v233, s61, v233
	v_mad_u64_u32 v[236:237], s[64:65], v233, s0, v[234:235]
	v_lshl_add_u64 v[236:237], v[236:237], 0, v[230:231]
	v_lshl_add_u64 v[236:237], v[236:237], 0, s[66:67]
	global_load_dwordx4 v[210:213], v[236:237], off offset:2048
	v_or_b32_e32 v233, 32, v232
	v_or_b32_e32 v233, s61, v233
	v_mad_u64_u32 v[236:237], s[64:65], v233, s0, v[234:235]
	v_lshl_add_u64 v[236:237], v[236:237], 0, v[230:231]
	v_lshl_add_u64 v[236:237], v[236:237], 0, s[66:67]
	global_load_dwordx4 v[214:217], v[236:237], off offset:2048
	v_or_b32_e32 v233, 48, v232
	v_or_b32_e32 v233, s61, v233
	v_mad_u64_u32 v[236:237], s[64:65], v233, s0, v[234:235]
	v_lshl_add_u64 v[236:237], v[236:237], 0, v[230:231]
	v_lshl_add_u64 v[236:237], v[236:237], 0, s[66:67]
	global_load_dwordx4 v[218:221], v[236:237], off offset:2048
	v_lshrrev_b32_e32 v233, 6, v204
	v_lshlrev_b32_e32 v233, 4, v233
	v_or_b32_e32 v236, s63, v232
	v_add_u32_e32 v236, v236, v233
	v_lshlrev_b32_e32 v236, 5, v236
	v_and_b32_e32 v233, 16, v204
	v_add_u32_e32 v236, v236, v233
	v_mov_b32_e32 v237, 0
	v_lshl_add_u64 v[236:237], v[236:237], 0, s[18:19]
	v_mov_b32_e32 v222, 0
	v_mov_b32_e32 v223, 0
	v_mov_b32_e32 v224, 0
	v_mov_b32_e32 v225, 0
	v_and_b32_e32 v233, 63, v204
	v_cmp_gt_u32_e32 vcc, 32, v233
	s_and_saveexec_b64 s[70:71], vcc
	global_load_dwordx4 v[222:225], v[236:237], off
	s_or_b64 exec, exec, s[70:71]
	s_lshl_b32 s63, s63, 2
	s_add_u32 s74, s24, s63
	s_addc_u32 s75, s25, 0
	v_lshrrev_b32_e32 v233, 6, v204
	v_lshlrev_b32_e32 v236, 6, v233
	v_bfe_u32 v233, v204, 4, 2
	v_lshl_add_u32 v236, v233, 4, v236
	v_mov_b32_e32 v237, 0
	v_lshl_add_u64 v[236:237], v[236:237], 0, s[74:75]
	global_load_dwordx4 v[226:229], v[236:237], off
.Lgca_skip:
	v_or_b32_e32 v84, v175, v132
	v_ashrrev_i32_e32 v85, 31, v84
	s_lshl_b32 s38, s60, 9
	v_lshl_add_u64 v[44:45], v[134:135], 0, s[38:39]
	v_lshlrev_b64 v[46:47], 1, v[84:85]
	v_lshl_add_u64 v[44:45], v[44:45], 0, v[46:47]
	v_add_co_u32_e32 v44, vcc, s20, v44
	v_lshl_add_u64 v[56:57], v[136:137], 0, s[38:39]
	s_nop 0
	v_addc_co_u32_e32 v45, vcc, 0, v45, vcc
	v_lshl_add_u64 v[56:57], v[56:57], 0, v[46:47]
	v_add_co_u32_e32 v56, vcc, s20, v56
	v_and_b32_e32 v86, 64, v205
	s_nop 0
	v_addc_co_u32_e32 v57, vcc, 0, v57, vcc
	global_load_dwordx4 v[72:75], v[44:45], off
	global_load_dwordx4 v[68:71], v[56:57], off
	v_lshl_add_u64 v[44:45], v[138:139], 0, s[38:39]
	v_lshl_add_u64 v[44:45], v[44:45], 0, v[46:47]
	v_add_co_u32_e32 v44, vcc, s20, v44
	v_lshl_add_u64 v[56:57], v[140:141], 0, s[38:39]
	s_nop 0
	v_addc_co_u32_e32 v45, vcc, 0, v45, vcc
	v_lshl_add_u64 v[46:47], v[56:57], 0, v[46:47]
	v_add_co_u32_e32 v46, vcc, s20, v46
	v_xor_b32_e32 v8, 16, v205
	s_nop 0
	v_addc_co_u32_e32 v47, vcc, 0, v47, vcc
	global_load_dwordx4 v[56:59], v[44:45], off
	s_nop 0
	global_load_dwordx4 v[44:47], v[46:47], off
	v_add_u32_e32 v86, 64, v86
	v_cmp_lt_i32_e32 vcc, v8, v86
	v_xor_b32_e32 v88, 32, v205
	s_nop 0
	v_cndmask_b32_e32 v8, v205, v8, vcc
	v_lshlrev_b32_e32 v175, 2, v8
	v_mul_f32_e32 v8, v81, v81
	v_fmac_f32_e32 v8, v80, v80
	v_fmac_f32_e32 v8, v82, v82
	v_fmac_f32_e32 v8, v83, v83
	v_fmac_f32_e32 v8, v76, v76
	v_fmac_f32_e32 v8, v77, v77
	v_fmac_f32_e32 v8, v78, v78
	v_fmac_f32_e32 v8, v79, v79
	ds_bpermute_b32 v87, v175, v8
	v_cmp_lt_i32_e32 vcc, v88, v86
	s_nop 1
	v_cndmask_b32_e32 v86, v205, v88, vcc
	v_lshlrev_b32_e32 v176, 2, v86
	s_waitcnt lgkmcnt(0)
	v_add_f32_e32 v86, v8, v87
	ds_bpermute_b32 v87, v176, v86
	v_lshlrev_b32_e32 v8, 2, v178
	v_lshlrev_b32_e32 v88, 2, v131
	v_cmp_gt_u32_e32 vcc, 16, v133
	v_add3_u32 v8, s96, v8, v88
	s_and_saveexec_b64 s[8:9], vcc
	s_cbranch_execz .LBB0_1771
	s_waitcnt lgkmcnt(0)
	v_add_f32_e32 v86, v86, v87
	ds_write_b32 v8, v86

.LBB0_1780:
	s_ashr_i32 s2, s47, 8
	s_add_i32 s10, s2, 4
	s_and_b32 s55, s47, 63
	s_ashr_i32 s11, s10, 31
	s_bfe_u32 s49, s47, 0x20006
	v_mov_b32_e32 v187, v204
	s_lshl_b64 s[8:9], s[10:11], 12
	s_lshl_b32 s2, s55, 6
	s_or_b32 s8, s8, s2
	v_lshlrev_b32_e32 v8, 3, v187
	s_lshl_b32 s11, s49, 7
	s_lshl_b32 s2, s49, 8
	v_and_b32_e32 v158, 0x78, v8
	v_ashrrev_i32_e32 v168, 4, v187
	s_add_u32 s12, s16, s2
	s_addc_u32 s13, s17, 0
	v_lshlrev_b32_e32 v8, 1, v158
	v_ashrrev_i32_e32 v169, 31, v168
	v_lshl_add_u64 v[10:11], s[12:13], 0, v[8:9]
	v_lshl_add_u64 v[36:37], s[8:9], 0, v[168:169]
	v_add_u32_e32 v164, 32, v168
	v_mad_u64_u32 v[38:39], s[12:13], v36, s0, v[10:11]
	v_ashrrev_i32_e32 v165, 31, v164
	v_mad_i32_i24 v39, v37, s0, v39
	v_lshl_add_u64 v[36:37], s[8:9], 0, v[164:165]
	v_mad_u64_u32 v[10:11], s[12:13], v36, s0, v[10:11]
	v_and_b32_e32 v131, 15, v187
	v_mad_i32_i24 v11, v37, s0, v11
	global_load_dwordx4 v[96:99], v[38:39], off
	global_load_dwordx4 v[104:107], v[38:39], off offset:1024
	global_load_dwordx4 v[60:63], v[10:11], off
	global_load_dwordx4 v[100:103], v[10:11], off offset:1024
	v_or_b32_e32 v10, s8, v131
	v_mov_b64_e32 v[36:37], s[16:17]
	v_mad_u64_u32 v[134:135], s[12:13], v10, s0, v[36:37]
	v_or_b32_e32 v129, 16, v131
	v_mad_i32_i24 v135, s9, v174, v135
	v_and_b32_e32 v116, 48, v187
	v_mov_b32_e32 v117, v9
	v_or_b32_e32 v130, s8, v129
	v_lshl_add_u64 v[38:39], v[134:135], 0, v[116:117]
	v_mad_u64_u32 v[136:137], s[12:13], v130, s0, v[36:37]
	v_or_b32_e32 v177, 32, v131
	v_add_co_u32_e32 v38, vcc, s20, v38
	v_mad_i32_i24 v137, s9, v174, v137
	v_or_b32_e32 v128, s8, v177
	v_addc_co_u32_e32 v39, vcc, 0, v39, vcc
	v_lshl_add_u64 v[40:41], v[136:137], 0, v[116:117]
	v_mad_u64_u32 v[138:139], s[12:13], v128, s0, v[36:37]
	v_or_b32_e32 v125, 48, v131
	v_add_co_u32_e32 v40, vcc, s20, v40
	v_mad_i32_i24 v139, s9, v174, v139
	v_or_b32_e32 v124, s8, v125
	v_addc_co_u32_e32 v41, vcc, 0, v41, vcc
	global_load_dword v239, v[38:39], off offset:2048
	v_mov_b32_e32 v56, v206
	v_mov_b32_e32 v57, v207
	v_mov_b32_e32 v58, v208
	v_mov_b32_e32 v59, v209
	global_load_dword v239, v[40:41], off offset:2048
	v_mov_b32_e32 v52, v210
	v_mov_b32_e32 v53, v211
	v_mov_b32_e32 v54, v212
	v_mov_b32_e32 v55, v213
	v_lshl_add_u64 v[38:39], v[138:139], 0, v[116:117]
	v_mad_u64_u32 v[140:141], s[12:13], v124, s0, v[36:37]
	v_add_co_u32_e32 v38, vcc, s20, v38
	v_mad_i32_i24 v141, s9, v174, v141
	s_nop 0
	v_addc_co_u32_e32 v39, vcc, 0, v39, vcc
	v_lshl_add_u64 v[36:37], v[140:141], 0, v[116:117]
	v_add_co_u32_e32 v36, vcc, s20, v36
	v_ashrrev_i32_e32 v66, 6, v187
	s_nop 0
	v_addc_co_u32_e32 v37, vcc, 0, v37, vcc
	global_load_dword v239, v[38:39], off offset:2048
	v_mov_b32_e32 v44, v214
	v_mov_b32_e32 v45, v215
	v_mov_b32_e32 v46, v216
	v_mov_b32_e32 v47, v217
	s_nop 0
	global_load_dword v239, v[36:37], off offset:2048
	v_mov_b32_e32 v36, v218
	v_mov_b32_e32 v37, v219
	v_mov_b32_e32 v38, v220
	v_mov_b32_e32 v39, v221
	v_lshlrev_b32_e32 v122, 4, v66
	v_or_b32_e32 v40, s11, v131
	v_and_b32_e32 v133, 63, v187
	v_add_u32_e32 v48, v40, v122
	v_and_b32_e32 v40, 16, v187
	v_mov_b32_e32 v41, v9
	v_mov_b32_e32 v11, s9
	v_lshl_add_u64 v[50:51], s[18:19], 0, v[40:41]
	v_cmp_lt_u32_e32 vcc, 31, v133
	v_cmp_gt_u32_e64 s[8:9], 32, v133
	v_mov_b32_e32 v40, 0
	v_ashrrev_i32_e32 v49, 31, v48
	v_mov_b32_e32 v108, 0
	v_mov_b32_e32 v109, 0
	v_mov_b32_e32 v110, 0
	v_mov_b32_e32 v111, 0
	s_and_saveexec_b64 s[12:13], s[8:9]
	s_cbranch_execz .LBB0_1782
	v_lshlrev_b64 v[42:43], 5, v[48:49]
	v_lshl_add_u64 v[42:43], v[50:51], 0, v[42:43]
	global_load_dword v239, v[42:43], off
	v_mov_b32_e32 v108, v222
	v_mov_b32_e32 v109, v223
	v_mov_b32_e32 v110, v224
	v_mov_b32_e32 v111, v225
.LBB0_1782:
	s_or_b64 exec, exec, s[12:13]
	s_lshl_b32 s8, s11, 2
	s_add_u32 s8, s24, s8
	v_bfe_u32 v117, v187, 4, 2
	s_addc_u32 s9, s25, 0
	v_ashrrev_i32_e32 v123, 31, v122
	v_lshl_add_u64 v[42:43], v[122:123], 2, s[8:9]
	v_lshlrev_b32_e32 v64, 4, v117
	v_mov_b32_e32 v65, v9
	v_lshl_add_u64 v[64:65], v[42:43], 0, v[64:65]
	global_load_dword v239, v[64:65], off
	v_mov_b32_e32 v112, v226
	v_mov_b32_e32 v113, v227
	v_mov_b32_e32 v114, v228
	v_mov_b32_e32 v115, v229
	v_mov_b32_e32 v41, 0
	v_mov_b32_e32 v42, 0
	v_mov_b32_e32 v43, 0
	s_and_saveexec_b64 s[8:9], vcc
	s_cbranch_execz .LBB0_1784
	v_lshlrev_b64 v[40:41], 5, v[48:49]
	v_lshl_add_u64 v[40:41], v[50:51], 0, v[40:41]
	v_add_co_u32_e32 v40, vcc, 0x4000, v40
	s_nop 1
	v_addc_co_u32_e32 v41, vcc, 0, v41, vcc
	global_load_dwordx4 v[40:43], v[40:41], off

.LBB0_1792:
	v_lshlrev_b32_e32 v64, 1, v131
	v_lshlrev_b32_e32 v132, 5, v66
	v_and_b32_e32 v64, 24, v64
	v_and_b32_e32 v65, 3, v187
	s_lshl_b64 s[12:13], s[12:13], 22
	v_or3_b32 v72, v65, v64, v132
	s_add_u32 s10, s10, s12
	s_addc_u32 s11, s11, s13
	s_lshl_b32 s12, s55, 16
	v_ashrrev_i32_e32 v73, 31, v72
	v_lshlrev_b32_e32 v179, 3, v117
	v_lshlrev_b32_e32 v64, 9, v131
	v_and_b32_e32 v178, 0xffffffc0, v187
	s_add_u32 s10, s10, s12
	v_lshlrev_b64 v[118:119], 8, v[72:73]
	v_or_b32_e32 v72, 4, v72
	v_add3_u32 v148, 0, v64, v178
	v_lshlrev_b32_e32 v64, 2, v187
	s_addc_u32 s11, s11, 0
	v_lshlrev_b32_e32 v126, 1, v179
	v_mov_b32_e32 v127, v9
	v_ashrrev_i32_e32 v73, 31, v72
	v_and_b32_e32 v65, 0x1fc, v64
	v_lshl_add_u64 v[74:75], s[10:11], 0, v[126:127]
	v_lshlrev_b64 v[120:121], 8, v[72:73]
	v_add_u32_e32 v180, 0, v65
	v_add_u32_e32 v183, s92, v64
	v_add_u32_e32 v182, s92, v65
	v_lshl_add_u64 v[64:65], v[74:75], 0, v[118:119]
	v_lshl_add_u64 v[72:73], v[74:75], 0, v[120:121]
	global_load_dwordx4 v[84:87], v[64:65], off
	global_load_dwordx4 v[80:83], v[64:65], off offset:64
	global_load_dwordx4 v[68:71], v[64:65], off offset:128
	s_nop 0
	global_load_dwordx4 v[64:67], v[64:65], off offset:192
	s_nop 0
	global_load_dwordx4 v[92:95], v[72:73], off
	global_load_dwordx4 v[88:91], v[72:73], off offset:64
	global_load_dwordx4 v[76:79], v[72:73], off offset:128
	s_nop 0
	global_load_dwordx4 v[72:75], v[72:73], off offset:192
	s_nop 0
	v_mfma_f32_16x16x32_bf16 v[142:145], v[108:111], v[56:59], 0
	v_add_u32_e32 v184, v148, v116
	v_ashrrev_i32_e32 v123, 7, v187
	v_lshlrev_b32_e32 v181, 13, v123
	v_cmp_lt_i32_e64 s[8:9], 0, v123
	v_mov_b32_e32 v169, 0
	s_nop 0
	s_nop 1
	v_add_f32_e32 v127, v112, v142
	v_add_f32_e32 v143, v113, v143
	v_add_f32_e32 v147, v114, v144
	v_min_f32_e32 v142, 0, v127
	v_mul_f32_e64 v127, |v127|, s33
	v_mul_f32_e64 v146, |v143|, s33
	v_min_f32_e32 v144, 0, v147
	v_mul_f32_e64 v147, |v147|, s33
	v_add_f32_e32 v145, v115, v145
	v_exp_f32_e32 v127, v127
	v_exp_f32_e32 v146, v146
	v_exp_f32_e32 v147, v147
	v_mul_f32_e64 v149, |v145|, s33
	v_exp_f32_e32 v149, v149
	v_add_f32_e32 v127, 1.0, v127
	v_add_f32_e32 v146, 1.0, v146
	v_add_f32_e32 v147, 1.0, v147
	v_log_f32_e32 v127, v127
	v_log_f32_e32 v146, v146
	v_log_f32_e32 v150, v147
	v_add_f32_e32 v147, 1.0, v149
	v_log_f32_e32 v149, v147
	v_min_f32_e32 v143, 0, v143
	v_xor_b32_e32 v147, 0x80000000, v146
	v_xor_b32_e32 v146, 0x80000000, v127
	v_min_f32_e32 v145, 0, v145
	v_pk_fma_f32 v[142:143], v[146:147], s[40:41], v[142:143] op_sel_hi:[1,0,1]
	v_xor_b32_e32 v147, 0x80000000, v149
	v_xor_b32_e32 v146, 0x80000000, v150
	v_pk_fma_f32 v[144:145], v[146:147], s[40:41], v[144:145] op_sel_hi:[1,0,1]
	v_pk_mul_f32 v[142:143], v[142:143], s[42:43] op_sel_hi:[1,0]
	v_pk_mul_f32 v[144:145], v[144:145], s[42:43] op_sel_hi:[1,0]
	ds_write_b128 v184, v[142:145]
	v_mfma_f32_16x16x32_bf16 v[142:145], v[108:111], v[52:55], 0
	s_nop 7
	v_add_f32_e32 v127, v112, v142
	v_add_f32_e32 v143, v113, v143
	v_add_f32_e32 v147, v114, v144
	v_min_f32_e32 v142, 0, v127
	v_mul_f32_e64 v127, |v127|, s33
	v_mul_f32_e64 v146, |v143|, s33
	v_min_f32_e32 v144, 0, v147
	v_mul_f32_e64 v147, |v147|, s33
	v_add_f32_e32 v145, v115, v145
	v_exp_f32_e32 v127, v127
	v_exp_f32_e32 v146, v146
	v_exp_f32_e32 v147, v147
	v_mul_f32_e64 v148, |v145|, s33
	v_exp_f32_e32 v148, v148
	v_add_f32_e32 v127, 1.0, v127
	v_add_f32_e32 v146, 1.0, v146
	v_add_f32_e32 v147, 1.0, v147
	v_log_f32_e32 v127, v127
	v_log_f32_e32 v146, v146
	v_log_f32_e32 v149, v147
	v_add_f32_e32 v147, 1.0, v148
	v_log_f32_e32 v148, v147
	v_min_f32_e32 v143, 0, v143
	v_xor_b32_e32 v147, 0x80000000, v146
	v_xor_b32_e32 v146, 0x80000000, v127
	v_min_f32_e32 v145, 0, v145
	v_pk_fma_f32 v[142:143], v[146:147], s[40:41], v[142:143] op_sel_hi:[1,0,1]
	v_xor_b32_e32 v147, 0x80000000, v148
	v_xor_b32_e32 v146, 0x80000000, v149
	v_pk_fma_f32 v[144:145], v[146:147], s[40:41], v[144:145] op_sel_hi:[1,0,1]
	v_pk_mul_f32 v[142:143], v[142:143], s[42:43] op_sel_hi:[1,0]
	v_pk_mul_f32 v[144:145], v[144:145], s[42:43] op_sel_hi:[1,0]
	ds_write_b128 v184, v[142:145] offset:8192
	v_mfma_f32_16x16x32_bf16 v[142:145], v[108:111], v[44:47], 0
	v_mfma_f32_16x16x32_bf16 v[108:111], v[108:111], v[36:39], 0
	s_nop 6
	v_add_f32_e32 v127, v112, v142
	v_add_f32_e32 v112, v112, v108
	v_add_f32_e32 v109, v113, v109
	v_add_f32_e32 v143, v113, v143
	v_add_f32_e32 v147, v114, v144
	v_min_f32_e32 v108, 0, v112
	v_mul_f32_e64 v112, |v112|, s33
	v_mul_f32_e64 v113, |v109|, s33
	v_add_f32_e32 v114, v114, v110
	v_add_f32_e32 v111, v115, v111
	v_min_f32_e32 v142, 0, v127
	v_mul_f32_e64 v127, |v127|, s33
	v_mul_f32_e64 v146, |v143|, s33
	v_min_f32_e32 v144, 0, v147
	v_mul_f32_e64 v147, |v147|, s33
	v_add_f32_e32 v145, v115, v145
	v_exp_f32_e32 v112, v112
	v_exp_f32_e32 v113, v113
	v_min_f32_e32 v110, 0, v114
	v_mul_f32_e64 v114, |v114|, s33
	v_mul_f32_e64 v115, |v111|, s33
	v_exp_f32_e32 v127, v127
	v_exp_f32_e32 v146, v146
	v_exp_f32_e32 v147, v147
	v_mul_f32_e64 v148, |v145|, s33
	v_exp_f32_e32 v114, v114
	v_exp_f32_e32 v115, v115
	v_exp_f32_e32 v148, v148
	v_add_f32_e32 v112, 1.0, v112
	v_add_f32_e32 v113, 1.0, v113
	v_add_f32_e32 v127, 1.0, v127
	v_add_f32_e32 v146, 1.0, v146
	v_add_f32_e32 v147, 1.0, v147
	v_log_f32_e32 v112, v112
	v_log_f32_e32 v113, v113
	v_add_f32_e32 v114, 1.0, v114
	v_add_f32_e32 v115, 1.0, v115
	v_log_f32_e32 v127, v127
	v_log_f32_e32 v146, v146
	v_log_f32_e32 v149, v147
	v_add_f32_e32 v147, 1.0, v148
	v_log_f32_e32 v114, v114
	v_log_f32_e32 v115, v115
	v_log_f32_e32 v148, v147
	v_min_f32_e32 v109, 0, v109
	v_xor_b32_e32 v113, 0x80000000, v113
	v_xor_b32_e32 v112, 0x80000000, v112
	v_min_f32_e32 v143, 0, v143
	v_xor_b32_e32 v147, 0x80000000, v146
	v_xor_b32_e32 v146, 0x80000000, v127
	v_min_f32_e32 v111, 0, v111
	v_pk_fma_f32 v[108:109], v[112:113], s[40:41], v[108:109] op_sel_hi:[1,0,1]
	v_xor_b32_e32 v113, 0x80000000, v115
	v_xor_b32_e32 v112, 0x80000000, v114
	v_min_f32_e32 v145, 0, v145
	v_pk_fma_f32 v[142:143], v[146:147], s[40:41], v[142:143] op_sel_hi:[1,0,1]
	v_xor_b32_e32 v147, 0x80000000, v148
	v_xor_b32_e32 v146, 0x80000000, v149
	v_pk_fma_f32 v[110:111], v[112:113], s[40:41], v[110:111] op_sel_hi:[1,0,1]
	v_pk_fma_f32 v[144:145], v[146:147], s[40:41], v[144:145] op_sel_hi:[1,0,1]
	v_pk_mul_f32 v[110:111], v[110:111], s[42:43] op_sel_hi:[1,0]
	v_pk_mul_f32 v[108:109], v[108:109], s[42:43] op_sel_hi:[1,0]
	v_pk_mul_f32 v[144:145], v[144:145], s[42:43] op_sel_hi:[1,0]
	v_pk_mul_f32 v[142:143], v[142:143], s[42:43] op_sel_hi:[1,0]
	ds_write_b128 v184, v[108:111] offset:24576
	v_add_u32_e32 v108, v180, v181
	ds_write_b128 v184, v[142:145] offset:16384
	s_waitcnt lgkmcnt(0)
	s_barrier
	ds_read2st64_b32 v[110:111], v108 offset1:2
	ds_read2st64_b32 v[112:113], v108 offset0:4 offset1:6
	ds_read2st64_b32 v[114:115], v108 offset0:8 offset1:10
	ds_read2st64_b32 v[142:143], v108 offset0:12 offset1:14
	ds_read2st64_b32 v[144:145], v108 offset0:16 offset1:18
	ds_read2st64_b32 v[146:147], v108 offset0:20 offset1:22
	ds_read2st64_b32 v[148:149], v108 offset0:24 offset1:26
	ds_read2st64_b32 v[150:151], v108 offset0:28 offset1:30
	s_waitcnt lgkmcnt(7)
	v_add_f32_e32 v166, 0, v110
	v_add_f32_e32 v167, v166, v111
	s_waitcnt lgkmcnt(6)
	v_add_f32_e32 v163, v167, v112
	v_add_f32_e32 v165, v163, v113
	s_waitcnt lgkmcnt(5)
	v_add_f32_e32 v161, v165, v114
	v_add_f32_e32 v162, v161, v115
	s_waitcnt lgkmcnt(4)
	v_add_f32_e32 v159, v162, v142
	v_add_f32_e32 v160, v159, v143
	s_waitcnt lgkmcnt(3)
	v_add_f32_e32 v115, v160, v144
	v_add_f32_e32 v127, v115, v145
	s_waitcnt lgkmcnt(2)
	v_add_f32_e32 v113, v127, v146
	v_add_f32_e32 v114, v113, v147
	s_waitcnt lgkmcnt(1)
	v_add_f32_e32 v111, v114, v148
	v_add_f32_e32 v112, v111, v149
	s_waitcnt lgkmcnt(0)
	v_add_f32_e32 v109, v112, v150
	v_add_f32_e32 v110, v109, v151
	ds_write_b32 v183, v110
	s_waitcnt lgkmcnt(0)
	s_barrier
	s_and_saveexec_b64 s[10:11], s[8:9]
	s_cbranch_execnz .LBB0_1820
	s_or_b64 exec, exec, s[10:11]
	v_cmp_lt_i32_e64 s[10:11], 1, v123
	s_and_saveexec_b64 s[12:13], s[10:11]
	s_cbranch_execnz .LBB0_1821

.LBB0_1796:
	s_or_b64 exec, exec, s[14:15]
	s_waitcnt vmcnt(16)
	v_lshlrev_b32_e32 v148, 16, v100
	v_and_b32_e32 v149, 0xffff0000, v100
	v_lshlrev_b32_e32 v146, 16, v101
	v_and_b32_e32 v147, 0xffff0000, v101
	v_add_f32_e32 v100, v166, v169
	v_add_f32_e32 v101, v167, v169
	ds_write2st64_b32 v108, v100, v101 offset1:2
	v_add_f32_e32 v100, v163, v169
	v_add_f32_e32 v101, v165, v169
	ds_write2st64_b32 v108, v100, v101 offset0:4 offset1:6
	v_add_f32_e32 v100, v161, v169
	v_add_f32_e32 v101, v162, v169
	ds_write2st64_b32 v108, v100, v101 offset0:8 offset1:10
	v_add_f32_e32 v100, v159, v169
	v_add_f32_e32 v101, v160, v169
	ds_write2st64_b32 v108, v100, v101 offset0:12 offset1:14
	v_add_f32_e32 v100, v115, v169
	v_add_f32_e32 v101, v127, v169
	ds_write2st64_b32 v108, v100, v101 offset0:16 offset1:18
	v_add_f32_e32 v100, v113, v169
	v_add_f32_e32 v101, v114, v169
	ds_write2st64_b32 v108, v100, v101 offset0:20 offset1:22
	v_add_f32_e32 v100, v111, v169
	v_add_f32_e32 v101, v112, v169
	ds_write2st64_b32 v108, v100, v101 offset0:24 offset1:26
	v_add_f32_e32 v100, v109, v169
	v_add_f32_e32 v101, v110, v169
	v_lshl_add_u32 v186, v158, 2, 0
	ds_write2st64_b32 v108, v100, v101 offset0:28 offset1:30
	v_lshlrev_b32_e32 v100, 9, v168
	v_add_u32_e32 v188, v186, v100
	v_lshlrev_b32_e32 v156, 16, v104
	v_and_b32_e32 v157, 0xffff0000, v104
	v_lshlrev_b32_e32 v154, 16, v105
	v_and_b32_e32 v155, 0xffff0000, v105
	v_lshlrev_b32_e32 v152, 16, v106
	v_and_b32_e32 v153, 0xffff0000, v106
	v_lshlrev_b32_e32 v150, 16, v107
	v_and_b32_e32 v151, 0xffff0000, v107
	s_waitcnt lgkmcnt(0)
	s_barrier
	ds_read_b128 v[104:107], v186 offset:16384
	ds_read_b128 v[108:111], v188
	v_and_b32_e32 v159, 0xffff0000, v96
	v_ashrrev_i32_e32 v100, 3, v187
	v_lshlrev_b32_e32 v144, 16, v102
	v_and_b32_e32 v145, 0xffff0000, v102
	s_waitcnt lgkmcnt(0)
	v_sub_f32_e32 v158, v108, v104
	v_mul_f32_e32 v158, 0x3fb8aa3b, v158
	v_exp_f32_e32 v160, v158
	v_sub_f32_e32 v158, v104, v108
	v_mul_f32_e32 v158, 0x3fb8aa3b, v158
	v_exp_f32_e32 v162, v158
	v_lshlrev_b32_e32 v158, 16, v96
	v_sub_f32_e32 v96, v109, v105
	v_mul_f32_e32 v96, 0x3fb8aa3b, v96
	v_exp_f32_e32 v161, v96
	v_sub_f32_e32 v96, v105, v109
	v_mul_f32_e32 v96, 0x3fb8aa3b, v96
	v_exp_f32_e32 v163, v96
	v_mul_f32_e32 v96, 0x3fb8aa3b, v109
	v_exp_f32_e32 v109, v96
	v_sub_f32_e32 v96, v110, v106
	v_pk_mul_f32 v[172:173], v[162:163], v[156:157]
	v_lshlrev_b32_e32 v162, 16, v97
	v_and_b32_e32 v163, 0xffff0000, v97
	v_sub_f32_e32 v97, v111, v107
	v_lshlrev_b32_e32 v142, 16, v103
	v_and_b32_e32 v143, 0xffff0000, v103
	v_and_b32_e32 v127, 0xffffffe0, v100
	ds_read_b128 v[100:103], v186 offset:16400
	ds_read_b128 v[112:115], v188 offset:16
	v_mul_f32_e32 v96, 0x3fb8aa3b, v96
	v_mul_f32_e32 v97, 0x3fb8aa3b, v97
	v_exp_f32_e32 v96, v96
	v_exp_f32_e32 v97, v97
	v_pk_mul_f32 v[162:163], v[162:163], s[44:45] op_sel_hi:[1,0]
	v_pk_mul_f32 v[158:159], v[158:159], s[44:45] op_sel_hi:[1,0]
	v_mul_f32_e32 v108, 0x3fb8aa3b, v108
	v_pk_mul_f32 v[190:191], v[162:163], v[96:97]
	s_waitcnt lgkmcnt(0)
	v_sub_f32_e32 v97, v100, v112
	v_pk_mul_f32 v[170:171], v[158:159], v[160:161]
	v_sub_f32_e32 v160, v106, v110
	v_sub_f32_e32 v161, v107, v111
	v_mul_f32_e32 v97, 0x3fb8aa3b, v97
	v_mul_f32_e32 v160, 0x3fb8aa3b, v160
	v_mul_f32_e32 v161, 0x3fb8aa3b, v161
	v_exp_f32_e32 v166, v97
	v_mul_f32_e32 v97, 0x3fb8aa3b, v112
	v_exp_f32_e32 v160, v160
	v_exp_f32_e32 v161, v161
	v_sub_f32_e32 v96, v112, v100
	v_exp_f32_e32 v112, v97
	v_sub_f32_e32 v97, v113, v101
	v_mul_f32_e32 v96, 0x3fb8aa3b, v96
	v_mul_f32_e32 v97, 0x3fb8aa3b, v97
	v_exp_f32_e32 v96, v96
	v_exp_f32_e32 v97, v97
	v_pk_mul_f32 v[192:193], v[160:161], v[154:155]
	v_lshlrev_b32_e32 v160, 16, v98
	v_and_b32_e32 v161, 0xffff0000, v98
	v_sub_f32_e32 v98, v101, v113
	v_mul_f32_e32 v98, 0x3fb8aa3b, v98
	v_pk_mul_f32 v[160:161], v[160:161], s[44:45] op_sel_hi:[1,0]
	v_exp_f32_e32 v167, v98
	v_pk_mul_f32 v[194:195], v[160:161], v[96:97]
	v_sub_f32_e32 v97, v102, v114
	v_mul_f32_e32 v98, 0x3fb8aa3b, v113
	v_mul_f32_e32 v97, 0x3fb8aa3b, v97
	v_exp_f32_e32 v113, v98
	v_exp_f32_e32 v98, v97
	v_mul_f32_e32 v97, 0x3fb8aa3b, v114
	v_sub_f32_e32 v96, v114, v102
	v_exp_f32_e32 v114, v97
	v_sub_f32_e32 v97, v115, v103
	v_pk_mul_f32 v[196:197], v[166:167], v[152:153]
	v_mul_f32_e32 v96, 0x3fb8aa3b, v96
	v_lshlrev_b32_e32 v166, 16, v99
	v_and_b32_e32 v167, 0xffff0000, v99
	v_mul_f32_e32 v97, 0x3fb8aa3b, v97
	v_sub_f32_e32 v99, v103, v115
	v_exp_f32_e32 v96, v96
	v_exp_f32_e32 v97, v97
	v_mul_f32_e32 v99, 0x3fb8aa3b, v99
	v_mul_f32_e32 v110, 0x3fb8aa3b, v110
	v_mul_f32_e32 v111, 0x3fb8aa3b, v111
	v_exp_f32_e32 v99, v99
	v_mul_f32_e32 v115, 0x3fb8aa3b, v115
	v_exp_f32_e32 v108, v108
	v_exp_f32_e32 v110, v110
	v_exp_f32_e32 v111, v111
	v_exp_f32_e32 v115, v115
	v_pk_mul_f32 v[166:167], v[166:167], s[44:45] op_sel_hi:[1,0]
	v_sub_u32_e32 v123, v186, v8
	v_pk_mul_f32 v[198:199], v[166:167], v[96:97]
	v_mul_lo_u32 v165, v168, s41
	v_pk_mul_f32 v[200:201], v[98:99], v[150:151]
	v_cvt_pk_bf16_f32 v96, v170, v171
	v_cvt_pk_bf16_f32 v97, v190, v191
	v_cvt_pk_bf16_f32 v98, v194, v195
	v_cvt_pk_bf16_f32 v99, v198, v199
	v_add_u32_e32 v185, v123, v165
	v_pk_mul_f32 v[108:109], v[158:159], v[108:109]
	v_pk_mul_f32 v[110:111], v[162:163], v[110:111]
	v_pk_mul_f32 v[112:113], v[160:161], v[112:113]
	v_pk_mul_f32 v[114:115], v[166:167], v[114:115]
	ds_write_b128 v185, v[96:99] offset:32768
	v_cvt_pk_bf16_f32 v96, v172, v173
	v_cvt_pk_bf16_f32 v97, v192, v193
	v_cvt_pk_bf16_f32 v98, v196, v197
	v_cvt_pk_bf16_f32 v99, v200, v201
	ds_write_b128 v185, v[96:99] offset:50176
	v_cvt_pk_bf16_f32 v96, v108, v109
	v_cvt_pk_bf16_f32 v97, v110, v111
	v_cvt_pk_bf16_f32 v98, v112, v113
	v_cvt_pk_bf16_f32 v99, v114, v115
	v_add3_u32 v8, s94, v8, v165
	ds_write_b128 v8, v[96:99]
	v_lshlrev_b32_e32 v96, 9, v164
	v_add_u32_e32 v191, v186, v96
	ds_read_b128 v[96:99], v191
	v_or_b32_e32 v108, v127, v131
	v_mul_lo_u32 v189, v108, s41
	ds_read_b128 v[108:111], v191 offset:16
	v_lshlrev_b32_e32 v114, 16, v60
	v_and_b32_e32 v115, 0xffff0000, v60
	s_waitcnt lgkmcnt(1)
	v_sub_f32_e32 v60, v97, v105
	v_mul_f32_e32 v60, 0x3fb8aa3b, v60
	v_exp_f32_e32 v113, v60
	v_sub_f32_e32 v60, v105, v97
	v_mul_f32_e32 v60, 0x3fb8aa3b, v60
	v_exp_f32_e32 v105, v60
	v_mul_f32_e32 v60, 0x3fb8aa3b, v97
	v_exp_f32_e32 v97, v60
	v_pk_mul_f32 v[164:165], v[114:115], s[44:45] op_sel_hi:[1,0]
	v_sub_f32_e32 v60, v98, v106
	v_lshlrev_b32_e32 v114, 16, v61
	v_and_b32_e32 v115, 0xffff0000, v61
	v_sub_f32_e32 v61, v99, v107
	v_mul_f32_e32 v60, 0x3fb8aa3b, v60
	v_mul_f32_e32 v61, 0x3fb8aa3b, v61
	v_exp_f32_e32 v60, v60
	v_exp_f32_e32 v61, v61
	v_pk_mul_f32 v[170:171], v[114:115], s[44:45] op_sel_hi:[1,0]
	v_lshlrev_b32_e32 v168, 16, v62
	v_and_b32_e32 v169, 0xffff0000, v62
	v_pk_mul_f32 v[114:115], v[170:171], v[60:61]
	s_waitcnt lgkmcnt(0)
	v_sub_f32_e32 v61, v100, v108
	v_mul_f32_e32 v61, 0x3fb8aa3b, v61
	v_sub_f32_e32 v60, v108, v100
	v_exp_f32_e32 v100, v61
	v_mul_f32_e32 v61, 0x3fb8aa3b, v108
	v_exp_f32_e32 v108, v61
	v_sub_f32_e32 v61, v109, v101
	v_mul_f32_e32 v60, 0x3fb8aa3b, v60
	v_mul_f32_e32 v61, 0x3fb8aa3b, v61
	v_exp_f32_e32 v60, v60
	v_exp_f32_e32 v61, v61
	v_sub_f32_e32 v62, v101, v109
	v_pk_mul_f32 v[168:169], v[168:169], s[44:45] op_sel_hi:[1,0]
	v_mul_f32_e32 v62, 0x3fb8aa3b, v62
	v_pk_mul_f32 v[192:193], v[168:169], v[60:61]
	v_sub_f32_e32 v61, v102, v110
	v_exp_f32_e32 v101, v62
	v_mul_f32_e32 v62, 0x3fb8aa3b, v109
	v_mul_f32_e32 v61, 0x3fb8aa3b, v61
	v_exp_f32_e32 v109, v62
	v_exp_f32_e32 v62, v61
	v_mul_f32_e32 v61, 0x3fb8aa3b, v110
	v_sub_f32_e32 v112, v96, v104
	v_sub_f32_e32 v60, v110, v102
	v_exp_f32_e32 v102, v61
	v_sub_f32_e32 v61, v111, v103
	v_mul_f32_e32 v112, 0x3fb8aa3b, v112
	v_sub_f32_e32 v104, v104, v96
	v_sub_f32_e32 v106, v106, v98
	v_sub_f32_e32 v107, v107, v99
	v_mul_f32_e32 v60, 0x3fb8aa3b, v60
	v_lshlrev_b32_e32 v172, 16, v63
	v_and_b32_e32 v173, 0xffff0000, v63
	v_mul_f32_e32 v61, 0x3fb8aa3b, v61
	v_sub_f32_e32 v63, v103, v111
	v_exp_f32_e32 v112, v112
	v_mul_f32_e32 v104, 0x3fb8aa3b, v104
	v_mul_f32_e32 v106, 0x3fb8aa3b, v106
	v_mul_f32_e32 v107, 0x3fb8aa3b, v107
	v_exp_f32_e32 v60, v60
	v_exp_f32_e32 v61, v61
	v_mul_f32_e32 v63, 0x3fb8aa3b, v63
	v_exp_f32_e32 v104, v104
	v_mul_f32_e32 v96, 0x3fb8aa3b, v96
	v_exp_f32_e32 v106, v106
	v_mul_f32_e32 v98, 0x3fb8aa3b, v98
	v_exp_f32_e32 v107, v107
	v_mul_f32_e32 v99, 0x3fb8aa3b, v99
	v_exp_f32_e32 v63, v63
	v_mul_f32_e32 v103, 0x3fb8aa3b, v111
	v_exp_f32_e32 v96, v96
	v_exp_f32_e32 v98, v98
	v_exp_f32_e32 v99, v99
	v_exp_f32_e32 v103, v103
	v_pk_mul_f32 v[172:173], v[172:173], s[44:45] op_sel_hi:[1,0]
	v_pk_mul_f32 v[112:113], v[164:165], v[112:113]
	v_pk_mul_f32 v[110:111], v[172:173], v[60:61]
	v_pk_mul_f32 v[104:105], v[104:105], v[148:149]
	v_pk_mul_f32 v[106:107], v[106:107], v[146:147]
	v_pk_mul_f32 v[100:101], v[100:101], v[144:145]
	v_pk_mul_f32 v[194:195], v[62:63], v[142:143]
	v_cvt_pk_bf16_f32 v60, v112, v113
	v_cvt_pk_bf16_f32 v61, v114, v115
	v_cvt_pk_bf16_f32 v62, v192, v193
	v_cvt_pk_bf16_f32 v63, v110, v111
	v_add_u32_e32 v123, 0, v116
	v_pk_mul_f32 v[96:97], v[164:165], v[96:97]
	v_pk_mul_f32 v[98:99], v[170:171], v[98:99]
	v_pk_mul_f32 v[108:109], v[168:169], v[108:109]
	v_pk_mul_f32 v[102:103], v[172:173], v[102:103]
	ds_write_b128 v185, v[60:63] offset:41472
	v_cvt_pk_bf16_f32 v60, v104, v105
	v_cvt_pk_bf16_f32 v61, v106, v107
	v_cvt_pk_bf16_f32 v62, v100, v101
	v_cvt_pk_bf16_f32 v63, v194, v195
	ds_write_b128 v185, v[60:63] offset:58880
	v_cvt_pk_bf16_f32 v60, v96, v97
	v_cvt_pk_bf16_f32 v61, v98, v99
	v_cvt_pk_bf16_f32 v62, v108, v109
	v_cvt_pk_bf16_f32 v63, v102, v103
	v_add_u32_e32 v192, v123, v189
	ds_write_b128 v8, v[60:63] offset:8704
	s_waitcnt lgkmcnt(0)
	s_barrier
	ds_read_b128 v[60:63], v192 offset:50176
	v_and_or_b32 v189, v122, 48, v131
	v_mad_u32_u24 v96, v189, s41, 0
	v_add_u32_e32 v193, v96, v116
	ds_read_b128 v[96:99], v193 offset:32768
	ds_read_b128 v[100:103], v193 offset:32832
	ds_read_b128 v[104:107], v192 offset:50240
	ds_read_b128 v[108:111], v192 offset:54528
	ds_read_b128 v[112:115], v192 offset:54592
	s_waitcnt lgkmcnt(4)
	v_mfma_f32_16x16x32_bf16 v[60:63], v[60:63], v[96:99], 0
	v_lshlrev_b32_e32 v117, 2, v117
	v_or_b32_e32 v194, v117, v127
	v_cmp_ge_i32_e32 vcc, v189, v194
	s_waitcnt lgkmcnt(1)
	v_mfma_f32_16x16x32_bf16 v[96:99], v[108:111], v[96:99], 0
	ds_read_b128 v[108:111], v192 offset:50304
	v_cmp_gt_i32_e64 s[14:15], v189, v194
	v_mul_u32_u24_e32 v117, 0x90, v189
	v_mfma_f32_16x16x32_bf16 v[60:63], v[104:107], v[100:103], v[60:63]
	ds_read_b128 v[104:107], v193 offset:32896
	ds_read_b128 v[196:199], v192 offset:54656
	v_or_b32_e32 v200, 17, v194
	v_or_b32_e32 v202, 18, v194
	s_waitcnt lgkmcnt(3)
	v_mfma_f32_16x16x32_bf16 v[96:99], v[112:115], v[100:103], v[96:99]
	ds_read_b128 v[100:103], v193 offset:32960
	ds_read_b128 v[112:115], v192 offset:50368
	v_bfe_u32 v122, v187, 2, 2
	v_or_b32_e32 v203, 19, v194
	s_waitcnt lgkmcnt(3)
	v_mfma_f32_16x16x32_bf16 v[60:63], v[108:111], v[104:107], v[60:63]
	ds_read_b128 v[108:111], v192 offset:54720
	v_add_u32_e32 v190, s95, v116
	v_add_u32_e32 v201, s94, v116
	s_waitcnt lgkmcnt(3)
	v_mfma_f32_16x16x32_bf16 v[96:99], v[196:199], v[104:107], v[96:99]
	v_or_b32_e32 v197, 2, v194
	v_or_b32_e32 v198, 3, v194
	v_or_b32_e32 v199, 16, v194
	s_waitcnt lgkmcnt(1)
	v_mfma_f32_16x16x32_bf16 v[60:63], v[112:115], v[100:103], v[60:63]
	v_lshrrev_b32_e32 v104, 1, v187
	v_lshlrev_b32_e32 v105, 4, v133
	v_and_or_b32 v196, v104, 24, v122
	s_waitcnt lgkmcnt(0)
	v_mfma_f32_16x16x32_bf16 v[96:99], v[108:111], v[100:103], v[96:99]
	v_lshlrev_b32_e32 v104, 1, v132
	s_nop 1
	v_cndmask_b32_e32 v60, 0, v60, vcc
	v_cmp_ge_i32_e32 vcc, v189, v197
	v_cndmask_b32_e64 v61, 0, v61, s[14:15]
	v_cvt_pk_bf16_f32 v60, v60, v61
	v_cndmask_b32_e32 v62, 0, v62, vcc
	v_cmp_ge_i32_e32 vcc, v189, v198
	v_and_b32_e32 v105, 48, v105
	v_add3_u32 v187, s73, v104, v105
	v_cndmask_b32_e32 v63, 0, v63, vcc
	v_cvt_pk_bf16_f32 v61, v62, v63
	v_lshlrev_b32_e32 v62, 1, v194
	v_cmp_ge_i32_e32 vcc, v189, v199
	v_add3_u32 v195, s95, v117, v62
	v_mad_u32_u24 v117, v196, s21, v187
	v_cndmask_b32_e32 v62, 0, v96, vcc
	v_cmp_ge_i32_e32 vcc, v189, v200
	v_mad_u32_u24 v122, v131, s43, v190
	v_mad_u32_u24 v116, v131, s41, v201
	v_cndmask_b32_e32 v63, 0, v97, vcc
	v_cmp_ge_i32_e32 vcc, v189, v202
	v_cvt_pk_bf16_f32 v62, v62, v63
	s_nop 0
	v_cndmask_b32_e32 v96, 0, v98, vcc
	v_cmp_ge_i32_e32 vcc, v189, v203
	s_nop 1
	v_cndmask_b32_e32 v97, 0, v99, vcc
	v_cvt_pk_bf16_f32 v63, v96, v97
	ds_write2_b64 v195, v[60:61], v[62:63] offset1:4
	s_waitcnt lgkmcnt(0)
	s_barrier
	ds_read_b64_tr_b16 v[62:63], v117 offset:2176
	ds_read_b64_tr_b16 v[60:61], v117
	ds_read_b64_tr_b16 v[98:99], v117 offset:2184
	ds_read_b64_tr_b16 v[96:97], v117 offset:8
	ds_read_b128 v[100:103], v122
	ds_read_b128 v[104:107], v122 offset:64
	ds_read_b128 v[112:115], v122 offset:2304
	ds_read_b128 v[206:209], v122 offset:2368
	ds_read_b128 v[214:217], v122 offset:4608
	ds_read_b128 v[218:221], v122 offset:4672
	ds_read_b128 v[226:229], v122 offset:6912
	ds_read_b128 v[230:233], v122 offset:6976
	s_waitcnt lgkmcnt(7)
	v_mfma_f32_16x16x32_bf16 v[108:111], v[60:63], v[100:103], 0
	ds_read_b64_tr_b16 v[234:235], v117 offset:17408
	ds_read_b64_tr_b16 v[236:237], v117 offset:19584
	v_mfma_f32_16x16x32_bf16 v[100:103], v[96:99], v[100:103], 0
	s_waitcnt lgkmcnt(7)
	v_mfma_f32_16x16x32_bf16 v[210:213], v[60:63], v[112:115], 0
	v_mfma_f32_16x16x32_bf16 v[112:115], v[96:99], v[112:115], 0
	s_waitcnt lgkmcnt(5)
	v_mfma_f32_16x16x32_bf16 v[222:225], v[60:63], v[214:217], 0
	v_mfma_f32_16x16x32_bf16 v[214:217], v[96:99], v[214:217], 0
	s_waitcnt lgkmcnt(3)
	v_mfma_f32_16x16x32_bf16 v[60:63], v[60:63], v[226:229], 0
	v_mfma_f32_16x16x32_bf16 v[96:99], v[96:99], v[226:229], 0
	ds_read_b64_tr_b16 v[228:229], v117 offset:19592
	ds_read_b64_tr_b16 v[226:227], v117 offset:17416
	s_waitcnt lgkmcnt(2)
	v_mfma_f32_16x16x32_bf16 v[108:111], v[234:237], v[104:107], v[108:111]
	s_waitcnt lgkmcnt(0)
	v_mfma_f32_16x16x32_bf16 v[100:103], v[226:229], v[104:107], v[100:103]
	v_mfma_f32_16x16x32_bf16 v[104:107], v[234:237], v[206:209], v[210:213]
	v_mfma_f32_16x16x32_bf16 v[112:115], v[226:229], v[206:209], v[112:115]
	v_mfma_f32_16x16x32_bf16 v[206:209], v[234:237], v[218:221], v[222:225]
	v_mfma_f32_16x16x32_bf16 v[210:213], v[226:229], v[218:221], v[214:217]
	s_nop 2
	ds_read_b128 v[214:217], v116
	ds_read_b128 v[218:221], v116 offset:64
	s_waitcnt vmcnt(7) lgkmcnt(1)
	v_mfma_f32_16x16x32_bf16 v[108:111], v[84:87], v[214:217], v[108:111]
	s_waitcnt vmcnt(3)
	v_mfma_f32_16x16x32_bf16 v[100:103], v[92:95], v[214:217], v[100:103]
	ds_read_b128 v[214:217], v116 offset:4352
	ds_read_b128 v[222:225], v116 offset:4416
	v_mfma_f32_16x16x32_bf16 v[96:99], v[226:229], v[230:233], v[96:99]
	s_waitcnt lgkmcnt(1)
	v_mfma_f32_16x16x32_bf16 v[104:107], v[84:87], v[214:217], v[104:107]
	v_mfma_f32_16x16x32_bf16 v[112:115], v[92:95], v[214:217], v[112:115]
	ds_read_b128 v[214:217], v116 offset:8704
	ds_read_b128 v[226:229], v116 offset:8768
	v_mfma_f32_16x16x32_bf16 v[60:63], v[234:237], v[230:233], v[60:63]
	s_waitcnt lgkmcnt(1)
	v_mfma_f32_16x16x32_bf16 v[206:209], v[84:87], v[214:217], v[206:209]
	v_mfma_f32_16x16x32_bf16 v[210:213], v[92:95], v[214:217], v[210:213]
	ds_read_b128 v[214:217], v116 offset:13056
	ds_read_b128 v[230:233], v116 offset:13120
	s_waitcnt lgkmcnt(1)
	v_mfma_f32_16x16x32_bf16 v[60:63], v[84:87], v[214:217], v[60:63]
	v_mfma_f32_16x16x32_bf16 v[84:87], v[92:95], v[214:217], v[96:99]
	v_mfma_f32_16x16x32_bf16 v[92:95], v[80:83], v[218:221], v[108:111]
	s_waitcnt vmcnt(2)
	v_mfma_f32_16x16x32_bf16 v[96:99], v[88:91], v[218:221], v[100:103]
	v_mfma_f32_16x16x32_bf16 v[100:103], v[80:83], v[222:225], v[104:107]
	v_mfma_f32_16x16x32_bf16 v[108:111], v[80:83], v[226:229], v[206:209]
	s_waitcnt lgkmcnt(0)
	v_mfma_f32_16x16x32_bf16 v[60:63], v[80:83], v[230:233], v[60:63]
	v_mfma_f32_16x16x32_bf16 v[80:83], v[88:91], v[230:233], v[84:87]
	v_mfma_f32_16x16x32_bf16 v[104:107], v[88:91], v[222:225], v[112:115]
	v_mfma_f32_16x16x32_bf16 v[112:115], v[88:91], v[226:229], v[210:213]
	s_nop 0
	ds_read_b128 v[84:87], v116 offset:128
	ds_read_b128 v[206:209], v116 offset:192
	s_waitcnt lgkmcnt(1)
	v_mfma_f32_16x16x32_bf16 v[88:91], v[68:71], v[84:87], v[92:95]
	s_waitcnt vmcnt(1)
	v_mfma_f32_16x16x32_bf16 v[84:87], v[76:79], v[84:87], v[96:99]
	s_nop 0
	ds_read_b128 v[92:95], v116 offset:4480
	s_nop 0
	ds_read_b128 v[96:99], v116 offset:4544
	s_waitcnt lgkmcnt(1)
	v_mfma_f32_16x16x32_bf16 v[100:103], v[68:71], v[92:95], v[100:103]
	v_mfma_f32_16x16x32_bf16 v[104:107], v[76:79], v[92:95], v[104:107]
	ds_read_b128 v[92:95], v116 offset:8832
	ds_read_b128 v[210:213], v116 offset:8896
	s_waitcnt lgkmcnt(1)
	v_mfma_f32_16x16x32_bf16 v[108:111], v[68:71], v[92:95], v[108:111]
	v_mfma_f32_16x16x32_bf16 v[112:115], v[76:79], v[92:95], v[112:115]
	ds_read_b128 v[92:95], v116 offset:13184
	ds_read_b128 v[214:217], v116 offset:13248
	s_waitcnt lgkmcnt(1)
	v_mfma_f32_16x16x32_bf16 v[60:63], v[68:71], v[92:95], v[60:63]
	v_mfma_f32_16x16x32_bf16 v[218:221], v[76:79], v[92:95], v[80:83]
	v_mfma_f32_16x16x32_bf16 v[88:91], v[64:67], v[206:209], v[88:91]
	s_waitcnt vmcnt(0)
	v_mfma_f32_16x16x32_bf16 v[92:95], v[72:75], v[206:209], v[84:87]
	v_mfma_f32_16x16x32_bf16 v[80:83], v[64:67], v[96:99], v[100:103]
	v_mfma_f32_16x16x32_bf16 v[84:87], v[72:75], v[96:99], v[104:107]
	v_mfma_f32_16x16x32_bf16 v[68:71], v[64:67], v[210:213], v[108:111]
	v_mfma_f32_16x16x32_bf16 v[76:79], v[72:75], v[210:213], v[112:115]
	s_waitcnt lgkmcnt(0)
	v_mfma_f32_16x16x32_bf16 v[64:67], v[64:67], v[214:217], v[60:63]
	v_mfma_f32_16x16x32_bf16 v[60:63], v[72:75], v[214:217], v[218:221]
	s_or_b32 s54, s50, 1
	s_cmp_lt_i32 s54, 45
	s_mov_b64 s[58:59], -1
	s_cbranch_scc1 .LBB0_1802
	s_cmp_lt_u32 s54, 61
	s_cbranch_scc1 .LBB0_1799
	s_sub_i32 s38, s50, 60
	s_mov_b64 s[58:59], 0
	s_mov_b64 s[52:53], s[30:31]
	s_mov_b64 s[56:57], s[38:39]

.LBB0_1808:
	s_or_b64 exec, exec, s[8:9]
	v_sub_u32_e32 v53, 0, v181
	v_sub_u32_e32 v54, 0, v206
	v_add_f32_e32 v52, v52, v40
	v_add_u32_e32 v53, v180, v53
	v_sub_u32_e32 v55, 0, v207
	ds_write_b32 v53, v52 offset:32256
	v_add_f32_e32 v51, v51, v40
	v_add_u32_e32 v52, v180, v54
	v_sub_u32_e32 v56, 0, v208
	ds_write_b32 v52, v51 offset:32256
	v_add_f32_e32 v50, v50, v40
	v_add_u32_e32 v51, v180, v55
	v_sub_u32_e32 v57, 0, v209
	ds_write_b32 v51, v50 offset:32256
	v_add_f32_e32 v49, v49, v40
	v_add_u32_e32 v50, v180, v56
	v_sub_u32_e32 v58, 0, v210
	ds_write_b32 v50, v49 offset:32256
	v_add_f32_e32 v48, v48, v40
	v_add_u32_e32 v49, v180, v57
	v_sub_u32_e32 v59, 0, v211
	ds_write_b32 v49, v48 offset:32256
	v_add_f32_e32 v47, v47, v40
	v_add_u32_e32 v48, v180, v58
	v_sub_u32_e32 v127, 0, v212
	ds_write_b32 v48, v47 offset:32256
	v_add_f32_e32 v46, v46, v40
	v_add_u32_e32 v47, v180, v59
	v_sub_u32_e32 v181, 0, v213
	ds_write_b32 v47, v46 offset:32256
	v_add_f32_e32 v45, v45, v40
	v_add_u32_e32 v46, v180, v127
	v_sub_u32_e32 v182, 0, v214
	ds_write_b32 v46, v45 offset:32256
	v_add_f32_e32 v44, v44, v40
	v_add_u32_e32 v45, v180, v181
	v_sub_u32_e32 v183, 0, v215
	ds_write_b32 v45, v44 offset:32256
	v_add_f32_e32 v43, v43, v40
	v_add_u32_e32 v44, v180, v182
	v_sub_u32_e32 v184, 0, v216
	ds_write_b32 v44, v43 offset:32256
	v_add_f32_e32 v42, v42, v40
	v_add_u32_e32 v43, v180, v183
	v_sub_u32_e32 v206, 0, v217
	ds_write_b32 v43, v42 offset:32256
	v_add_f32_e32 v41, v41, v40
	v_add_u32_e32 v42, v180, v184
	v_sub_u32_e32 v207, 0, v218
	ds_write_b32 v42, v41 offset:32256
	v_add_f32_e32 v39, v39, v40
	v_add_u32_e32 v41, v180, v206
	v_sub_u32_e32 v208, 0, v219
	ds_write_b32 v41, v39 offset:32256
	v_add_f32_e32 v38, v38, v40
	v_add_u32_e32 v39, v180, v207
	v_sub_u32_e32 v209, 0, v220
	ds_write_b32 v39, v38 offset:32256
	v_add_f32_e32 v37, v37, v40
	v_add_u32_e32 v38, v180, v208
	ds_write_b32 v38, v37 offset:32256
	v_add_f32_e32 v36, v36, v40
	v_add_u32_e32 v37, v180, v209
	ds_write_b32 v37, v36 offset:32256
	s_waitcnt lgkmcnt(0)
	s_barrier
	ds_read_b128 v[36:39], v188
	ds_read_b128 v[40:43], v186 offset:15872
	ds_read_b128 v[44:47], v186 offset:15888
	ds_read_b128 v[48:51], v188 offset:16
	s_waitcnt lgkmcnt(2)
	v_sub_f32_e32 v53, v40, v36
	v_mul_f32_e32 v53, 0x3fb8aa3b, v53
	v_sub_f32_e32 v55, v41, v37
	v_sub_f32_e32 v52, v36, v40
	v_exp_f32_e32 v54, v53
	v_sub_f32_e32 v53, v37, v41
	v_mul_f32_e32 v55, 0x3fb8aa3b, v55
	v_mul_f32_e32 v36, 0x3fb8aa3b, v36
	v_mul_f32_e32 v37, 0x3fb8aa3b, v37
	v_sub_f32_e32 v57, v42, v38
	v_exp_f32_e32 v55, v55
	v_exp_f32_e32 v36, v36
	v_exp_f32_e32 v37, v37
	v_mul_f32_e32 v57, 0x3fb8aa3b, v57
	v_sub_f32_e32 v59, v43, v39
	v_sub_f32_e32 v56, v38, v42
	v_exp_f32_e32 v58, v57
	v_mul_f32_e32 v38, 0x3fb8aa3b, v38
	v_sub_f32_e32 v57, v39, v43
	v_mul_f32_e32 v59, 0x3fb8aa3b, v59
	v_mul_f32_e32 v39, 0x3fb8aa3b, v39
	v_exp_f32_e32 v38, v38
	v_exp_f32_e32 v59, v59
	v_exp_f32_e32 v39, v39
	v_pk_mul_f32 v[54:55], v[54:55], v[156:157]
	v_pk_mul_f32 v[156:157], v[158:159], v[36:37]
	s_waitcnt lgkmcnt(0)
	v_sub_f32_e32 v37, v44, v48
	v_mul_f32_e32 v37, 0x3fb8aa3b, v37
	v_pk_mul_f32 v[58:59], v[58:59], v[154:155]
	v_pk_mul_f32 v[154:155], v[162:163], v[38:39]
	v_sub_f32_e32 v36, v48, v44
	v_exp_f32_e32 v38, v37
	v_sub_f32_e32 v37, v49, v45
	v_mul_f32_e32 v52, 0x3fb8aa3b, v52
	v_mul_f32_e32 v53, 0x3fb8aa3b, v53
	v_mul_f32_e32 v36, 0x3fb8aa3b, v36
	v_mul_f32_e32 v37, 0x3fb8aa3b, v37
	v_exp_f32_e32 v52, v52
	v_exp_f32_e32 v53, v53
	v_exp_f32_e32 v36, v36
	v_exp_f32_e32 v37, v37
	v_sub_f32_e32 v39, v45, v49
	v_mul_f32_e32 v39, 0x3fb8aa3b, v39
	v_exp_f32_e32 v39, v39
	v_pk_mul_f32 v[52:53], v[158:159], v[52:53]
	v_pk_mul_f32 v[158:159], v[160:161], v[36:37]
	v_sub_f32_e32 v37, v46, v50
	v_mul_f32_e32 v37, 0x3fb8aa3b, v37
	v_pk_mul_f32 v[152:153], v[38:39], v[152:153]
	v_mul_f32_e32 v36, 0x3fb8aa3b, v49
	v_exp_f32_e32 v38, v37
	v_mul_f32_e32 v37, 0x3fb8aa3b, v50
	v_exp_f32_e32 v49, v36
	v_sub_f32_e32 v36, v50, v46
	v_exp_f32_e32 v50, v37
	v_sub_f32_e32 v37, v51, v47
	v_mul_f32_e32 v56, 0x3fb8aa3b, v56
	v_mul_f32_e32 v57, 0x3fb8aa3b, v57
	v_mul_f32_e32 v48, 0x3fb8aa3b, v48
	v_mul_f32_e32 v36, 0x3fb8aa3b, v36
	v_mul_f32_e32 v37, 0x3fb8aa3b, v37
	v_sub_f32_e32 v39, v47, v51
	v_exp_f32_e32 v56, v56
	v_exp_f32_e32 v57, v57
	v_exp_f32_e32 v48, v48
	v_exp_f32_e32 v36, v36
	v_exp_f32_e32 v37, v37
	v_mul_f32_e32 v39, 0x3fb8aa3b, v39
	v_exp_f32_e32 v39, v39
	v_mul_f32_e32 v51, 0x3fb8aa3b, v51
	v_exp_f32_e32 v51, v51
	v_pk_mul_f32 v[56:57], v[162:163], v[56:57]
	v_pk_mul_f32 v[48:49], v[160:161], v[48:49]
	v_pk_mul_f32 v[160:161], v[166:167], v[36:37]
	v_pk_mul_f32 v[150:151], v[38:39], v[150:151]
	v_cvt_pk_bf16_f32 v36, v52, v53
	v_cvt_pk_bf16_f32 v37, v56, v57
	v_cvt_pk_bf16_f32 v38, v158, v159
	v_cvt_pk_bf16_f32 v39, v160, v161
	v_pk_mul_f32 v[50:51], v[166:167], v[50:51]
	ds_write_b128 v185, v[36:39] offset:32768
	v_cvt_pk_bf16_f32 v36, v54, v55
	v_cvt_pk_bf16_f32 v37, v58, v59
	v_cvt_pk_bf16_f32 v38, v152, v153
	v_cvt_pk_bf16_f32 v39, v150, v151
	ds_write_b128 v185, v[36:39] offset:50176
	v_cvt_pk_bf16_f32 v36, v156, v157
	v_cvt_pk_bf16_f32 v37, v154, v155
	v_cvt_pk_bf16_f32 v38, v48, v49
	v_cvt_pk_bf16_f32 v39, v50, v51
	ds_write_b128 v8, v[36:39]
	ds_read_b128 v[36:39], v191
	ds_read_b128 v[48:51], v191 offset:16
	s_waitcnt lgkmcnt(1)
	v_sub_f32_e32 v52, v36, v40
	v_sub_f32_e32 v40, v40, v36
	v_sub_f32_e32 v53, v37, v41
	v_sub_f32_e32 v41, v41, v37
	v_mul_f32_e32 v36, 0x3fb8aa3b, v36
	v_mul_f32_e32 v37, 0x3fb8aa3b, v37
	v_exp_f32_e32 v36, v36
	v_exp_f32_e32 v37, v37
	v_sub_f32_e32 v54, v38, v42
	v_sub_f32_e32 v42, v42, v38
	v_mul_f32_e32 v38, 0x3fb8aa3b, v38
	v_sub_f32_e32 v55, v39, v43
	v_sub_f32_e32 v43, v43, v39
	v_mul_f32_e32 v39, 0x3fb8aa3b, v39
	v_exp_f32_e32 v38, v38
	v_exp_f32_e32 v39, v39
	v_pk_mul_f32 v[56:57], v[164:165], v[36:37]
	s_waitcnt lgkmcnt(0)
	v_sub_f32_e32 v37, v44, v48
	v_mul_f32_e32 v37, 0x3fb8aa3b, v37
	v_pk_mul_f32 v[58:59], v[170:171], v[38:39]
	v_sub_f32_e32 v36, v48, v44
	v_exp_f32_e32 v38, v37
	v_sub_f32_e32 v37, v49, v45
	v_mul_f32_e32 v42, 0x3fb8aa3b, v42
	v_mul_f32_e32 v43, 0x3fb8aa3b, v43
	v_mul_f32_e32 v36, 0x3fb8aa3b, v36
	v_mul_f32_e32 v37, 0x3fb8aa3b, v37
	v_exp_f32_e32 v42, v42
	v_exp_f32_e32 v43, v43
	v_exp_f32_e32 v36, v36
	v_exp_f32_e32 v37, v37
	v_sub_f32_e32 v39, v45, v49
	v_mul_f32_e32 v39, 0x3fb8aa3b, v39
	v_exp_f32_e32 v39, v39
	v_pk_mul_f32 v[42:43], v[42:43], v[146:147]
	v_pk_mul_f32 v[146:147], v[168:169], v[36:37]
	v_sub_f32_e32 v37, v46, v50
	v_mul_f32_e32 v37, 0x3fb8aa3b, v37
	v_pk_mul_f32 v[144:145], v[38:39], v[144:145]
	v_mul_f32_e32 v36, 0x3fb8aa3b, v49
	v_exp_f32_e32 v38, v37
	v_mul_f32_e32 v37, 0x3fb8aa3b, v50
	v_exp_f32_e32 v45, v36
	v_sub_f32_e32 v36, v50, v46
	v_exp_f32_e32 v46, v37
	v_sub_f32_e32 v37, v51, v47
	v_mul_f32_e32 v52, 0x3fb8aa3b, v52
	v_mul_f32_e32 v53, 0x3fb8aa3b, v53
	v_mul_f32_e32 v54, 0x3fb8aa3b, v54
	v_mul_f32_e32 v55, 0x3fb8aa3b, v55
	v_mul_f32_e32 v36, 0x3fb8aa3b, v36
	v_mul_f32_e32 v37, 0x3fb8aa3b, v37
	v_sub_f32_e32 v39, v47, v51
	v_exp_f32_e32 v52, v52
	v_mul_f32_e32 v40, 0x3fb8aa3b, v40
	v_exp_f32_e32 v53, v53
	v_mul_f32_e32 v41, 0x3fb8aa3b, v41
	v_exp_f32_e32 v54, v54
	v_exp_f32_e32 v55, v55
	v_exp_f32_e32 v36, v36
	v_exp_f32_e32 v37, v37
	v_mul_f32_e32 v39, 0x3fb8aa3b, v39
	v_exp_f32_e32 v40, v40
	v_exp_f32_e32 v41, v41
	v_mul_f32_e32 v44, 0x3fb8aa3b, v48
	v_exp_f32_e32 v39, v39
	v_mul_f32_e32 v47, 0x3fb8aa3b, v51
	v_exp_f32_e32 v44, v44
	v_exp_f32_e32 v47, v47
	v_pk_mul_f32 v[52:53], v[164:165], v[52:53]
	v_pk_mul_f32 v[54:55], v[170:171], v[54:55]
	v_pk_mul_f32 v[48:49], v[172:173], v[36:37]
	v_pk_mul_f32 v[40:41], v[40:41], v[148:149]
	v_pk_mul_f32 v[50:51], v[38:39], v[142:143]
	v_cvt_pk_bf16_f32 v36, v52, v53
	v_cvt_pk_bf16_f32 v37, v54, v55
	v_cvt_pk_bf16_f32 v38, v146, v147
	v_cvt_pk_bf16_f32 v39, v48, v49
	v_pk_mul_f32 v[44:45], v[168:169], v[44:45]
	v_pk_mul_f32 v[46:47], v[172:173], v[46:47]
	ds_write_b128 v185, v[36:39] offset:41472
	v_cvt_pk_bf16_f32 v36, v40, v41
	v_cvt_pk_bf16_f32 v37, v42, v43
	v_cvt_pk_bf16_f32 v38, v144, v145
	v_cvt_pk_bf16_f32 v39, v50, v51
	ds_write_b128 v185, v[36:39] offset:58880
	v_cvt_pk_bf16_f32 v36, v56, v57
	v_cvt_pk_bf16_f32 v37, v58, v59
	v_cvt_pk_bf16_f32 v38, v44, v45
	v_cvt_pk_bf16_f32 v39, v46, v47
	ds_write_b128 v8, v[36:39] offset:8704
	s_waitcnt lgkmcnt(0)
	s_barrier
	ds_read_b128 v[36:39], v192 offset:50176
	ds_read_b128 v[40:43], v193 offset:32768
	ds_read_b128 v[44:47], v193 offset:32832
	ds_read_b128 v[48:51], v192 offset:50240
	s_waitcnt lgkmcnt(2)
	v_mfma_f32_16x16x32_bf16 v[36:39], v[36:39], v[40:43], 0
	ds_read_b128 v[52:55], v192 offset:54528
	ds_read_b128 v[56:59], v192 offset:54592
	v_mul_u32_u24_e32 v8, 0x90, v131
	v_add_u32_e32 v8, v190, v8
	s_waitcnt lgkmcnt(2)
	v_mfma_f32_16x16x32_bf16 v[36:39], v[48:51], v[44:47], v[36:39]
	ds_read_b128 v[48:51], v192 offset:50304
	s_waitcnt lgkmcnt(2)
	v_mfma_f32_16x16x32_bf16 v[40:43], v[52:55], v[40:43], 0
	s_waitcnt lgkmcnt(1)
	v_mfma_f32_16x16x32_bf16 v[40:43], v[56:59], v[44:47], v[40:43]
	ds_read_b128 v[44:47], v193 offset:32896
	ds_read_b128 v[52:55], v193 offset:32960
	ds_read_b128 v[56:59], v192 offset:50368
	s_waitcnt lgkmcnt(2)
	v_mfma_f32_16x16x32_bf16 v[36:39], v[48:51], v[44:47], v[36:39]
	ds_read_b128 v[48:51], v192 offset:54656
	ds_read_b128 v[142:145], v192 offset:54720
	s_waitcnt lgkmcnt(1)
	v_mfma_f32_16x16x32_bf16 v[40:43], v[48:51], v[44:47], v[40:43]
	v_or_b32_e32 v45, 1, v194
	v_cmp_le_i32_e32 vcc, v189, v45
	v_mul_u32_u24_e32 v44, 0x220, v196
	v_mfma_f32_16x16x32_bf16 v[36:39], v[56:59], v[52:55], v[36:39]
	v_add_u32_e32 v127, v187, v44
	s_waitcnt lgkmcnt(0)
	v_mfma_f32_16x16x32_bf16 v[40:43], v[142:145], v[52:55], v[40:43]
	s_nop 4
	v_cndmask_b32_e32 v37, 0, v37, vcc
	v_cmp_le_i32_e32 vcc, v189, v197
	v_cndmask_b32_e64 v36, v36, 0, s[14:15]
	v_cvt_pk_bf16_f32 v36, v36, v37
	v_cndmask_b32_e32 v38, 0, v38, vcc
	v_cmp_le_i32_e32 vcc, v189, v198
	s_nop 1
	v_cndmask_b32_e32 v39, 0, v39, vcc
	v_cmp_le_i32_e32 vcc, v189, v199
	v_cvt_pk_bf16_f32 v37, v38, v39
	s_nop 0
	v_cndmask_b32_e32 v38, 0, v40, vcc
	v_cmp_le_i32_e32 vcc, v189, v200
	s_nop 1
	v_cndmask_b32_e32 v39, 0, v41, vcc
	v_cmp_le_i32_e32 vcc, v189, v202
	v_cvt_pk_bf16_f32 v38, v38, v39
	s_nop 0
	v_cndmask_b32_e32 v40, 0, v42, vcc
	v_cmp_le_i32_e32 vcc, v189, v203
	s_nop 1
	v_cndmask_b32_e32 v41, 0, v43, vcc
	v_cvt_pk_bf16_f32 v39, v40, v41
	ds_write2_b64 v195, v[36:37], v[38:39] offset1:4
	s_waitcnt lgkmcnt(0)
	s_barrier
	ds_read_b64_tr_b16 v[38:39], v127 offset:2176
	ds_read_b64_tr_b16 v[36:37], v127
	ds_read_b64_tr_b16 v[42:43], v127 offset:2184
	ds_read_b64_tr_b16 v[40:41], v127 offset:8
	ds_read_b128 v[44:47], v8
	ds_read_b128 v[48:51], v8 offset:64
	s_waitcnt lgkmcnt(1)
	v_mfma_f32_16x16x32_bf16 v[52:55], v[36:39], v[44:47], v[88:91]
	ds_read_b128 v[56:59], v8 offset:2304
	s_nop 1
	ds_read_b128 v[88:91], v8 offset:2368
	v_mfma_f32_16x16x32_bf16 v[44:47], v[40:43], v[44:47], v[92:95]
	s_waitcnt lgkmcnt(1)
	v_mfma_f32_16x16x32_bf16 v[80:83], v[36:39], v[56:59], v[80:83]
	v_mfma_f32_16x16x32_bf16 v[56:59], v[40:43], v[56:59], v[84:87]
	s_nop 2
	ds_read_b128 v[84:87], v8 offset:4608
	ds_read_b128 v[92:95], v8 offset:4672
	s_waitcnt lgkmcnt(1)
	v_mfma_f32_16x16x32_bf16 v[68:71], v[36:39], v[84:87], v[68:71]
	v_mfma_f32_16x16x32_bf16 v[76:79], v[40:43], v[84:87], v[76:79]
	ds_read_b128 v[84:87], v8 offset:6912
	ds_read_b128 v[142:145], v8 offset:6976
	v_mul_u32_u24_e32 v8, 0x110, v131
	v_add_u32_e32 v8, v201, v8
	s_waitcnt lgkmcnt(1)
	v_mfma_f32_16x16x32_bf16 v[36:39], v[36:39], v[84:87], v[64:67]
	s_nop 2
	ds_read_b64_tr_b16 v[64:65], v127 offset:17408
	ds_read_b64_tr_b16 v[66:67], v127 offset:19584
	v_mfma_f32_16x16x32_bf16 v[40:43], v[40:43], v[84:87], v[60:63]
	s_nop 2
	ds_read_b64_tr_b16 v[62:63], v127 offset:19592
	ds_read_b64_tr_b16 v[60:61], v127 offset:17416
	s_waitcnt lgkmcnt(2)
	v_mfma_f32_16x16x32_bf16 v[52:55], v[64:67], v[48:51], v[52:55]
	s_waitcnt lgkmcnt(0)
	v_mfma_f32_16x16x32_bf16 v[44:47], v[60:63], v[48:51], v[44:47]
	v_mfma_f32_16x16x32_bf16 v[48:51], v[64:67], v[88:91], v[80:83]
	v_mfma_f32_16x16x32_bf16 v[56:59], v[60:63], v[88:91], v[56:59]
	v_mfma_f32_16x16x32_bf16 v[68:71], v[64:67], v[92:95], v[68:71]
	v_mfma_f32_16x16x32_bf16 v[76:79], v[60:63], v[92:95], v[76:79]
	v_mfma_f32_16x16x32_bf16 v[36:39], v[64:67], v[142:145], v[36:39]
	v_mfma_f32_16x16x32_bf16 v[40:43], v[60:63], v[142:145], v[40:43]
	ds_read_b128 v[60:63], v8
	ds_read_b128 v[64:67], v8 offset:64
	s_waitcnt vmcnt(7) lgkmcnt(1)
	v_mfma_f32_16x16x32_bf16 v[52:55], v[116:119], v[60:63], v[52:55]
	s_waitcnt vmcnt(3)
	v_mfma_f32_16x16x32_bf16 v[44:47], v[120:123], v[60:63], v[44:47]
	ds_read_b128 v[60:63], v8 offset:4352
	ds_read_b128 v[80:83], v8 offset:4416
	s_waitcnt lgkmcnt(1)
	v_mfma_f32_16x16x32_bf16 v[48:51], v[116:119], v[60:63], v[48:51]
	v_mfma_f32_16x16x32_bf16 v[56:59], v[120:123], v[60:63], v[56:59]
	ds_read_b128 v[60:63], v8 offset:8704
	ds_read_b128 v[84:87], v8 offset:8768
	s_waitcnt lgkmcnt(1)
	v_mfma_f32_16x16x32_bf16 v[68:71], v[116:119], v[60:63], v[68:71]
	v_mfma_f32_16x16x32_bf16 v[60:63], v[120:123], v[60:63], v[76:79]
	s_nop 2
	ds_read_b128 v[76:79], v8 offset:13056
	ds_read_b128 v[88:91], v8 offset:13120
	s_waitcnt lgkmcnt(1)
	v_mfma_f32_16x16x32_bf16 v[36:39], v[116:119], v[76:79], v[36:39]
	v_mfma_f32_16x16x32_bf16 v[40:43], v[120:123], v[76:79], v[40:43]
	v_mfma_f32_16x16x32_bf16 v[52:55], v[108:111], v[64:67], v[52:55]
	s_waitcnt vmcnt(2)
	v_mfma_f32_16x16x32_bf16 v[44:47], v[112:115], v[64:67], v[44:47]
	v_mfma_f32_16x16x32_bf16 v[48:51], v[108:111], v[80:83], v[48:51]
	v_mfma_f32_16x16x32_bf16 v[56:59], v[112:115], v[80:83], v[56:59]
	v_mfma_f32_16x16x32_bf16 v[64:67], v[108:111], v[84:87], v[68:71]
	v_mfma_f32_16x16x32_bf16 v[60:63], v[112:115], v[84:87], v[60:63]
	s_waitcnt lgkmcnt(0)
	v_mfma_f32_16x16x32_bf16 v[36:39], v[108:111], v[88:91], v[36:39]
	v_mfma_f32_16x16x32_bf16 v[40:43], v[112:115], v[88:91], v[40:43]
	ds_read_b128 v[68:71], v8 offset:128
	ds_read_b128 v[76:79], v8 offset:192
	s_waitcnt lgkmcnt(1)
	v_mfma_f32_16x16x32_bf16 v[52:55], v[100:103], v[68:71], v[52:55]
	s_waitcnt vmcnt(1)
	v_mfma_f32_16x16x32_bf16 v[44:47], v[104:107], v[68:71], v[44:47]
	ds_read_b128 v[68:71], v8 offset:4480
	ds_read_b128 v[84:87], v8 offset:4544
	s_waitcnt lgkmcnt(1)
	v_mfma_f32_16x16x32_bf16 v[48:51], v[100:103], v[68:71], v[48:51]
	v_mfma_f32_16x16x32_bf16 v[56:59], v[104:107], v[68:71], v[56:59]
	ds_read_b128 v[68:71], v8 offset:8832
	ds_read_b128 v[88:91], v8 offset:8896
	s_waitcnt lgkmcnt(1)
	v_mfma_f32_16x16x32_bf16 v[92:95], v[100:103], v[68:71], v[64:67]
	v_mfma_f32_16x16x32_bf16 v[68:71], v[104:107], v[68:71], v[60:63]
	s_nop 2
	ds_read_b128 v[60:63], v8 offset:13184
	ds_read_b128 v[108:111], v8 offset:13248
	s_waitcnt lgkmcnt(1)
	v_mfma_f32_16x16x32_bf16 v[36:39], v[100:103], v[60:63], v[36:39]
	v_mfma_f32_16x16x32_bf16 v[100:103], v[104:107], v[60:63], v[40:43]
	v_mfma_f32_16x16x32_bf16 v[80:83], v[72:75], v[76:79], v[52:55]
	s_waitcnt vmcnt(0)
	v_mfma_f32_16x16x32_bf16 v[76:79], v[96:99], v[76:79], v[44:47]
	v_mfma_f32_16x16x32_bf16 v[64:67], v[72:75], v[84:87], v[48:51]
	v_mfma_f32_16x16x32_bf16 v[60:63], v[96:99], v[84:87], v[56:59]
	v_mfma_f32_16x16x32_bf16 v[52:55], v[72:75], v[88:91], v[92:95]
	v_mfma_f32_16x16x32_bf16 v[48:51], v[96:99], v[88:91], v[68:71]
	s_waitcnt lgkmcnt(0)
	v_mfma_f32_16x16x32_bf16 v[40:43], v[72:75], v[108:111], v[36:39]
	v_mfma_f32_16x16x32_bf16 v[36:39], v[96:99], v[108:111], v[100:103]
	s_add_i32 s76, s47, s22
	s_cmpk_gt_i32 s76, 0x3ff
	s_cbranch_scc1 .Lgcb_skip
	s_ashr_i32 s61, s76, 8
	s_add_i32 s61, s61, 4
	s_lshl_b32 s61, s61, 12
	s_and_b32 s62, s76, 63
	s_lshl_b32 s62, s62, 6
	s_or_b32 s61, s61, s62
	s_bfe_u32 s62, s76, 0x20006
	s_lshl_b32 s63, s62, 7
	s_mov_b32 s66, s20
	s_mov_b32 s67, 0
	v_and_b32_e32 v230, 48, v204
	v_mov_b32_e32 v231, 0
	v_and_b32_e32 v232, 15, v204
	v_mov_b64_e32 v[234:235], s[16:17]
	v_or_b32_e32 v233, s61, v232
	v_mad_u64_u32 v[236:237], s[64:65], v233, s0, v[234:235]
	v_lshl_add_u64 v[236:237], v[236:237], 0, v[230:231]
	v_lshl_add_u64 v[236:237], v[236:237], 0, s[66:67]
	global_load_dwordx4 v[206:209], v[236:237], off offset:2048
	v_or_b32_e32 v233, 16, v232
	v_or_b32_e32 v233, s61, v233
	v_mad_u64_u32 v[236:237], s[64:65], v233, s0, v[234:235]
	v_lshl_add_u64 v[236:237], v[236:237], 0, v[230:231]
	v_lshl_add_u64 v[236:237], v[236:237], 0, s[66:67]
	global_load_dwordx4 v[210:213], v[236:237], off offset:2048
	v_or_b32_e32 v233, 32, v232
	v_or_b32_e32 v233, s61, v233
	v_mad_u64_u32 v[236:237], s[64:65], v233, s0, v[234:235]
	v_lshl_add_u64 v[236:237], v[236:237], 0, v[230:231]
	v_lshl_add_u64 v[236:237], v[236:237], 0, s[66:67]
	global_load_dwordx4 v[214:217], v[236:237], off offset:2048
	v_or_b32_e32 v233, 48, v232
	v_or_b32_e32 v233, s61, v233
	v_mad_u64_u32 v[236:237], s[64:65], v233, s0, v[234:235]
	v_lshl_add_u64 v[236:237], v[236:237], 0, v[230:231]
	v_lshl_add_u64 v[236:237], v[236:237], 0, s[66:67]
	global_load_dwordx4 v[218:221], v[236:237], off offset:2048
	v_lshrrev_b32_e32 v233, 6, v204
	v_lshlrev_b32_e32 v233, 4, v233
	v_or_b32_e32 v236, s63, v232
	v_add_u32_e32 v236, v236, v233
	v_lshlrev_b32_e32 v236, 5, v236
	v_and_b32_e32 v233, 16, v204
	v_add_u32_e32 v236, v236, v233
	v_mov_b32_e32 v237, 0
	v_lshl_add_u64 v[236:237], v[236:237], 0, s[18:19]
	v_mov_b32_e32 v222, 0
	v_mov_b32_e32 v223, 0
	v_mov_b32_e32 v224, 0
	v_mov_b32_e32 v225, 0
	v_and_b32_e32 v233, 63, v204
	v_cmp_gt_u32_e32 vcc, 32, v233
	s_and_saveexec_b64 s[70:71], vcc
	global_load_dwordx4 v[222:225], v[236:237], off
	s_or_b64 exec, exec, s[70:71]
	s_lshl_b32 s63, s63, 2
	s_add_u32 s74, s24, s63
	s_addc_u32 s75, s25, 0
	v_lshrrev_b32_e32 v233, 6, v204
	v_lshlrev_b32_e32 v236, 6, v233
	v_bfe_u32 v233, v204, 4, 2
	v_lshl_add_u32 v236, v233, 4, v236
	v_mov_b32_e32 v237, 0
	v_lshl_add_u64 v[236:237], v[236:237], 0, s[74:75]
	global_load_dwordx4 v[226:229], v[236:237], off
.Lgcb_skip:
	v_or_b32_e32 v84, v179, v132
	v_ashrrev_i32_e32 v85, 31, v84
	s_lshl_b32 s38, s49, 9
	v_lshl_add_u64 v[44:45], v[134:135], 0, s[38:39]
	v_lshlrev_b64 v[46:47], 1, v[84:85]
	v_lshl_add_u64 v[44:45], v[44:45], 0, v[46:47]
	v_add_co_u32_e32 v44, vcc, s20, v44
	v_lshl_add_u64 v[56:57], v[136:137], 0, s[38:39]
	s_nop 0
	v_addc_co_u32_e32 v45, vcc, 0, v45, vcc
	v_lshl_add_u64 v[56:57], v[56:57], 0, v[46:47]
	v_add_co_u32_e32 v56, vcc, s20, v56
	v_mul_f32_e32 v8, v81, v81
	s_nop 0
	v_addc_co_u32_e32 v57, vcc, 0, v57, vcc
	global_load_dwordx4 v[72:75], v[44:45], off
	global_load_dwordx4 v[68:71], v[56:57], off
	v_lshl_add_u64 v[44:45], v[138:139], 0, s[38:39]
	v_lshl_add_u64 v[44:45], v[44:45], 0, v[46:47]
	v_add_co_u32_e32 v44, vcc, s20, v44
	v_lshl_add_u64 v[56:57], v[140:141], 0, s[38:39]
	s_nop 0
	v_addc_co_u32_e32 v45, vcc, 0, v45, vcc
	v_lshl_add_u64 v[46:47], v[56:57], 0, v[46:47]
	v_add_co_u32_e32 v46, vcc, s20, v46
	v_fmac_f32_e32 v8, v80, v80
	s_nop 0
	v_addc_co_u32_e32 v47, vcc, 0, v47, vcc
	global_load_dwordx4 v[56:59], v[44:45], off
	s_nop 0
	global_load_dwordx4 v[44:47], v[46:47], off
	v_fmac_f32_e32 v8, v82, v82
	v_fmac_f32_e32 v8, v83, v83
	v_fmac_f32_e32 v8, v76, v76
	v_fmac_f32_e32 v8, v77, v77
	v_fmac_f32_e32 v8, v78, v78
	v_fmac_f32_e32 v8, v79, v79
	ds_bpermute_b32 v86, v175, v8
	v_lshlrev_b32_e32 v88, 2, v131
	v_cmp_gt_u32_e32 vcc, 16, v133
	s_waitcnt lgkmcnt(0)
	v_add_f32_e32 v86, v8, v86
	ds_bpermute_b32 v87, v176, v86
	v_lshlrev_b32_e32 v8, 2, v178
	v_add3_u32 v8, s96, v8, v88
	s_and_saveexec_b64 s[8:9], vcc
	s_cbranch_execz .LBB0_1810
	s_waitcnt lgkmcnt(0)
	v_add_f32_e32 v86, v86, v87
	ds_write_b32 v8, v86
